# P6_fused_finalnorm
# speedup vs baseline: 1.0142x; 1.0114x over previous
; #define LAS __attribute__((address_space(3)))
; __global__ void __launch_bounds__(NWAVES * 64, 2) hybrid_fwd(Args args) {
;     ...
;     const int tid = threadIdx.x, lane = tid & 63, wave = __builtin_amdgcn_readfirstlane(tid >> 6);
;     const int G = gridDim.x, bx = blockIdx.x, vcu = (G % 8 == 0) ? (bx % 8) * (G / 8) + bx / 8 : bx;
;     const float* x = args.in[0]; const float* norm_mix_w = args.in[1]; const float* w_in = args.in[2]; const float* w_out = args.in[3]; const float* norm_ffn_w = args.in[4];
;     const float* w_gate = args.in[5]; const float* w_up = args.in[6]; const float* w_down = args.in[7]; const float* norm_final_w = args.in[8];
;     float* out = args.out; unsigned char* ws = args.ws;
;     float* SS1 = (float*)(ws + WS_SS); float* SS2 = SS1 + M;
;     bf16* Win_t = (bf16*)(ws + WS_WIN); bf16* Wout_t = (bf16*)(ws + WS_WOUT); bf16* Wgu_t = (bf16*)(ws + WS_WGU); bf16* Wdn_t = (bf16*)(ws + WS_WDN);
;     bf16* HB = (bf16*)(ws + WS_H); bf16* PROJ = (bf16*)(ws + WS_PROJ); bf16* ACT = (bf16*)(ws + WS_PROJ); bf16* MIXED = (bf16*)(ws + WS_MIXED);
;     const int lo = args.ph_lo, hi = args.ph_hi;
;     ...
;     volatile LAS unsigned* MISC = (volatile LAS unsigned*)((LAS unsigned char*)lds + LDS_BYTES - 64);
;     if (tid < 16) MISC[tid] = 0u;
;     __syncthreads();
;     XcdBarrier bar = xcd_barrier_post((unsigned*)(ws + WS_BAR), MISC);
_Z10hybrid_fwd4Args:
	s_load_dwordx2 s[76:77], s[0:1], 0x50
	s_mov_b32 s101, 0
	s_load_dwordx4 s[4:7], s[0:1], 0x40
	v_and_b32_e32 v185, 0x3ff, v0
	s_waitcnt lgkmcnt(0)
	v_writelane_b32 v244, s4, 0
	s_nop 1
	v_writelane_b32 v244, s5, 1
	v_writelane_b32 v244, s6, 2
	v_writelane_b32 v244, s7, 3
	s_load_dwordx2 s[6:7], s[0:1], 0x60
	s_add_u32 s4, s0, 0x60
	s_addc_u32 s5, s1, 0
	v_readfirstlane_b32 s12, v185
	s_waitcnt lgkmcnt(0)
	v_writelane_b32 v244, s6, 4
	s_and_b32 s3, s6, 7
	s_cmp_lg_u32 s3, 0
	s_mov_b32 s3, s2
	v_writelane_b32 v244, s7, 5
	s_cbranch_scc1 .LBB0_2
	s_load_dwordx2 s[6:7], s[0:1], 0x60
	s_waitcnt lgkmcnt(0)
	s_ashr_i32 s3, s6, 3
	s_ashr_i32 s6, s2, 31
	s_lshr_b32 s6, s6, 29
	s_add_i32 s6, s2, s6
	s_and_b32 s7, s6, -8
	s_sub_i32 s7, s2, s7
	s_mul_i32 s3, s3, s7
	s_ashr_i32 s6, s6, 3
	s_add_i32 s3, s3, s6

; template <class Epi, class Sched, bool ALIGN_EPI = false, bool SP2 = false>
; __device__ __forceinline__ void gemm_phase(PG8_LAS unsigned char* lds, const Gemm g, const Sched& S, const Epi& E) {
;     ...
;         const bool has_next = S.next(ui + 1, nxt);
;         const char* nA = has_next ? (const char*)g.A + (size_t)nxt.pm * tstep : cA; const char* nB = has_next ? (const char*)g.Bt + (size_t)nxt.pn * tstep : cB;
;         for (int t = 0; t < nt; t += 2) {
;             const bool last = (t == nt - 2);
;             const char* a1 = cA + (size_t)(t + 1) * kstep;
;             const char* a2 = last ? nA : cA + (size_t)(t + 2) * kstep; const char* b2 = last ? nB : cB + (size_t)(t + 2) * kstep;
;             const char* a3 = a2 + kstep; const char* b3 = b2 + kstep;
;             if (last && has_next) S.a_ready(nxt);
;     ...
; #pragma unroll
;         for (int a = 0; a < 2; ++a)
; #pragma unroll
;             for (int b = 0; b < 2; ++b)
; #pragma unroll
;                 for (int m = 0; m < 4; ++m)
; #pragma unroll
;                     for (int n = 0; n < 2; ++n) acc[a][b][m][n] = (f32x4){0.f, 0.f, 0.f, 0.f};
;         cur = nxt; cA = nA; cB = nB; ++ui;
.Lp5_unit:
	s_add_u32 s45, s16, 1
	s_mul_i32 s40, s45, s14
	s_add_u32 s40, s40, s2
	s_cmp_lt_u32 s40, 2816
	s_cselect_b32 s19, 1, 0
	s_min_u32 s40, s40, 2815
	s_and_b32 s41, s40, 7
	s_lshr_b32 s42, s40, 3
	s_mul_i32 s41, s41, 352
	s_add_u32 s41, s41, s42
	s_mul_hi_u32 s42, s41, 0xba2e8c
	s_mul_i32 s43, s42, 352
	s_sub_u32 s43, s41, s43
	s_and_b32 s40, s43, 7
	s_lshl_b32 s42, s42, 3
	s_add_u32 s20, s42, s40
	s_lshr_b32 s21, s43, 3
	s_mul_i32 s40, s20, 0x100000
	s_add_u32 s26, s10, s40
	s_addc_u32 s27, s11, 0
	s_mul_i32 s40, s21, 0x100000
	s_add_u32 s28, s12, s40
	s_addc_u32 s29, s13, 0
	s_cmp_eq_u32 s19, 0
	s_cselect_b32 s26, s22, s26
	s_cselect_b32 s27, s23, s27
	s_cselect_b32 s28, s24, s28
	s_cselect_b32 s29, s25, s29
	s_add_u32 s30, s22, 256
	s_addc_u32 s31, s23, 0
	s_add_u32 s32, s24, 256
	s_addc_u32 s33, s25, 0
	s_add_u32 s56, s30, 0x80000
	s_addc_u32 s57, s31, 0
	s_add_u32 s58, s32, 0x80000
	s_addc_u32 s59, s33, 0
	s_movk_i32 s34, 16
	v_mov_b32_e32 v0, 0
	v_mov_b32_e32 v1, 0
	v_mov_b32_e32 v2, 0
	v_mov_b32_e32 v3, 0
	v_mov_b32_e32 v4, 0
	v_mov_b32_e32 v5, 0
	v_mov_b32_e32 v6, 0
	v_mov_b32_e32 v7, 0
	v_mov_b32_e32 v8, 0
	v_mov_b32_e32 v9, 0
	v_mov_b32_e32 v10, 0
	v_mov_b32_e32 v11, 0
	v_mov_b32_e32 v12, 0
	v_mov_b32_e32 v13, 0
	v_mov_b32_e32 v14, 0
	v_mov_b32_e32 v15, 0
	v_mov_b32_e32 v16, 0
	v_mov_b32_e32 v17, 0
	v_mov_b32_e32 v18, 0
	v_mov_b32_e32 v19, 0
	v_mov_b32_e32 v20, 0
	v_mov_b32_e32 v21, 0
	v_mov_b32_e32 v22, 0
	v_mov_b32_e32 v23, 0
	v_mov_b32_e32 v24, 0
	v_mov_b32_e32 v25, 0
	v_mov_b32_e32 v26, 0
	v_mov_b32_e32 v27, 0
	v_mov_b32_e32 v28, 0
	v_mov_b32_e32 v29, 0
	v_mov_b32_e32 v30, 0
	v_mov_b32_e32 v31, 0
	v_mov_b32_e32 v32, 0
	v_mov_b32_e32 v33, 0
	v_mov_b32_e32 v34, 0
	v_mov_b32_e32 v35, 0
	v_mov_b32_e32 v36, 0
	v_mov_b32_e32 v37, 0
	v_mov_b32_e32 v38, 0
	v_mov_b32_e32 v39, 0
	v_mov_b32_e32 v40, 0
	v_mov_b32_e32 v41, 0
	v_mov_b32_e32 v42, 0
	v_mov_b32_e32 v43, 0
	v_mov_b32_e32 v44, 0
	v_mov_b32_e32 v45, 0
	v_mov_b32_e32 v46, 0
	v_mov_b32_e32 v47, 0
	v_mov_b32_e32 v48, 0
	v_mov_b32_e32 v49, 0
	v_mov_b32_e32 v50, 0
	v_mov_b32_e32 v51, 0
	v_mov_b32_e32 v52, 0
	v_mov_b32_e32 v53, 0
	v_mov_b32_e32 v54, 0
	v_mov_b32_e32 v55, 0
	v_mov_b32_e32 v56, 0
	v_mov_b32_e32 v57, 0
	v_mov_b32_e32 v58, 0
	v_mov_b32_e32 v59, 0
	v_mov_b32_e32 v60, 0
	v_mov_b32_e32 v61, 0
	v_mov_b32_e32 v62, 0
	v_mov_b32_e32 v63, 0
	v_mov_b32_e32 v64, 0
	v_mov_b32_e32 v65, 0
	v_mov_b32_e32 v66, 0
	v_mov_b32_e32 v67, 0
	v_mov_b32_e32 v68, 0
	v_mov_b32_e32 v69, 0
	v_mov_b32_e32 v70, 0
	v_mov_b32_e32 v71, 0
	v_mov_b32_e32 v72, 0
	v_mov_b32_e32 v73, 0
	v_mov_b32_e32 v74, 0
	v_mov_b32_e32 v75, 0
	v_mov_b32_e32 v76, 0
	v_mov_b32_e32 v77, 0
	v_mov_b32_e32 v78, 0
	v_mov_b32_e32 v79, 0
	v_mov_b32_e32 v80, 0
	v_mov_b32_e32 v81, 0
	v_mov_b32_e32 v82, 0
	v_mov_b32_e32 v83, 0
	v_mov_b32_e32 v84, 0
	v_mov_b32_e32 v85, 0
	v_mov_b32_e32 v86, 0
	v_mov_b32_e32 v87, 0
	v_mov_b32_e32 v88, 0
	v_mov_b32_e32 v89, 0
	v_mov_b32_e32 v90, 0
	v_mov_b32_e32 v91, 0
	v_mov_b32_e32 v92, 0
	v_mov_b32_e32 v93, 0
	v_mov_b32_e32 v94, 0
	v_mov_b32_e32 v95, 0
	v_mov_b32_e32 v96, 0
	v_mov_b32_e32 v97, 0
	v_mov_b32_e32 v98, 0
	v_mov_b32_e32 v99, 0
	v_mov_b32_e32 v100, 0
	v_mov_b32_e32 v101, 0
	v_mov_b32_e32 v102, 0
	v_mov_b32_e32 v103, 0
	v_mov_b32_e32 v104, 0
	v_mov_b32_e32 v105, 0
	v_mov_b32_e32 v106, 0
	v_mov_b32_e32 v107, 0
	v_mov_b32_e32 v108, 0
	v_mov_b32_e32 v109, 0
	v_mov_b32_e32 v110, 0
	v_mov_b32_e32 v111, 0
	v_mov_b32_e32 v112, 0
	v_mov_b32_e32 v113, 0
	v_mov_b32_e32 v114, 0
	v_mov_b32_e32 v115, 0
	v_mov_b32_e32 v116, 0
	v_mov_b32_e32 v117, 0
	v_mov_b32_e32 v118, 0
	v_mov_b32_e32 v119, 0
	v_mov_b32_e32 v120, 0
	v_mov_b32_e32 v121, 0
	v_mov_b32_e32 v122, 0
	v_mov_b32_e32 v123, 0
	v_mov_b32_e32 v124, 0
	v_mov_b32_e32 v125, 0
	v_mov_b32_e32 v126, 0
	v_mov_b32_e32 v127, 0
	ds_read_b128 v[194:197], v247 offset:0
	ds_read_b128 v[198:201], v248 offset:0
	ds_read_b128 v[202:205], v247 offset:2048
	ds_read_b128 v[206:209], v248 offset:2048
	ds_read_b128 v[128:131], v245 offset:0
	ds_read_b128 v[132:135], v246 offset:0
	ds_read_b128 v[136:139], v245 offset:2048
	ds_read_b128 v[140:143], v246 offset:2048
	ds_read_b128 v[144:147], v245 offset:4096
	ds_read_b128 v[148:151], v246 offset:4096
	ds_read_b128 v[152:155], v245 offset:6144
	ds_read_b128 v[156:159], v246 offset:6144
	s_cmp_ge_u32 s36, 4
	s_cbranch_scc1 .Lp5_kloop1
; #define PG8_STAGE(bufoff, gbase, voff) do { _Pragma("unroll") for (int _i = 0; _i < 2; ++_i) \
;         __builtin_amdgcn_global_load_lds((const unsigned*)((const char*)(gbase) + (voff)[_i]), (PG8_LAS unsigned*)(lds + (bufoff) + ldsw + _i * 8192), 16, 0, 0); } while (0)
; #define PG8_LDA(dst, b, h) do { _Pragma("unroll") for (int m = 0; m < 4; ++m) _Pragma("unroll") for (int k = 0; k < 2; ++k) dst[m][k] = *(const PG8_LAS bf16x8*)(lds + PG8_SA(b, h) + aoff + m * 2048 + k * 1024); } while (0)
; #define PG8_LDB(dst, b, h) do { _Pragma("unroll") for (int n = 0; n < 2; ++n) _Pragma("unroll") for (int k = 0; k < 2; ++k) dst[n][k] = *(const PG8_LAS bf16x8*)(lds + PG8_SB(b, h) + boff + n * 2048 + k * 1024); } while (0)
; #define PG8_MMA(ai, bj, At, Bt) do { __builtin_amdgcn_s_setprio(1); _Pragma("unroll") for (int m = 0; m < 4; ++m) _Pragma("unroll") for (int n = 0; n < 2; ++n) _Pragma("unroll") for (int k = 0; k < 2; ++k) \
;         acc[ai][bj][m][n] = __builtin_amdgcn_mfma_f32_16x16x32_bf16(Bt[n][k], At[m][k], acc[ai][bj][m][n], 0, 0, 0); __builtin_amdgcn_s_setprio(0); } while (0)
; #define PG8_WAIT_V(n) asm volatile("s_waitcnt vmcnt(" #n ")" ::: "memory")
; #define PG8_WAIT_L(n) asm volatile("s_waitcnt lgkmcnt(" #n ")" ::: "memory")
; #define PG8_BAR __builtin_amdgcn_s_barrier()
; #define PG8_SCHED __builtin_amdgcn_sched_barrier(0)
; template <class Epi, class Sched, bool ALIGN_EPI = false, bool SP2 = false>
; __device__ __forceinline__ void gemm_phase(PG8_LAS unsigned char* lds, const Gemm g, const Sched& S, const Epi& E) {
;     ...
;             PG8_LDB(B0, 0, 0); PG8_LDB(B1, 0, 1); PG8_SCHED; PG8_LDA(At, 0, 0); PG8_STAGE(PG8_SA(1, 1), a1 + hstep, voffA);
;             PG8_WAIT_V(8); PG8_WAIT_L(0); PG8_BAR; PG8_MMA(0, 0, At, B0); PG8_MMA(0, 1, At, B1); PG8_BAR; PG8_SCHED;
;             PG8_LDA(At, 0, 1); PG8_STAGE(PG8_SB(0, 0), b2, voffB); PG8_STAGE(PG8_SB(0, 1), b2 + hstep, voffB); PG8_STAGE(PG8_SA(0, 0), a2, voffA);
;             PG8_WAIT_V(8); PG8_WAIT_L(0); PG8_BAR; PG8_MMA(1, 0, At, B0); PG8_MMA(1, 1, At, B1); PG8_BAR; PG8_SCHED;
.Lp5_kloop0:
	s_waitcnt vmcnt(8)
	s_waitcnt lgkmcnt(0)
	s_barrier
	v_mfma_f32_16x16x32_bf16 v[0:3], v[194:197], v[128:131], v[0:3]
	ds_read_b128 v[210:213], v247 offset:16384
	v_mfma_f32_16x16x32_bf16 v[4:7], v[202:205], v[128:131], v[4:7]
	ds_read_b128 v[214:217], v248 offset:16384
	v_mfma_f32_16x16x32_bf16 v[8:11], v[194:197], v[136:139], v[8:11]
	ds_read_b128 v[218:221], v247 offset:18432
	v_mfma_f32_16x16x32_bf16 v[12:15], v[202:205], v[136:139], v[12:15]
	ds_read_b128 v[222:225], v248 offset:18432
	v_mfma_f32_16x16x32_bf16 v[16:19], v[194:197], v[144:147], v[16:19]
	s_add_i32 m0, s35, 0x0
	v_mfma_f32_16x16x32_bf16 v[20:23], v[202:205], v[144:147], v[20:23]
	global_load_lds_dwordx4 v249, s[30:31]
	v_mfma_f32_16x16x32_bf16 v[24:27], v[194:197], v[152:155], v[24:27]
	s_add_i32 m0, s35, 0x2000
	v_mfma_f32_16x16x32_bf16 v[28:31], v[202:205], v[152:155], v[28:31]
	global_load_lds_dwordx4 v250, s[30:31]
	v_mfma_f32_16x16x32_bf16 v[0:3], v[198:201], v[132:135], v[0:3]
	s_add_i32 m0, s35, 0x10000
	v_mfma_f32_16x16x32_bf16 v[4:7], v[206:209], v[132:135], v[4:7]
	global_load_lds_dwordx4 v251, s[32:33]
	v_mfma_f32_16x16x32_bf16 v[8:11], v[198:201], v[140:143], v[8:11]
	s_add_i32 m0, s35, 0x12000
	v_mfma_f32_16x16x32_bf16 v[12:15], v[206:209], v[140:143], v[12:15]
	global_load_lds_dwordx4 v252, s[32:33]
	v_mfma_f32_16x16x32_bf16 v[16:19], v[198:201], v[148:151], v[16:19]
	ds_read_b128 v[160:163], v245 offset:16384
	v_mfma_f32_16x16x32_bf16 v[20:23], v[206:209], v[148:151], v[20:23]
	ds_read_b128 v[164:167], v246 offset:16384
	v_mfma_f32_16x16x32_bf16 v[24:27], v[198:201], v[156:159], v[24:27]
	ds_read_b128 v[168:171], v245 offset:18432
	v_mfma_f32_16x16x32_bf16 v[28:31], v[206:209], v[156:159], v[28:31]
	ds_read_b128 v[172:175], v246 offset:18432
	s_waitcnt lgkmcnt(4)
	v_mfma_f32_16x16x32_bf16 v[32:35], v[210:213], v[128:131], v[32:35]
	ds_read_b128 v[176:179], v245 offset:20480
	v_mfma_f32_16x16x32_bf16 v[36:39], v[218:221], v[128:131], v[36:39]
	ds_read_b128 v[180:183], v246 offset:20480
	v_mfma_f32_16x16x32_bf16 v[40:43], v[210:213], v[136:139], v[40:43]
	ds_read_b128 v[186:189], v245 offset:22528
	v_mfma_f32_16x16x32_bf16 v[44:47], v[218:221], v[136:139], v[44:47]
	ds_read_b128 v[190:193], v246 offset:22528
	v_mfma_f32_16x16x32_bf16 v[48:51], v[210:213], v[144:147], v[48:51]
	v_mfma_f32_16x16x32_bf16 v[52:55], v[218:221], v[144:147], v[52:55]
	v_mfma_f32_16x16x32_bf16 v[56:59], v[210:213], v[152:155], v[56:59]
	v_mfma_f32_16x16x32_bf16 v[60:63], v[218:221], v[152:155], v[60:63]
	v_mfma_f32_16x16x32_bf16 v[32:35], v[214:217], v[132:135], v[32:35]
	v_mfma_f32_16x16x32_bf16 v[36:39], v[222:225], v[132:135], v[36:39]
	v_mfma_f32_16x16x32_bf16 v[40:43], v[214:217], v[140:143], v[40:43]
	v_mfma_f32_16x16x32_bf16 v[44:47], v[222:225], v[140:143], v[44:47]
	v_mfma_f32_16x16x32_bf16 v[48:51], v[214:217], v[148:151], v[48:51]
	v_mfma_f32_16x16x32_bf16 v[52:55], v[222:225], v[148:151], v[52:55]
	v_mfma_f32_16x16x32_bf16 v[56:59], v[214:217], v[156:159], v[56:59]
	v_mfma_f32_16x16x32_bf16 v[60:63], v[222:225], v[156:159], v[60:63]
	s_waitcnt vmcnt(8)
	s_waitcnt lgkmcnt(0)
	s_barrier
	v_mfma_f32_16x16x32_bf16 v[96:99], v[210:213], v[160:163], v[96:99]
	s_add_i32 m0, s35, 0x4000
	v_mfma_f32_16x16x32_bf16 v[100:103], v[218:221], v[160:163], v[100:103]
	global_load_lds_dwordx4 v249, s[56:57]
	v_mfma_f32_16x16x32_bf16 v[104:107], v[210:213], v[168:171], v[104:107]
	s_add_i32 m0, s35, 0x6000
	v_mfma_f32_16x16x32_bf16 v[108:111], v[218:221], v[168:171], v[108:111]
	global_load_lds_dwordx4 v250, s[56:57]
	v_mfma_f32_16x16x32_bf16 v[112:115], v[210:213], v[176:179], v[112:115]
	s_add_i32 m0, s35, 0x14000
	v_mfma_f32_16x16x32_bf16 v[116:119], v[218:221], v[176:179], v[116:119]
	global_load_lds_dwordx4 v251, s[58:59]
	v_mfma_f32_16x16x32_bf16 v[120:123], v[210:213], v[186:189], v[120:123]
	s_add_i32 m0, s35, 0x16000
	v_mfma_f32_16x16x32_bf16 v[124:127], v[218:221], v[186:189], v[124:127]
	global_load_lds_dwordx4 v252, s[58:59]
	v_mfma_f32_16x16x32_bf16 v[96:99], v[214:217], v[164:167], v[96:99]
	ds_read_b128 v[128:131], v245 offset:32768
	v_mfma_f32_16x16x32_bf16 v[100:103], v[222:225], v[164:167], v[100:103]
	ds_read_b128 v[132:135], v246 offset:32768
	v_mfma_f32_16x16x32_bf16 v[104:107], v[214:217], v[172:175], v[104:107]
	ds_read_b128 v[136:139], v245 offset:34816
	v_mfma_f32_16x16x32_bf16 v[108:111], v[222:225], v[172:175], v[108:111]
	ds_read_b128 v[140:143], v246 offset:34816
	v_mfma_f32_16x16x32_bf16 v[112:115], v[214:217], v[180:183], v[112:115]
	ds_read_b128 v[144:147], v245 offset:36864
	v_mfma_f32_16x16x32_bf16 v[116:119], v[222:225], v[180:183], v[116:119]
	ds_read_b128 v[148:151], v246 offset:36864
	v_mfma_f32_16x16x32_bf16 v[120:123], v[214:217], v[190:193], v[120:123]
	ds_read_b128 v[152:155], v245 offset:38912
	v_mfma_f32_16x16x32_bf16 v[124:127], v[222:225], v[190:193], v[124:127]
	ds_read_b128 v[156:159], v246 offset:38912
	v_mfma_f32_16x16x32_bf16 v[64:67], v[194:197], v[160:163], v[64:67]
	ds_read_b128 v[210:213], v247 offset:49152
	v_mfma_f32_16x16x32_bf16 v[68:71], v[202:205], v[160:163], v[68:71]
	ds_read_b128 v[214:217], v248 offset:49152
	v_mfma_f32_16x16x32_bf16 v[72:75], v[194:197], v[168:171], v[72:75]
	ds_read_b128 v[218:221], v247 offset:51200
	v_mfma_f32_16x16x32_bf16 v[76:79], v[202:205], v[168:171], v[76:79]
	ds_read_b128 v[222:225], v248 offset:51200
	v_mfma_f32_16x16x32_bf16 v[80:83], v[194:197], v[176:179], v[80:83]
	s_add_u32 s30, s30, 128
	s_addc_u32 s31, s31, 0
	v_mfma_f32_16x16x32_bf16 v[84:87], v[202:205], v[176:179], v[84:87]
	s_add_u32 s56, s56, 128
	s_addc_u32 s57, s57, 0
	v_mfma_f32_16x16x32_bf16 v[88:91], v[194:197], v[186:189], v[88:91]
	s_add_u32 s32, s32, 128
	s_addc_u32 s33, s33, 0
	v_mfma_f32_16x16x32_bf16 v[92:95], v[202:205], v[186:189], v[92:95]
	s_add_u32 s58, s58, 128
	s_addc_u32 s59, s59, 0
	v_mfma_f32_16x16x32_bf16 v[64:67], v[198:201], v[164:167], v[64:67]
	v_mfma_f32_16x16x32_bf16 v[68:71], v[206:209], v[164:167], v[68:71]
	v_mfma_f32_16x16x32_bf16 v[72:75], v[198:201], v[172:175], v[72:75]
	v_mfma_f32_16x16x32_bf16 v[76:79], v[206:209], v[172:175], v[76:79]
	v_mfma_f32_16x16x32_bf16 v[80:83], v[198:201], v[180:183], v[80:83]
	v_mfma_f32_16x16x32_bf16 v[84:87], v[206:209], v[180:183], v[84:87]
	v_mfma_f32_16x16x32_bf16 v[88:91], v[198:201], v[190:193], v[88:91]
	v_mfma_f32_16x16x32_bf16 v[92:95], v[206:209], v[190:193], v[92:95]
	s_waitcnt vmcnt(8)
	s_waitcnt lgkmcnt(0)
	s_barrier
; #define PG8_STAGE(bufoff, gbase, voff) do { _Pragma("unroll") for (int _i = 0; _i < 2; ++_i) \
;         __builtin_amdgcn_global_load_lds((const unsigned*)((const char*)(gbase) + (voff)[_i]), (PG8_LAS unsigned*)(lds + (bufoff) + ldsw + _i * 8192), 16, 0, 0); } while (0)
; #define PG8_LDA(dst, b, h) do { _Pragma("unroll") for (int m = 0; m < 4; ++m) _Pragma("unroll") for (int k = 0; k < 2; ++k) dst[m][k] = *(const PG8_LAS bf16x8*)(lds + PG8_SA(b, h) + aoff + m * 2048 + k * 1024); } while (0)
; #define PG8_LDB(dst, b, h) do { _Pragma("unroll") for (int n = 0; n < 2; ++n) _Pragma("unroll") for (int k = 0; k < 2; ++k) dst[n][k] = *(const PG8_LAS bf16x8*)(lds + PG8_SB(b, h) + boff + n * 2048 + k * 1024); } while (0)
; #define PG8_MMA(ai, bj, At, Bt) do { __builtin_amdgcn_s_setprio(1); _Pragma("unroll") for (int m = 0; m < 4; ++m) _Pragma("unroll") for (int n = 0; n < 2; ++n) _Pragma("unroll") for (int k = 0; k < 2; ++k) \
;         acc[ai][bj][m][n] = __builtin_amdgcn_mfma_f32_16x16x32_bf16(Bt[n][k], At[m][k], acc[ai][bj][m][n], 0, 0, 0); __builtin_amdgcn_s_setprio(0); } while (0)
; #define PG8_WAIT_V(n) asm volatile("s_waitcnt vmcnt(" #n ")" ::: "memory")
; #define PG8_WAIT_L(n) asm volatile("s_waitcnt lgkmcnt(" #n ")" ::: "memory")
; #define PG8_BAR __builtin_amdgcn_s_barrier()
; #define PG8_SCHED __builtin_amdgcn_sched_barrier(0)
; template <class Epi, class Sched, bool ALIGN_EPI = false, bool SP2 = false>
; __device__ __forceinline__ void gemm_phase(PG8_LAS unsigned char* lds, const Gemm g, const Sched& S, const Epi& E) {
;     ...
;             const char* a2 = last ? nA : cA + (size_t)(t + 2) * kstep; const char* b2 = last ? nB : cB + (size_t)(t + 2) * kstep;
;     ...
;             PG8_LDB(B0, 1, 0); PG8_LDB(B1, 1, 1); PG8_SCHED; PG8_LDA(At, 1, 0); PG8_STAGE(PG8_SA(0, 1), a2 + hstep, voffA);
;             PG8_WAIT_V(8); PG8_WAIT_L(0); PG8_BAR; PG8_MMA(0, 0, At, B0); PG8_MMA(0, 1, At, B1); PG8_BAR; PG8_SCHED;
;             PG8_LDA(At, 1, 1); PG8_STAGE(PG8_SB(1, 0), b3, voffB); PG8_STAGE(PG8_SB(1, 1), b3 + hstep, voffB); PG8_STAGE(PG8_SA(1, 0), a3, voffA);
;             PG8_WAIT_V(8); PG8_WAIT_L(0); PG8_BAR; PG8_MMA(1, 0, At, B0); PG8_MMA(1, 1, At, B1); PG8_BAR; PG8_SCHED;
	v_mfma_f32_16x16x32_bf16 v[32:35], v[210:213], v[128:131], v[32:35]
	ds_read_b128 v[194:197], v247 offset:32768
	v_mfma_f32_16x16x32_bf16 v[36:39], v[218:221], v[128:131], v[36:39]
	ds_read_b128 v[198:201], v248 offset:32768
	v_mfma_f32_16x16x32_bf16 v[40:43], v[210:213], v[136:139], v[40:43]
	ds_read_b128 v[202:205], v247 offset:34816
	v_mfma_f32_16x16x32_bf16 v[44:47], v[218:221], v[136:139], v[44:47]
	ds_read_b128 v[206:209], v248 offset:34816
	v_mfma_f32_16x16x32_bf16 v[48:51], v[210:213], v[144:147], v[48:51]
	s_add_i32 m0, s35, 0x8000
	v_mfma_f32_16x16x32_bf16 v[52:55], v[218:221], v[144:147], v[52:55]
	global_load_lds_dwordx4 v249, s[30:31]
	v_mfma_f32_16x16x32_bf16 v[56:59], v[210:213], v[152:155], v[56:59]
	s_add_i32 m0, s35, 0xa000
	v_mfma_f32_16x16x32_bf16 v[60:63], v[218:221], v[152:155], v[60:63]
	global_load_lds_dwordx4 v250, s[30:31]
	v_mfma_f32_16x16x32_bf16 v[32:35], v[214:217], v[132:135], v[32:35]
	s_add_i32 m0, s35, 0x1c000
	v_mfma_f32_16x16x32_bf16 v[36:39], v[222:225], v[132:135], v[36:39]
	global_load_lds_dwordx4 v251, s[58:59]
	v_mfma_f32_16x16x32_bf16 v[40:43], v[214:217], v[140:143], v[40:43]
	s_add_i32 m0, s35, 0x1e000
	v_mfma_f32_16x16x32_bf16 v[44:47], v[222:225], v[140:143], v[44:47]
	global_load_lds_dwordx4 v252, s[58:59]
	v_mfma_f32_16x16x32_bf16 v[48:51], v[214:217], v[148:151], v[48:51]
	ds_read_b128 v[160:163], v245 offset:49152
	v_mfma_f32_16x16x32_bf16 v[52:55], v[222:225], v[148:151], v[52:55]
	ds_read_b128 v[164:167], v246 offset:49152
	v_mfma_f32_16x16x32_bf16 v[56:59], v[214:217], v[156:159], v[56:59]
	ds_read_b128 v[168:171], v245 offset:51200
	v_mfma_f32_16x16x32_bf16 v[60:63], v[222:225], v[156:159], v[60:63]
	ds_read_b128 v[172:175], v246 offset:51200
	s_waitcnt lgkmcnt(4)
	v_mfma_f32_16x16x32_bf16 v[0:3], v[194:197], v[128:131], v[0:3]
	ds_read_b128 v[176:179], v245 offset:53248
	v_mfma_f32_16x16x32_bf16 v[4:7], v[202:205], v[128:131], v[4:7]
	ds_read_b128 v[180:183], v246 offset:53248
	v_mfma_f32_16x16x32_bf16 v[8:11], v[194:197], v[136:139], v[8:11]
	ds_read_b128 v[186:189], v245 offset:55296
	v_mfma_f32_16x16x32_bf16 v[12:15], v[202:205], v[136:139], v[12:15]
	ds_read_b128 v[190:193], v246 offset:55296
	v_mfma_f32_16x16x32_bf16 v[16:19], v[194:197], v[144:147], v[16:19]
	v_mfma_f32_16x16x32_bf16 v[20:23], v[202:205], v[144:147], v[20:23]
	v_mfma_f32_16x16x32_bf16 v[24:27], v[194:197], v[152:155], v[24:27]
	v_mfma_f32_16x16x32_bf16 v[28:31], v[202:205], v[152:155], v[28:31]
	v_mfma_f32_16x16x32_bf16 v[0:3], v[198:201], v[132:135], v[0:3]
	v_mfma_f32_16x16x32_bf16 v[4:7], v[206:209], v[132:135], v[4:7]
	v_mfma_f32_16x16x32_bf16 v[8:11], v[198:201], v[140:143], v[8:11]
	v_mfma_f32_16x16x32_bf16 v[12:15], v[206:209], v[140:143], v[12:15]
	v_mfma_f32_16x16x32_bf16 v[16:19], v[198:201], v[148:151], v[16:19]
	v_mfma_f32_16x16x32_bf16 v[20:23], v[206:209], v[148:151], v[20:23]
	v_mfma_f32_16x16x32_bf16 v[24:27], v[198:201], v[156:159], v[24:27]
	v_mfma_f32_16x16x32_bf16 v[28:31], v[206:209], v[156:159], v[28:31]
	s_waitcnt vmcnt(8)
	s_waitcnt lgkmcnt(0)
	s_barrier
	v_mfma_f32_16x16x32_bf16 v[64:67], v[194:197], v[160:163], v[64:67]
	s_add_i32 m0, s35, 0xc000
	v_mfma_f32_16x16x32_bf16 v[68:71], v[202:205], v[160:163], v[68:71]
	global_load_lds_dwordx4 v249, s[56:57]
	v_mfma_f32_16x16x32_bf16 v[72:75], v[194:197], v[168:171], v[72:75]
	s_add_i32 m0, s35, 0xe000
	v_mfma_f32_16x16x32_bf16 v[76:79], v[202:205], v[168:171], v[76:79]
	global_load_lds_dwordx4 v250, s[56:57]
	v_mfma_f32_16x16x32_bf16 v[80:83], v[194:197], v[176:179], v[80:83]
	s_add_i32 m0, s35, 0x18000
	v_mfma_f32_16x16x32_bf16 v[84:87], v[202:205], v[176:179], v[84:87]
	global_load_lds_dwordx4 v251, s[32:33]
	v_mfma_f32_16x16x32_bf16 v[88:91], v[194:197], v[186:189], v[88:91]
	s_add_i32 m0, s35, 0x1a000
	v_mfma_f32_16x16x32_bf16 v[92:95], v[202:205], v[186:189], v[92:95]
	global_load_lds_dwordx4 v252, s[32:33]
	v_mfma_f32_16x16x32_bf16 v[64:67], v[198:201], v[164:167], v[64:67]
	ds_read_b128 v[128:131], v245 offset:0
	v_mfma_f32_16x16x32_bf16 v[68:71], v[206:209], v[164:167], v[68:71]
	ds_read_b128 v[132:135], v246 offset:0
	v_mfma_f32_16x16x32_bf16 v[72:75], v[198:201], v[172:175], v[72:75]
	ds_read_b128 v[136:139], v245 offset:2048
	v_mfma_f32_16x16x32_bf16 v[76:79], v[206:209], v[172:175], v[76:79]
	ds_read_b128 v[140:143], v246 offset:2048
	v_mfma_f32_16x16x32_bf16 v[80:83], v[198:201], v[180:183], v[80:83]
	ds_read_b128 v[144:147], v245 offset:4096
	v_mfma_f32_16x16x32_bf16 v[84:87], v[206:209], v[180:183], v[84:87]
	ds_read_b128 v[148:151], v246 offset:4096
	v_mfma_f32_16x16x32_bf16 v[88:91], v[198:201], v[190:193], v[88:91]
	ds_read_b128 v[152:155], v245 offset:6144
	v_mfma_f32_16x16x32_bf16 v[92:95], v[206:209], v[190:193], v[92:95]
	ds_read_b128 v[156:159], v246 offset:6144
	v_mfma_f32_16x16x32_bf16 v[96:99], v[210:213], v[160:163], v[96:99]
	ds_read_b128 v[194:197], v247 offset:0
	v_mfma_f32_16x16x32_bf16 v[100:103], v[218:221], v[160:163], v[100:103]
	ds_read_b128 v[198:201], v248 offset:0
	v_mfma_f32_16x16x32_bf16 v[104:107], v[210:213], v[168:171], v[104:107]
	ds_read_b128 v[202:205], v247 offset:2048
	v_mfma_f32_16x16x32_bf16 v[108:111], v[218:221], v[168:171], v[108:111]
	ds_read_b128 v[206:209], v248 offset:2048
	v_mfma_f32_16x16x32_bf16 v[112:115], v[210:213], v[176:179], v[112:115]
	s_add_u32 s30, s30, 128
	s_addc_u32 s31, s31, 0
	v_mfma_f32_16x16x32_bf16 v[116:119], v[218:221], v[176:179], v[116:119]
	s_add_u32 s56, s56, 128
	s_addc_u32 s57, s57, 0
	v_mfma_f32_16x16x32_bf16 v[120:123], v[210:213], v[186:189], v[120:123]
	s_add_u32 s32, s32, 128
	s_addc_u32 s33, s33, 0
	v_mfma_f32_16x16x32_bf16 v[124:127], v[218:221], v[186:189], v[124:127]
	s_add_u32 s58, s58, 128
	s_addc_u32 s59, s59, 0
	v_mfma_f32_16x16x32_bf16 v[96:99], v[214:217], v[164:167], v[96:99]
	v_mfma_f32_16x16x32_bf16 v[100:103], v[222:225], v[164:167], v[100:103]
	v_mfma_f32_16x16x32_bf16 v[104:107], v[214:217], v[172:175], v[104:107]
	v_mfma_f32_16x16x32_bf16 v[108:111], v[222:225], v[172:175], v[108:111]
	v_mfma_f32_16x16x32_bf16 v[112:115], v[214:217], v[180:183], v[112:115]
	v_mfma_f32_16x16x32_bf16 v[116:119], v[222:225], v[180:183], v[116:119]
	v_mfma_f32_16x16x32_bf16 v[120:123], v[214:217], v[190:193], v[120:123]
	v_mfma_f32_16x16x32_bf16 v[124:127], v[222:225], v[190:193], v[124:127]
	s_add_i32 s34, s34, -1
	s_cmp_lg_u32 s34, 1
	s_cbranch_scc1 .Lp5_nosw0
	s_add_u32 s30, s26, 0
	s_addc_u32 s31, s27, 0
	s_add_u32 s32, s28, 0
	s_addc_u32 s33, s29, 0
	s_add_u32 s56, s30, 0x80000
	s_addc_u32 s57, s31, 0
	s_add_u32 s58, s32, 0x80000
	s_addc_u32 s59, s33, 0
; #define PG8_STAGE(bufoff, gbase, voff) do { _Pragma("unroll") for (int _i = 0; _i < 2; ++_i) \
;         __builtin_amdgcn_global_load_lds((const unsigned*)((const char*)(gbase) + (voff)[_i]), (PG8_LAS unsigned*)(lds + (bufoff) + ldsw + _i * 8192), 16, 0, 0); } while (0)
; #define PG8_LDA(dst, b, h) do { _Pragma("unroll") for (int m = 0; m < 4; ++m) _Pragma("unroll") for (int k = 0; k < 2; ++k) dst[m][k] = *(const PG8_LAS bf16x8*)(lds + PG8_SA(b, h) + aoff + m * 2048 + k * 1024); } while (0)
; #define PG8_LDB(dst, b, h) do { _Pragma("unroll") for (int n = 0; n < 2; ++n) _Pragma("unroll") for (int k = 0; k < 2; ++k) dst[n][k] = *(const PG8_LAS bf16x8*)(lds + PG8_SB(b, h) + boff + n * 2048 + k * 1024); } while (0)
; #define PG8_MMA(ai, bj, At, Bt) do { __builtin_amdgcn_s_setprio(1); _Pragma("unroll") for (int m = 0; m < 4; ++m) _Pragma("unroll") for (int n = 0; n < 2; ++n) _Pragma("unroll") for (int k = 0; k < 2; ++k) \
;         acc[ai][bj][m][n] = __builtin_amdgcn_mfma_f32_16x16x32_bf16(Bt[n][k], At[m][k], acc[ai][bj][m][n], 0, 0, 0); __builtin_amdgcn_s_setprio(0); } while (0)
; #define PG8_WAIT_V(n) asm volatile("s_waitcnt vmcnt(" #n ")" ::: "memory")
; #define PG8_WAIT_L(n) asm volatile("s_waitcnt lgkmcnt(" #n ")" ::: "memory")
; #define PG8_BAR __builtin_amdgcn_s_barrier()
; #define PG8_SCHED __builtin_amdgcn_sched_barrier(0)
; template <class Epi, class Sched, bool ALIGN_EPI = false, bool SP2 = false>
; __device__ __forceinline__ void gemm_phase(PG8_LAS unsigned char* lds, const Gemm g, const Sched& S, const Epi& E) {
;     ...
;             PG8_LDB(B0, 0, 0); PG8_LDB(B1, 0, 1); PG8_SCHED; PG8_LDA(At, 0, 0); PG8_STAGE(PG8_SA(1, 1), a1 + hstep, voffA);
;             PG8_WAIT_V(8); PG8_WAIT_L(0); PG8_BAR; PG8_MMA(0, 0, At, B0); PG8_MMA(0, 1, At, B1); PG8_BAR; PG8_SCHED;
;             PG8_LDA(At, 0, 1); PG8_STAGE(PG8_SB(0, 0), b2, voffB); PG8_STAGE(PG8_SB(0, 1), b2 + hstep, voffB); PG8_STAGE(PG8_SA(0, 0), a2, voffA);
;             PG8_WAIT_V(8); PG8_WAIT_L(0); PG8_BAR; PG8_MMA(1, 0, At, B0); PG8_MMA(1, 1, At, B1); PG8_BAR; PG8_SCHED;
.Lp5_nosw0:
	s_cmp_lg_u32 s34, 0
	s_cbranch_scc1 .Lp5_kloop0
	s_branch .Lp5_kdone
.Lp5_kloop1:
	s_waitcnt vmcnt(8)
	s_waitcnt lgkmcnt(0)
	s_barrier
	v_mfma_f32_16x16x32_bf16 v[0:3], v[194:197], v[128:131], v[0:3]
	ds_read_b128 v[210:213], v247 offset:16384
	v_mfma_f32_16x16x32_bf16 v[4:7], v[202:205], v[128:131], v[4:7]
	ds_read_b128 v[214:217], v248 offset:16384
	v_mfma_f32_16x16x32_bf16 v[8:11], v[194:197], v[136:139], v[8:11]
	ds_read_b128 v[218:221], v247 offset:18432
	v_mfma_f32_16x16x32_bf16 v[12:15], v[202:205], v[136:139], v[12:15]
	ds_read_b128 v[222:225], v248 offset:18432
	v_mfma_f32_16x16x32_bf16 v[16:19], v[194:197], v[144:147], v[16:19]
	ds_read_b128 v[160:163], v245 offset:16384
	v_mfma_f32_16x16x32_bf16 v[20:23], v[202:205], v[144:147], v[20:23]
	ds_read_b128 v[164:167], v246 offset:16384
	v_mfma_f32_16x16x32_bf16 v[24:27], v[194:197], v[152:155], v[24:27]
	ds_read_b128 v[168:171], v245 offset:18432
	v_mfma_f32_16x16x32_bf16 v[28:31], v[202:205], v[152:155], v[28:31]
	ds_read_b128 v[172:175], v246 offset:18432
	v_mfma_f32_16x16x32_bf16 v[0:3], v[198:201], v[132:135], v[0:3]
	ds_read_b128 v[176:179], v245 offset:20480
	v_mfma_f32_16x16x32_bf16 v[4:7], v[206:209], v[132:135], v[4:7]
	ds_read_b128 v[180:183], v246 offset:20480
	v_mfma_f32_16x16x32_bf16 v[8:11], v[198:201], v[140:143], v[8:11]
	ds_read_b128 v[186:189], v245 offset:22528
	v_mfma_f32_16x16x32_bf16 v[12:15], v[206:209], v[140:143], v[12:15]
	ds_read_b128 v[190:193], v246 offset:22528
	v_mfma_f32_16x16x32_bf16 v[16:19], v[198:201], v[148:151], v[16:19]
	v_mfma_f32_16x16x32_bf16 v[20:23], v[206:209], v[148:151], v[20:23]
	v_mfma_f32_16x16x32_bf16 v[24:27], v[198:201], v[156:159], v[24:27]
	v_mfma_f32_16x16x32_bf16 v[28:31], v[206:209], v[156:159], v[28:31]
	s_waitcnt lgkmcnt(8)
	v_mfma_f32_16x16x32_bf16 v[32:35], v[210:213], v[128:131], v[32:35]
	v_mfma_f32_16x16x32_bf16 v[36:39], v[218:221], v[128:131], v[36:39]
	s_add_i32 m0, s35, 0x0
	v_mfma_f32_16x16x32_bf16 v[40:43], v[210:213], v[136:139], v[40:43]
	global_load_lds_dwordx4 v249, s[30:31]
	v_mfma_f32_16x16x32_bf16 v[44:47], v[218:221], v[136:139], v[44:47]
	v_mfma_f32_16x16x32_bf16 v[48:51], v[210:213], v[144:147], v[48:51]
	s_add_i32 m0, s35, 0x2000
	v_mfma_f32_16x16x32_bf16 v[52:55], v[218:221], v[144:147], v[52:55]
	global_load_lds_dwordx4 v250, s[30:31]
	v_mfma_f32_16x16x32_bf16 v[56:59], v[210:213], v[152:155], v[56:59]
	v_mfma_f32_16x16x32_bf16 v[60:63], v[218:221], v[152:155], v[60:63]
	s_add_i32 m0, s35, 0x10000
	v_mfma_f32_16x16x32_bf16 v[32:35], v[214:217], v[132:135], v[32:35]
	global_load_lds_dwordx4 v251, s[32:33]
	v_mfma_f32_16x16x32_bf16 v[36:39], v[222:225], v[132:135], v[36:39]
	v_mfma_f32_16x16x32_bf16 v[40:43], v[214:217], v[140:143], v[40:43]
	s_add_i32 m0, s35, 0x12000
	v_mfma_f32_16x16x32_bf16 v[44:47], v[222:225], v[140:143], v[44:47]
	global_load_lds_dwordx4 v252, s[32:33]
	v_mfma_f32_16x16x32_bf16 v[48:51], v[214:217], v[148:151], v[48:51]
	v_mfma_f32_16x16x32_bf16 v[52:55], v[222:225], v[148:151], v[52:55]
	v_mfma_f32_16x16x32_bf16 v[56:59], v[214:217], v[156:159], v[56:59]
	v_mfma_f32_16x16x32_bf16 v[60:63], v[222:225], v[156:159], v[60:63]
	s_waitcnt vmcnt(8)
	s_waitcnt lgkmcnt(0)
	s_barrier
	v_mfma_f32_16x16x32_bf16 v[96:99], v[210:213], v[160:163], v[96:99]
	ds_read_b128 v[128:131], v245 offset:32768
	v_mfma_f32_16x16x32_bf16 v[100:103], v[218:221], v[160:163], v[100:103]
	ds_read_b128 v[132:135], v246 offset:32768
	v_mfma_f32_16x16x32_bf16 v[104:107], v[210:213], v[168:171], v[104:107]
	ds_read_b128 v[136:139], v245 offset:34816
	v_mfma_f32_16x16x32_bf16 v[108:111], v[218:221], v[168:171], v[108:111]
	ds_read_b128 v[140:143], v246 offset:34816
	v_mfma_f32_16x16x32_bf16 v[112:115], v[210:213], v[176:179], v[112:115]
	ds_read_b128 v[144:147], v245 offset:36864
	v_mfma_f32_16x16x32_bf16 v[116:119], v[218:221], v[176:179], v[116:119]
	ds_read_b128 v[148:151], v246 offset:36864
	v_mfma_f32_16x16x32_bf16 v[120:123], v[210:213], v[186:189], v[120:123]
	ds_read_b128 v[152:155], v245 offset:38912
	v_mfma_f32_16x16x32_bf16 v[124:127], v[218:221], v[186:189], v[124:127]
	ds_read_b128 v[156:159], v246 offset:38912
	v_mfma_f32_16x16x32_bf16 v[96:99], v[214:217], v[164:167], v[96:99]
	v_mfma_f32_16x16x32_bf16 v[100:103], v[222:225], v[164:167], v[100:103]
	v_mfma_f32_16x16x32_bf16 v[104:107], v[214:217], v[172:175], v[104:107]
	v_mfma_f32_16x16x32_bf16 v[108:111], v[222:225], v[172:175], v[108:111]
	v_mfma_f32_16x16x32_bf16 v[112:115], v[214:217], v[180:183], v[112:115]
	v_mfma_f32_16x16x32_bf16 v[116:119], v[222:225], v[180:183], v[116:119]
	v_mfma_f32_16x16x32_bf16 v[120:123], v[214:217], v[190:193], v[120:123]
	v_mfma_f32_16x16x32_bf16 v[124:127], v[222:225], v[190:193], v[124:127]
	v_mfma_f32_16x16x32_bf16 v[64:67], v[194:197], v[160:163], v[64:67]
	ds_read_b128 v[210:213], v247 offset:49152
	v_mfma_f32_16x16x32_bf16 v[68:71], v[202:205], v[160:163], v[68:71]
	ds_read_b128 v[214:217], v248 offset:49152
	v_mfma_f32_16x16x32_bf16 v[72:75], v[194:197], v[168:171], v[72:75]
	ds_read_b128 v[218:221], v247 offset:51200
	v_mfma_f32_16x16x32_bf16 v[76:79], v[202:205], v[168:171], v[76:79]
	ds_read_b128 v[222:225], v248 offset:51200
	v_mfma_f32_16x16x32_bf16 v[80:83], v[194:197], v[176:179], v[80:83]
	s_add_i32 m0, s35, 0x4000
	v_mfma_f32_16x16x32_bf16 v[84:87], v[202:205], v[176:179], v[84:87]
	global_load_lds_dwordx4 v249, s[56:57]
	v_mfma_f32_16x16x32_bf16 v[88:91], v[194:197], v[186:189], v[88:91]
	s_add_i32 m0, s35, 0x6000
	v_mfma_f32_16x16x32_bf16 v[92:95], v[202:205], v[186:189], v[92:95]
	global_load_lds_dwordx4 v250, s[56:57]
	v_mfma_f32_16x16x32_bf16 v[64:67], v[198:201], v[164:167], v[64:67]
	s_add_i32 m0, s35, 0x14000
	v_mfma_f32_16x16x32_bf16 v[68:71], v[206:209], v[164:167], v[68:71]
	global_load_lds_dwordx4 v251, s[58:59]
	v_mfma_f32_16x16x32_bf16 v[72:75], v[198:201], v[172:175], v[72:75]
	s_add_i32 m0, s35, 0x16000
	v_mfma_f32_16x16x32_bf16 v[76:79], v[206:209], v[172:175], v[76:79]
	global_load_lds_dwordx4 v252, s[58:59]
	v_mfma_f32_16x16x32_bf16 v[80:83], v[198:201], v[180:183], v[80:83]
	s_add_u32 s30, s30, 128
	s_addc_u32 s31, s31, 0
	v_mfma_f32_16x16x32_bf16 v[84:87], v[206:209], v[180:183], v[84:87]
	s_add_u32 s56, s56, 128
	s_addc_u32 s57, s57, 0
	v_mfma_f32_16x16x32_bf16 v[88:91], v[198:201], v[190:193], v[88:91]
	s_add_u32 s32, s32, 128
	s_addc_u32 s33, s33, 0
	v_mfma_f32_16x16x32_bf16 v[92:95], v[206:209], v[190:193], v[92:95]
	s_add_u32 s58, s58, 128
	s_addc_u32 s59, s59, 0
	s_waitcnt vmcnt(8)
	s_waitcnt lgkmcnt(0)
	s_barrier
; #define PG8_STAGE(bufoff, gbase, voff) do { _Pragma("unroll") for (int _i = 0; _i < 2; ++_i) \
;         __builtin_amdgcn_global_load_lds((const unsigned*)((const char*)(gbase) + (voff)[_i]), (PG8_LAS unsigned*)(lds + (bufoff) + ldsw + _i * 8192), 16, 0, 0); } while (0)
; #define PG8_LDA(dst, b, h) do { _Pragma("unroll") for (int m = 0; m < 4; ++m) _Pragma("unroll") for (int k = 0; k < 2; ++k) dst[m][k] = *(const PG8_LAS bf16x8*)(lds + PG8_SA(b, h) + aoff + m * 2048 + k * 1024); } while (0)
; #define PG8_LDB(dst, b, h) do { _Pragma("unroll") for (int n = 0; n < 2; ++n) _Pragma("unroll") for (int k = 0; k < 2; ++k) dst[n][k] = *(const PG8_LAS bf16x8*)(lds + PG8_SB(b, h) + boff + n * 2048 + k * 1024); } while (0)
; #define PG8_MMA(ai, bj, At, Bt) do { __builtin_amdgcn_s_setprio(1); _Pragma("unroll") for (int m = 0; m < 4; ++m) _Pragma("unroll") for (int n = 0; n < 2; ++n) _Pragma("unroll") for (int k = 0; k < 2; ++k) \
;         acc[ai][bj][m][n] = __builtin_amdgcn_mfma_f32_16x16x32_bf16(Bt[n][k], At[m][k], acc[ai][bj][m][n], 0, 0, 0); __builtin_amdgcn_s_setprio(0); } while (0)
; #define PG8_WAIT_V(n) asm volatile("s_waitcnt vmcnt(" #n ")" ::: "memory")
; #define PG8_WAIT_L(n) asm volatile("s_waitcnt lgkmcnt(" #n ")" ::: "memory")
; #define PG8_BAR __builtin_amdgcn_s_barrier()
; #define PG8_SCHED __builtin_amdgcn_sched_barrier(0)
; template <class Epi, class Sched, bool ALIGN_EPI = false, bool SP2 = false>
; __device__ __forceinline__ void gemm_phase(PG8_LAS unsigned char* lds, const Gemm g, const Sched& S, const Epi& E) {
;     ...
;             const char* a2 = last ? nA : cA + (size_t)(t + 2) * kstep; const char* b2 = last ? nB : cB + (size_t)(t + 2) * kstep;
;     ...
;             PG8_LDB(B0, 1, 0); PG8_LDB(B1, 1, 1); PG8_SCHED; PG8_LDA(At, 1, 0); PG8_STAGE(PG8_SA(0, 1), a2 + hstep, voffA);
;             PG8_WAIT_V(8); PG8_WAIT_L(0); PG8_BAR; PG8_MMA(0, 0, At, B0); PG8_MMA(0, 1, At, B1); PG8_BAR; PG8_SCHED;
;             PG8_LDA(At, 1, 1); PG8_STAGE(PG8_SB(1, 0), b3, voffB); PG8_STAGE(PG8_SB(1, 1), b3 + hstep, voffB); PG8_STAGE(PG8_SA(1, 0), a3, voffA);
;             PG8_WAIT_V(8); PG8_WAIT_L(0); PG8_BAR; PG8_MMA(1, 0, At, B0); PG8_MMA(1, 1, At, B1); PG8_BAR; PG8_SCHED;
	v_mfma_f32_16x16x32_bf16 v[32:35], v[210:213], v[128:131], v[32:35]
	ds_read_b128 v[194:197], v247 offset:32768
	v_mfma_f32_16x16x32_bf16 v[36:39], v[218:221], v[128:131], v[36:39]
	ds_read_b128 v[198:201], v248 offset:32768
	v_mfma_f32_16x16x32_bf16 v[40:43], v[210:213], v[136:139], v[40:43]
	ds_read_b128 v[202:205], v247 offset:34816
	v_mfma_f32_16x16x32_bf16 v[44:47], v[218:221], v[136:139], v[44:47]
	ds_read_b128 v[206:209], v248 offset:34816
	v_mfma_f32_16x16x32_bf16 v[48:51], v[210:213], v[144:147], v[48:51]
	ds_read_b128 v[160:163], v245 offset:49152
	v_mfma_f32_16x16x32_bf16 v[52:55], v[218:221], v[144:147], v[52:55]
	ds_read_b128 v[164:167], v246 offset:49152
	v_mfma_f32_16x16x32_bf16 v[56:59], v[210:213], v[152:155], v[56:59]
	ds_read_b128 v[168:171], v245 offset:51200
	v_mfma_f32_16x16x32_bf16 v[60:63], v[218:221], v[152:155], v[60:63]
	ds_read_b128 v[172:175], v246 offset:51200
	v_mfma_f32_16x16x32_bf16 v[32:35], v[214:217], v[132:135], v[32:35]
	ds_read_b128 v[176:179], v245 offset:53248
	v_mfma_f32_16x16x32_bf16 v[36:39], v[222:225], v[132:135], v[36:39]
	ds_read_b128 v[180:183], v246 offset:53248
	v_mfma_f32_16x16x32_bf16 v[40:43], v[214:217], v[140:143], v[40:43]
	ds_read_b128 v[186:189], v245 offset:55296
	v_mfma_f32_16x16x32_bf16 v[44:47], v[222:225], v[140:143], v[44:47]
	ds_read_b128 v[190:193], v246 offset:55296
	v_mfma_f32_16x16x32_bf16 v[48:51], v[214:217], v[148:151], v[48:51]
	v_mfma_f32_16x16x32_bf16 v[52:55], v[222:225], v[148:151], v[52:55]
	v_mfma_f32_16x16x32_bf16 v[56:59], v[214:217], v[156:159], v[56:59]
	v_mfma_f32_16x16x32_bf16 v[60:63], v[222:225], v[156:159], v[60:63]
	s_waitcnt lgkmcnt(8)
	v_mfma_f32_16x16x32_bf16 v[0:3], v[194:197], v[128:131], v[0:3]
	v_mfma_f32_16x16x32_bf16 v[4:7], v[202:205], v[128:131], v[4:7]
	s_add_i32 m0, s35, 0x8000
	v_mfma_f32_16x16x32_bf16 v[8:11], v[194:197], v[136:139], v[8:11]
	global_load_lds_dwordx4 v249, s[30:31]
	v_mfma_f32_16x16x32_bf16 v[12:15], v[202:205], v[136:139], v[12:15]
	v_mfma_f32_16x16x32_bf16 v[16:19], v[194:197], v[144:147], v[16:19]
	s_add_i32 m0, s35, 0xa000
	v_mfma_f32_16x16x32_bf16 v[20:23], v[202:205], v[144:147], v[20:23]
	global_load_lds_dwordx4 v250, s[30:31]
	v_mfma_f32_16x16x32_bf16 v[24:27], v[194:197], v[152:155], v[24:27]
	v_mfma_f32_16x16x32_bf16 v[28:31], v[202:205], v[152:155], v[28:31]
	s_add_i32 m0, s35, 0x1c000
	v_mfma_f32_16x16x32_bf16 v[0:3], v[198:201], v[132:135], v[0:3]
	global_load_lds_dwordx4 v251, s[58:59]
	v_mfma_f32_16x16x32_bf16 v[4:7], v[206:209], v[132:135], v[4:7]
	v_mfma_f32_16x16x32_bf16 v[8:11], v[198:201], v[140:143], v[8:11]
	s_add_i32 m0, s35, 0x1e000
	v_mfma_f32_16x16x32_bf16 v[12:15], v[206:209], v[140:143], v[12:15]
	global_load_lds_dwordx4 v252, s[58:59]
	v_mfma_f32_16x16x32_bf16 v[16:19], v[198:201], v[148:151], v[16:19]
	v_mfma_f32_16x16x32_bf16 v[20:23], v[206:209], v[148:151], v[20:23]
	v_mfma_f32_16x16x32_bf16 v[24:27], v[198:201], v[156:159], v[24:27]
	v_mfma_f32_16x16x32_bf16 v[28:31], v[206:209], v[156:159], v[28:31]
	s_waitcnt vmcnt(8)
	s_waitcnt lgkmcnt(0)
	s_barrier
	v_mfma_f32_16x16x32_bf16 v[64:67], v[194:197], v[160:163], v[64:67]
	ds_read_b128 v[128:131], v245 offset:0
	v_mfma_f32_16x16x32_bf16 v[68:71], v[202:205], v[160:163], v[68:71]
	ds_read_b128 v[132:135], v246 offset:0
	v_mfma_f32_16x16x32_bf16 v[72:75], v[194:197], v[168:171], v[72:75]
	ds_read_b128 v[136:139], v245 offset:2048
	v_mfma_f32_16x16x32_bf16 v[76:79], v[202:205], v[168:171], v[76:79]
	ds_read_b128 v[140:143], v246 offset:2048
	v_mfma_f32_16x16x32_bf16 v[80:83], v[194:197], v[176:179], v[80:83]
	ds_read_b128 v[144:147], v245 offset:4096
	v_mfma_f32_16x16x32_bf16 v[84:87], v[202:205], v[176:179], v[84:87]
	ds_read_b128 v[148:151], v246 offset:4096
	v_mfma_f32_16x16x32_bf16 v[88:91], v[194:197], v[186:189], v[88:91]
	ds_read_b128 v[152:155], v245 offset:6144
	v_mfma_f32_16x16x32_bf16 v[92:95], v[202:205], v[186:189], v[92:95]
	ds_read_b128 v[156:159], v246 offset:6144
	v_mfma_f32_16x16x32_bf16 v[64:67], v[198:201], v[164:167], v[64:67]
	v_mfma_f32_16x16x32_bf16 v[68:71], v[206:209], v[164:167], v[68:71]
	v_mfma_f32_16x16x32_bf16 v[72:75], v[198:201], v[172:175], v[72:75]
	v_mfma_f32_16x16x32_bf16 v[76:79], v[206:209], v[172:175], v[76:79]
	v_mfma_f32_16x16x32_bf16 v[80:83], v[198:201], v[180:183], v[80:83]
	v_mfma_f32_16x16x32_bf16 v[84:87], v[206:209], v[180:183], v[84:87]
	v_mfma_f32_16x16x32_bf16 v[88:91], v[198:201], v[190:193], v[88:91]
	v_mfma_f32_16x16x32_bf16 v[92:95], v[206:209], v[190:193], v[92:95]
	v_mfma_f32_16x16x32_bf16 v[96:99], v[210:213], v[160:163], v[96:99]
	ds_read_b128 v[194:197], v247 offset:0
	v_mfma_f32_16x16x32_bf16 v[100:103], v[218:221], v[160:163], v[100:103]
	ds_read_b128 v[198:201], v248 offset:0
	v_mfma_f32_16x16x32_bf16 v[104:107], v[210:213], v[168:171], v[104:107]
	ds_read_b128 v[202:205], v247 offset:2048
	v_mfma_f32_16x16x32_bf16 v[108:111], v[218:221], v[168:171], v[108:111]
	ds_read_b128 v[206:209], v248 offset:2048
	v_mfma_f32_16x16x32_bf16 v[112:115], v[210:213], v[176:179], v[112:115]
	s_add_i32 m0, s35, 0xc000
	v_mfma_f32_16x16x32_bf16 v[116:119], v[218:221], v[176:179], v[116:119]
	global_load_lds_dwordx4 v249, s[56:57]
	v_mfma_f32_16x16x32_bf16 v[120:123], v[210:213], v[186:189], v[120:123]
	s_add_i32 m0, s35, 0xe000
	v_mfma_f32_16x16x32_bf16 v[124:127], v[218:221], v[186:189], v[124:127]
	global_load_lds_dwordx4 v250, s[56:57]
	v_mfma_f32_16x16x32_bf16 v[96:99], v[214:217], v[164:167], v[96:99]
	s_add_i32 m0, s35, 0x18000
	v_mfma_f32_16x16x32_bf16 v[100:103], v[222:225], v[164:167], v[100:103]
	global_load_lds_dwordx4 v251, s[32:33]
	v_mfma_f32_16x16x32_bf16 v[104:107], v[214:217], v[172:175], v[104:107]
	s_add_i32 m0, s35, 0x1a000
	v_mfma_f32_16x16x32_bf16 v[108:111], v[222:225], v[172:175], v[108:111]
	global_load_lds_dwordx4 v252, s[32:33]
	v_mfma_f32_16x16x32_bf16 v[112:115], v[214:217], v[180:183], v[112:115]
	s_add_u32 s30, s30, 128
	s_addc_u32 s31, s31, 0
	v_mfma_f32_16x16x32_bf16 v[116:119], v[222:225], v[180:183], v[116:119]
	s_add_u32 s56, s56, 128
	s_addc_u32 s57, s57, 0
	v_mfma_f32_16x16x32_bf16 v[120:123], v[214:217], v[190:193], v[120:123]
	s_add_u32 s32, s32, 128
	s_addc_u32 s33, s33, 0
	v_mfma_f32_16x16x32_bf16 v[124:127], v[222:225], v[190:193], v[124:127]
	s_add_u32 s58, s58, 128
	s_addc_u32 s59, s59, 0
	s_add_i32 s34, s34, -1
	s_cmp_lg_u32 s34, 1
	s_cbranch_scc1 .Lp5_nosw1
	s_add_u32 s30, s26, 0
	s_addc_u32 s31, s27, 0
	s_add_u32 s32, s28, 0
	s_addc_u32 s33, s29, 0
	s_add_u32 s56, s30, 0x80000
	s_addc_u32 s57, s31, 0
	s_add_u32 s58, s32, 0x80000
	s_addc_u32 s59, s33, 0

;     __device__ __forceinline__ void operator()(const f32x4 (&acc)[2][2][4][2], const Unit& u, int wr, int wc, int fr, int fq) const {
;         const int row0 = u.pm * BM + wr * 64 + fr, col0 = u.pn * HALF + wc * 32 + 8 * fq;
;         float rsv[2][4];
; #pragma unroll
;         for (int ai = 0; ai < 2; ++ai)
; #pragma unroll
;             for (int m = 0; m < 4; ++m) rsv[ai][m] = ss[row0 + ai * HALF + m * 16];
;         asm volatile("" ::: "memory");
; #pragma unroll
;         for (int ai = 0; ai < 2; ++ai)
; #pragma unroll
;             for (int m = 0; m < 4; ++m) { const int row = row0 + ai * HALF + m * 16; const float rs = __builtin_amdgcn_rsqf(rsv[ai][m] * inv_n + eps);
;                 float a[8];
; #pragma unroll
;                 for (int n = 0; n < 2; ++n)
; #pragma unroll
;                     for (int i = 0; i < 4; ++i) { const float g = acc[ai][0][m][n][i] * rs, up = acc[ai][1][m][n][i] * rs;
.Lp5_kdone:
	s_waitcnt lgkmcnt(0)
	s_nop 7
	s_nop 7
	v_and_b32_e32 v254, 63, v185
	v_and_b32_e32 v255, 15, v254
	v_lshrrev_b32_e32 v226, 4, v254
	s_lshl_b32 s40, s37, 6
	v_add_u32_e32 v255, s40, v255
	v_lshlrev_b32_e32 v128, 2, v255
	v_mul_u32_u24_e32 v129, 0x2c00, v255
	s_lshl_b32 s41, s38, 6
	v_lshl_add_u32 v129, v226, 4, v129
	v_add_u32_e32 v129, s41, v129
	v_mov_b32_e32 v130, 0x358637bd
	s_lshl_b32 s40, s17, 10
	s_add_u32 s48, s76, s40
	s_addc_u32 s49, s77, 0
	s_mul_i32 s40, s17, 0x2c0000
	s_lshl_b32 s41, s18, 8
	s_add_u32 s40, s40, s41
	s_add_u32 s50, s76, 0xa800000
	s_addc_u32 s51, s77, 0
	s_add_u32 s50, s50, s40
	s_addc_u32 s51, s51, 0
	global_load_dword v134, v128, s[48:49] offset:0
	global_load_dword v135, v128, s[48:49] offset:64
	global_load_dword v136, v128, s[48:49] offset:128
	global_load_dword v137, v128, s[48:49] offset:192
	global_load_dword v138, v128, s[48:49] offset:512
	global_load_dword v139, v128, s[48:49] offset:576
	global_load_dword v140, v128, s[48:49] offset:640
	global_load_dword v141, v128, s[48:49] offset:704
	s_waitcnt vmcnt(0)
	v_fmamk_f32 v131, v134, 0x3a000000, v130
	v_add_u32_e32 v132, 0x0, v129
	v_rsq_f32_e32 v131, v131
	s_nop 0
	v_mul_f32_e32 v0, v0, v131
	v_mul_f32_e32 v1, v1, v131
	v_mul_f32_e32 v2, v2, v131
	v_mul_f32_e32 v3, v3, v131
	v_mul_f32_e32 v4, v4, v131
	v_mul_f32_e32 v5, v5, v131
	v_mul_f32_e32 v6, v6, v131
	v_mul_f32_e32 v7, v7, v131
	v_mul_f32_e32 v32, v32, v131
	v_mul_f32_e32 v33, v33, v131
	v_mul_f32_e32 v34, v34, v131
	v_mul_f32_e32 v35, v35, v131
	v_mul_f32_e32 v36, v36, v131
	v_mul_f32_e32 v37, v37, v131
	v_mul_f32_e32 v38, v38, v131
	v_mul_f32_e32 v39, v39, v131
	v_mul_f32_e32 v144, 0xbfb8aa3b, v0
	v_mul_f32_e32 v145, 0xbfb8aa3b, v1
	v_mul_f32_e32 v146, 0xbfb8aa3b, v2
	v_mul_f32_e32 v147, 0xbfb8aa3b, v3
	v_mul_f32_e32 v148, 0xbfb8aa3b, v4
	v_mul_f32_e32 v149, 0xbfb8aa3b, v5
	v_mul_f32_e32 v150, 0xbfb8aa3b, v6
	v_mul_f32_e32 v151, 0xbfb8aa3b, v7
	v_exp_f32_e32 v144, v144
	v_exp_f32_e32 v145, v145
	v_exp_f32_e32 v146, v146
	v_exp_f32_e32 v147, v147
	v_exp_f32_e32 v148, v148
	v_exp_f32_e32 v149, v149
	v_exp_f32_e32 v150, v150
	v_exp_f32_e32 v151, v151
	v_add_f32_e32 v144, 1.0, v144
	v_add_f32_e32 v145, 1.0, v145
	v_add_f32_e32 v146, 1.0, v146
	v_add_f32_e32 v147, 1.0, v147
	v_add_f32_e32 v148, 1.0, v148
	v_add_f32_e32 v149, 1.0, v149
	v_add_f32_e32 v150, 1.0, v150
	v_add_f32_e32 v151, 1.0, v151
	v_rcp_f32_e32 v144, v144
	v_rcp_f32_e32 v145, v145
	v_rcp_f32_e32 v146, v146
	v_rcp_f32_e32 v147, v147
	v_rcp_f32_e32 v148, v148
	v_rcp_f32_e32 v149, v149
	v_rcp_f32_e32 v150, v150
	v_rcp_f32_e32 v151, v151
	v_mul_f32_e32 v0, v0, v144
	v_mul_f32_e32 v1, v1, v145
	v_mul_f32_e32 v2, v2, v146
	v_mul_f32_e32 v3, v3, v147
	v_mul_f32_e32 v4, v4, v148
	v_mul_f32_e32 v5, v5, v149
	v_mul_f32_e32 v6, v6, v150
	v_mul_f32_e32 v7, v7, v151
	v_mul_f32_e32 v0, v32, v0
	v_mul_f32_e32 v1, v33, v1
	v_mul_f32_e32 v2, v34, v2
	v_mul_f32_e32 v3, v35, v3
	v_mul_f32_e32 v4, v36, v4
	v_mul_f32_e32 v5, v37, v5
	v_mul_f32_e32 v6, v38, v6
	v_mul_f32_e32 v7, v39, v7
	v_cvt_pk_bf16_f32 v152, v0, v1
	v_cvt_pk_bf16_f32 v153, v2, v3
	v_cvt_pk_bf16_f32 v154, v4, v5
	v_cvt_pk_bf16_f32 v155, v6, v7
	s_nop 1
	global_store_dwordx4 v132, v[152:155], s[50:51]
	s_nop 1
	v_fmamk_f32 v131, v135, 0x3a000000, v130
	v_add_u32_e32 v132, 0x2c000, v129
	v_rsq_f32_e32 v131, v131
	s_nop 0
	v_mul_f32_e32 v8, v8, v131
	v_mul_f32_e32 v9, v9, v131
	v_mul_f32_e32 v10, v10, v131
	v_mul_f32_e32 v11, v11, v131
	v_mul_f32_e32 v12, v12, v131
	v_mul_f32_e32 v13, v13, v131
	v_mul_f32_e32 v14, v14, v131
	v_mul_f32_e32 v15, v15, v131
	v_mul_f32_e32 v40, v40, v131
	v_mul_f32_e32 v41, v41, v131
	v_mul_f32_e32 v42, v42, v131
	v_mul_f32_e32 v43, v43, v131
	v_mul_f32_e32 v44, v44, v131
	v_mul_f32_e32 v45, v45, v131
	v_mul_f32_e32 v46, v46, v131
	v_mul_f32_e32 v47, v47, v131
	v_mul_f32_e32 v144, 0xbfb8aa3b, v8
	v_mul_f32_e32 v145, 0xbfb8aa3b, v9
	v_mul_f32_e32 v146, 0xbfb8aa3b, v10
	v_mul_f32_e32 v147, 0xbfb8aa3b, v11
	v_mul_f32_e32 v148, 0xbfb8aa3b, v12
	v_mul_f32_e32 v149, 0xbfb8aa3b, v13
	v_mul_f32_e32 v150, 0xbfb8aa3b, v14
	v_mul_f32_e32 v151, 0xbfb8aa3b, v15
	v_exp_f32_e32 v144, v144
	v_exp_f32_e32 v145, v145
	v_exp_f32_e32 v146, v146
	v_exp_f32_e32 v147, v147
	v_exp_f32_e32 v148, v148
	v_exp_f32_e32 v149, v149
	v_exp_f32_e32 v150, v150
	v_exp_f32_e32 v151, v151
	v_add_f32_e32 v144, 1.0, v144
	v_add_f32_e32 v145, 1.0, v145
	v_add_f32_e32 v146, 1.0, v146
	v_add_f32_e32 v147, 1.0, v147
	v_add_f32_e32 v148, 1.0, v148
	v_add_f32_e32 v149, 1.0, v149
	v_add_f32_e32 v150, 1.0, v150
	v_add_f32_e32 v151, 1.0, v151
	v_rcp_f32_e32 v144, v144
	v_rcp_f32_e32 v145, v145
	v_rcp_f32_e32 v146, v146
	v_rcp_f32_e32 v147, v147
	v_rcp_f32_e32 v148, v148
	v_rcp_f32_e32 v149, v149
	v_rcp_f32_e32 v150, v150
	v_rcp_f32_e32 v151, v151
	v_mul_f32_e32 v8, v8, v144
	v_mul_f32_e32 v9, v9, v145
	v_mul_f32_e32 v10, v10, v146
	v_mul_f32_e32 v11, v11, v147
	v_mul_f32_e32 v12, v12, v148
	v_mul_f32_e32 v13, v13, v149
	v_mul_f32_e32 v14, v14, v150
	v_mul_f32_e32 v15, v15, v151
	v_mul_f32_e32 v8, v40, v8
	v_mul_f32_e32 v9, v41, v9
	v_mul_f32_e32 v10, v42, v10
	v_mul_f32_e32 v11, v43, v11
	v_mul_f32_e32 v12, v44, v12
	v_mul_f32_e32 v13, v45, v13
	v_mul_f32_e32 v14, v46, v14
	v_mul_f32_e32 v15, v47, v15
	v_cvt_pk_bf16_f32 v152, v8, v9
	v_cvt_pk_bf16_f32 v153, v10, v11
	v_cvt_pk_bf16_f32 v154, v12, v13
	v_cvt_pk_bf16_f32 v155, v14, v15
	s_nop 1
	global_store_dwordx4 v132, v[152:155], s[50:51]
	s_nop 1
	v_fmamk_f32 v131, v136, 0x3a000000, v130
	v_add_u32_e32 v132, 0x58000, v129
	v_rsq_f32_e32 v131, v131
	s_nop 0
	v_mul_f32_e32 v16, v16, v131
	v_mul_f32_e32 v17, v17, v131
	v_mul_f32_e32 v18, v18, v131
; __device__ __forceinline__ unsigned cvt_pk_bf16(float lo, float hi) { unsigned r; asm volatile("v_cvt_pk_bf16_f32 %0, %1, %2" : "=v"(r) : "v"(lo), "v"(hi)); return r; }
;     __device__ __forceinline__ void operator()(const f32x4 (&acc)[2][2][4][2], const Unit& u, int wr, int wc, int fr, int fq) const {
;     ...
;         for (int ai = 0; ai < 2; ++ai)
; #pragma unroll
;             for (int m = 0; m < 4; ++m) { const int row = row0 + ai * HALF + m * 16; const float rs = __builtin_amdgcn_rsqf(rsv[ai][m] * inv_n + eps);
;                 float a[8];
; #pragma unroll
;                 for (int n = 0; n < 2; ++n)
; #pragma unroll
;                     for (int i = 0; i < 4; ++i) { const float g = acc[ai][0][m][n][i] * rs, up = acc[ai][1][m][n][i] * rs;
;                         a[n * 4 + i] = g * __builtin_amdgcn_rcpf(1.0f + __builtin_amdgcn_exp2f(-1.4426950408889634f * g)) * up; }
;                 u32x4 w; w.x = cvt_pk_bf16(a[0], a[1]); w.y = cvt_pk_bf16(a[2], a[3]); w.z = cvt_pk_bf16(a[4], a[5]); w.w = cvt_pk_bf16(a[6], a[7]);
;                 *(u32x4*)(O + (size_t)row * ldc + col0) = w; }
	v_mul_f32_e32 v19, v19, v131
	v_mul_f32_e32 v20, v20, v131
	v_mul_f32_e32 v21, v21, v131
	v_mul_f32_e32 v22, v22, v131
	v_mul_f32_e32 v23, v23, v131
	v_mul_f32_e32 v48, v48, v131
	v_mul_f32_e32 v49, v49, v131
	v_mul_f32_e32 v50, v50, v131
	v_mul_f32_e32 v51, v51, v131
	v_mul_f32_e32 v52, v52, v131
	v_mul_f32_e32 v53, v53, v131
	v_mul_f32_e32 v54, v54, v131
	v_mul_f32_e32 v55, v55, v131
	v_mul_f32_e32 v144, 0xbfb8aa3b, v16
	v_mul_f32_e32 v145, 0xbfb8aa3b, v17
	v_mul_f32_e32 v146, 0xbfb8aa3b, v18
	v_mul_f32_e32 v147, 0xbfb8aa3b, v19
	v_mul_f32_e32 v148, 0xbfb8aa3b, v20
	v_mul_f32_e32 v149, 0xbfb8aa3b, v21
	v_mul_f32_e32 v150, 0xbfb8aa3b, v22
	v_mul_f32_e32 v151, 0xbfb8aa3b, v23
	v_exp_f32_e32 v144, v144
	v_exp_f32_e32 v145, v145
	v_exp_f32_e32 v146, v146
	v_exp_f32_e32 v147, v147
	v_exp_f32_e32 v148, v148
	v_exp_f32_e32 v149, v149
	v_exp_f32_e32 v150, v150
	v_exp_f32_e32 v151, v151
	v_add_f32_e32 v144, 1.0, v144
	v_add_f32_e32 v145, 1.0, v145
	v_add_f32_e32 v146, 1.0, v146
	v_add_f32_e32 v147, 1.0, v147
	v_add_f32_e32 v148, 1.0, v148
	v_add_f32_e32 v149, 1.0, v149
	v_add_f32_e32 v150, 1.0, v150
	v_add_f32_e32 v151, 1.0, v151
	v_rcp_f32_e32 v144, v144
	v_rcp_f32_e32 v145, v145
	v_rcp_f32_e32 v146, v146
	v_rcp_f32_e32 v147, v147
	v_rcp_f32_e32 v148, v148
	v_rcp_f32_e32 v149, v149
	v_rcp_f32_e32 v150, v150
	v_rcp_f32_e32 v151, v151
	v_mul_f32_e32 v16, v16, v144
	v_mul_f32_e32 v17, v17, v145
	v_mul_f32_e32 v18, v18, v146
	v_mul_f32_e32 v19, v19, v147
	v_mul_f32_e32 v20, v20, v148
	v_mul_f32_e32 v21, v21, v149
	v_mul_f32_e32 v22, v22, v150
	v_mul_f32_e32 v23, v23, v151
	v_mul_f32_e32 v16, v48, v16
	v_mul_f32_e32 v17, v49, v17
	v_mul_f32_e32 v18, v50, v18
	v_mul_f32_e32 v19, v51, v19
	v_mul_f32_e32 v20, v52, v20
	v_mul_f32_e32 v21, v53, v21
	v_mul_f32_e32 v22, v54, v22
	v_mul_f32_e32 v23, v55, v23
	v_cvt_pk_bf16_f32 v152, v16, v17
	v_cvt_pk_bf16_f32 v153, v18, v19
	v_cvt_pk_bf16_f32 v154, v20, v21
	v_cvt_pk_bf16_f32 v155, v22, v23
	s_nop 1
	global_store_dwordx4 v132, v[152:155], s[50:51]
	s_nop 1
	v_fmamk_f32 v131, v137, 0x3a000000, v130
	v_add_u32_e32 v132, 0x84000, v129
	v_rsq_f32_e32 v131, v131
	s_nop 0
	v_mul_f32_e32 v24, v24, v131
	v_mul_f32_e32 v25, v25, v131
	v_mul_f32_e32 v26, v26, v131
	v_mul_f32_e32 v27, v27, v131
	v_mul_f32_e32 v28, v28, v131
	v_mul_f32_e32 v29, v29, v131
	v_mul_f32_e32 v30, v30, v131
	v_mul_f32_e32 v31, v31, v131
	v_mul_f32_e32 v56, v56, v131
	v_mul_f32_e32 v57, v57, v131
	v_mul_f32_e32 v58, v58, v131
	v_mul_f32_e32 v59, v59, v131
	v_mul_f32_e32 v60, v60, v131
	v_mul_f32_e32 v61, v61, v131
	v_mul_f32_e32 v62, v62, v131
	v_mul_f32_e32 v63, v63, v131
	v_mul_f32_e32 v144, 0xbfb8aa3b, v24
	v_mul_f32_e32 v145, 0xbfb8aa3b, v25
	v_mul_f32_e32 v146, 0xbfb8aa3b, v26
	v_mul_f32_e32 v147, 0xbfb8aa3b, v27
	v_mul_f32_e32 v148, 0xbfb8aa3b, v28
	v_mul_f32_e32 v149, 0xbfb8aa3b, v29
	v_mul_f32_e32 v150, 0xbfb8aa3b, v30
	v_mul_f32_e32 v151, 0xbfb8aa3b, v31
	v_exp_f32_e32 v144, v144
	v_exp_f32_e32 v145, v145
	v_exp_f32_e32 v146, v146
	v_exp_f32_e32 v147, v147
	v_exp_f32_e32 v148, v148
	v_exp_f32_e32 v149, v149
	v_exp_f32_e32 v150, v150
	v_exp_f32_e32 v151, v151
	v_add_f32_e32 v144, 1.0, v144
	v_add_f32_e32 v145, 1.0, v145
	v_add_f32_e32 v146, 1.0, v146
	v_add_f32_e32 v147, 1.0, v147
	v_add_f32_e32 v148, 1.0, v148
	v_add_f32_e32 v149, 1.0, v149
	v_add_f32_e32 v150, 1.0, v150
	v_add_f32_e32 v151, 1.0, v151
	v_rcp_f32_e32 v144, v144
	v_rcp_f32_e32 v145, v145
	v_rcp_f32_e32 v146, v146
	v_rcp_f32_e32 v147, v147
	v_rcp_f32_e32 v148, v148
	v_rcp_f32_e32 v149, v149
	v_rcp_f32_e32 v150, v150
	v_rcp_f32_e32 v151, v151
	v_mul_f32_e32 v24, v24, v144
	v_mul_f32_e32 v25, v25, v145
	v_mul_f32_e32 v26, v26, v146
	v_mul_f32_e32 v27, v27, v147
	v_mul_f32_e32 v28, v28, v148
	v_mul_f32_e32 v29, v29, v149
	v_mul_f32_e32 v30, v30, v150
	v_mul_f32_e32 v31, v31, v151
	v_mul_f32_e32 v24, v56, v24
	v_mul_f32_e32 v25, v57, v25
	v_mul_f32_e32 v26, v58, v26
	v_mul_f32_e32 v27, v59, v27
	v_mul_f32_e32 v28, v60, v28
	v_mul_f32_e32 v29, v61, v29
	v_mul_f32_e32 v30, v62, v30
	v_mul_f32_e32 v31, v63, v31
	v_cvt_pk_bf16_f32 v152, v24, v25
	v_cvt_pk_bf16_f32 v153, v26, v27
	v_cvt_pk_bf16_f32 v154, v28, v29
	v_cvt_pk_bf16_f32 v155, v30, v31
	s_nop 1
	global_store_dwordx4 v132, v[152:155], s[50:51]
	s_nop 1
	v_fmamk_f32 v131, v138, 0x3a000000, v130
	v_add_u32_e32 v132, 0x160000, v129
	v_rsq_f32_e32 v131, v131
	s_nop 0
	v_mul_f32_e32 v64, v64, v131
	v_mul_f32_e32 v65, v65, v131
	v_mul_f32_e32 v66, v66, v131
	v_mul_f32_e32 v67, v67, v131
	v_mul_f32_e32 v68, v68, v131
	v_mul_f32_e32 v69, v69, v131
	v_mul_f32_e32 v70, v70, v131
	v_mul_f32_e32 v71, v71, v131
	v_mul_f32_e32 v96, v96, v131
	v_mul_f32_e32 v97, v97, v131
	v_mul_f32_e32 v98, v98, v131
	v_mul_f32_e32 v99, v99, v131
	v_mul_f32_e32 v100, v100, v131
	v_mul_f32_e32 v101, v101, v131
	v_mul_f32_e32 v102, v102, v131
	v_mul_f32_e32 v103, v103, v131
	v_mul_f32_e32 v144, 0xbfb8aa3b, v64
	v_mul_f32_e32 v145, 0xbfb8aa3b, v65
	v_mul_f32_e32 v146, 0xbfb8aa3b, v66
	v_mul_f32_e32 v147, 0xbfb8aa3b, v67
	v_mul_f32_e32 v148, 0xbfb8aa3b, v68
	v_mul_f32_e32 v149, 0xbfb8aa3b, v69
	v_mul_f32_e32 v150, 0xbfb8aa3b, v70
	v_mul_f32_e32 v151, 0xbfb8aa3b, v71
	v_exp_f32_e32 v144, v144
	v_exp_f32_e32 v145, v145
	v_exp_f32_e32 v146, v146
	v_exp_f32_e32 v147, v147
	v_exp_f32_e32 v148, v148
	v_exp_f32_e32 v149, v149
	v_exp_f32_e32 v150, v150
	v_exp_f32_e32 v151, v151
	v_add_f32_e32 v144, 1.0, v144
	v_add_f32_e32 v145, 1.0, v145
	v_add_f32_e32 v146, 1.0, v146
	v_add_f32_e32 v147, 1.0, v147
	v_add_f32_e32 v148, 1.0, v148
	v_add_f32_e32 v149, 1.0, v149
	v_add_f32_e32 v150, 1.0, v150
	v_add_f32_e32 v151, 1.0, v151
	v_rcp_f32_e32 v144, v144
; __device__ __forceinline__ unsigned cvt_pk_bf16(float lo, float hi) { unsigned r; asm volatile("v_cvt_pk_bf16_f32 %0, %1, %2" : "=v"(r) : "v"(lo), "v"(hi)); return r; }
;     __device__ __forceinline__ void operator()(const f32x4 (&acc)[2][2][4][2], const Unit& u, int wr, int wc, int fr, int fq) const {
;     ...
;         for (int ai = 0; ai < 2; ++ai)
; #pragma unroll
;             for (int m = 0; m < 4; ++m) { const int row = row0 + ai * HALF + m * 16; const float rs = __builtin_amdgcn_rsqf(rsv[ai][m] * inv_n + eps);
;                 float a[8];
; #pragma unroll
;                 for (int n = 0; n < 2; ++n)
; #pragma unroll
;                     for (int i = 0; i < 4; ++i) { const float g = acc[ai][0][m][n][i] * rs, up = acc[ai][1][m][n][i] * rs;
;                         a[n * 4 + i] = g * __builtin_amdgcn_rcpf(1.0f + __builtin_amdgcn_exp2f(-1.4426950408889634f * g)) * up; }
;                 u32x4 w; w.x = cvt_pk_bf16(a[0], a[1]); w.y = cvt_pk_bf16(a[2], a[3]); w.z = cvt_pk_bf16(a[4], a[5]); w.w = cvt_pk_bf16(a[6], a[7]);
;                 *(u32x4*)(O + (size_t)row * ldc + col0) = w; }
	v_rcp_f32_e32 v145, v145
	v_rcp_f32_e32 v146, v146
	v_rcp_f32_e32 v147, v147
	v_rcp_f32_e32 v148, v148
	v_rcp_f32_e32 v149, v149
	v_rcp_f32_e32 v150, v150
	v_rcp_f32_e32 v151, v151
	v_mul_f32_e32 v64, v64, v144
	v_mul_f32_e32 v65, v65, v145
	v_mul_f32_e32 v66, v66, v146
	v_mul_f32_e32 v67, v67, v147
	v_mul_f32_e32 v68, v68, v148
	v_mul_f32_e32 v69, v69, v149
	v_mul_f32_e32 v70, v70, v150
	v_mul_f32_e32 v71, v71, v151
	v_mul_f32_e32 v64, v96, v64
	v_mul_f32_e32 v65, v97, v65
	v_mul_f32_e32 v66, v98, v66
	v_mul_f32_e32 v67, v99, v67
	v_mul_f32_e32 v68, v100, v68
	v_mul_f32_e32 v69, v101, v69
	v_mul_f32_e32 v70, v102, v70
	v_mul_f32_e32 v71, v103, v71
	v_cvt_pk_bf16_f32 v152, v64, v65
	v_cvt_pk_bf16_f32 v153, v66, v67
	v_cvt_pk_bf16_f32 v154, v68, v69
	v_cvt_pk_bf16_f32 v155, v70, v71
	s_nop 1
	global_store_dwordx4 v132, v[152:155], s[50:51]
	s_nop 1
	v_fmamk_f32 v131, v139, 0x3a000000, v130
	v_add_u32_e32 v132, 0x18c000, v129
	v_rsq_f32_e32 v131, v131
	s_nop 0
	v_mul_f32_e32 v72, v72, v131
	v_mul_f32_e32 v73, v73, v131
	v_mul_f32_e32 v74, v74, v131
	v_mul_f32_e32 v75, v75, v131
	v_mul_f32_e32 v76, v76, v131
	v_mul_f32_e32 v77, v77, v131
	v_mul_f32_e32 v78, v78, v131
	v_mul_f32_e32 v79, v79, v131
	v_mul_f32_e32 v104, v104, v131
	v_mul_f32_e32 v105, v105, v131
	v_mul_f32_e32 v106, v106, v131
	v_mul_f32_e32 v107, v107, v131
	v_mul_f32_e32 v108, v108, v131
	v_mul_f32_e32 v109, v109, v131
	v_mul_f32_e32 v110, v110, v131
	v_mul_f32_e32 v111, v111, v131
	v_mul_f32_e32 v144, 0xbfb8aa3b, v72
	v_mul_f32_e32 v145, 0xbfb8aa3b, v73
	v_mul_f32_e32 v146, 0xbfb8aa3b, v74
	v_mul_f32_e32 v147, 0xbfb8aa3b, v75
	v_mul_f32_e32 v148, 0xbfb8aa3b, v76
	v_mul_f32_e32 v149, 0xbfb8aa3b, v77
	v_mul_f32_e32 v150, 0xbfb8aa3b, v78
	v_mul_f32_e32 v151, 0xbfb8aa3b, v79
	v_exp_f32_e32 v144, v144
	v_exp_f32_e32 v145, v145
	v_exp_f32_e32 v146, v146
	v_exp_f32_e32 v147, v147
	v_exp_f32_e32 v148, v148
	v_exp_f32_e32 v149, v149
	v_exp_f32_e32 v150, v150
	v_exp_f32_e32 v151, v151
	v_add_f32_e32 v144, 1.0, v144
	v_add_f32_e32 v145, 1.0, v145
	v_add_f32_e32 v146, 1.0, v146
	v_add_f32_e32 v147, 1.0, v147
	v_add_f32_e32 v148, 1.0, v148
	v_add_f32_e32 v149, 1.0, v149
	v_add_f32_e32 v150, 1.0, v150
	v_add_f32_e32 v151, 1.0, v151
	v_rcp_f32_e32 v144, v144
	v_rcp_f32_e32 v145, v145
	v_rcp_f32_e32 v146, v146
	v_rcp_f32_e32 v147, v147
	v_rcp_f32_e32 v148, v148
	v_rcp_f32_e32 v149, v149
	v_rcp_f32_e32 v150, v150
	v_rcp_f32_e32 v151, v151
	v_mul_f32_e32 v72, v72, v144
	v_mul_f32_e32 v73, v73, v145
	v_mul_f32_e32 v74, v74, v146
	v_mul_f32_e32 v75, v75, v147
	v_mul_f32_e32 v76, v76, v148
	v_mul_f32_e32 v77, v77, v149
	v_mul_f32_e32 v78, v78, v150
	v_mul_f32_e32 v79, v79, v151
	v_mul_f32_e32 v72, v104, v72
	v_mul_f32_e32 v73, v105, v73
	v_mul_f32_e32 v74, v106, v74
	v_mul_f32_e32 v75, v107, v75
	v_mul_f32_e32 v76, v108, v76
	v_mul_f32_e32 v77, v109, v77
	v_mul_f32_e32 v78, v110, v78
	v_mul_f32_e32 v79, v111, v79
	v_cvt_pk_bf16_f32 v152, v72, v73
	v_cvt_pk_bf16_f32 v153, v74, v75
	v_cvt_pk_bf16_f32 v154, v76, v77
	v_cvt_pk_bf16_f32 v155, v78, v79
	s_nop 1
	global_store_dwordx4 v132, v[152:155], s[50:51]
	s_nop 1
	v_fmamk_f32 v131, v140, 0x3a000000, v130
	v_add_u32_e32 v132, 0x1b8000, v129
	v_rsq_f32_e32 v131, v131
	s_nop 0
	v_mul_f32_e32 v80, v80, v131
	v_mul_f32_e32 v81, v81, v131
	v_mul_f32_e32 v82, v82, v131
	v_mul_f32_e32 v83, v83, v131
	v_mul_f32_e32 v84, v84, v131
	v_mul_f32_e32 v85, v85, v131
	v_mul_f32_e32 v86, v86, v131
	v_mul_f32_e32 v87, v87, v131
	v_mul_f32_e32 v112, v112, v131
	v_mul_f32_e32 v113, v113, v131
	v_mul_f32_e32 v114, v114, v131
	v_mul_f32_e32 v115, v115, v131
	v_mul_f32_e32 v116, v116, v131
	v_mul_f32_e32 v117, v117, v131
	v_mul_f32_e32 v118, v118, v131
	v_mul_f32_e32 v119, v119, v131
	v_mul_f32_e32 v144, 0xbfb8aa3b, v80
	v_mul_f32_e32 v145, 0xbfb8aa3b, v81
	v_mul_f32_e32 v146, 0xbfb8aa3b, v82
	v_mul_f32_e32 v147, 0xbfb8aa3b, v83
	v_mul_f32_e32 v148, 0xbfb8aa3b, v84
; __device__ __forceinline__ unsigned cvt_pk_bf16(float lo, float hi) { unsigned r; asm volatile("v_cvt_pk_bf16_f32 %0, %1, %2" : "=v"(r) : "v"(lo), "v"(hi)); return r; }
;     __device__ __forceinline__ void operator()(const f32x4 (&acc)[2][2][4][2], const Unit& u, int wr, int wc, int fr, int fq) const {
;     ...
;         for (int ai = 0; ai < 2; ++ai)
; #pragma unroll
;             for (int m = 0; m < 4; ++m) { const int row = row0 + ai * HALF + m * 16; const float rs = __builtin_amdgcn_rsqf(rsv[ai][m] * inv_n + eps);
;                 float a[8];
; #pragma unroll
;                 for (int n = 0; n < 2; ++n)
; #pragma unroll
;                     for (int i = 0; i < 4; ++i) { const float g = acc[ai][0][m][n][i] * rs, up = acc[ai][1][m][n][i] * rs;
;                         a[n * 4 + i] = g * __builtin_amdgcn_rcpf(1.0f + __builtin_amdgcn_exp2f(-1.4426950408889634f * g)) * up; }
;                 u32x4 w; w.x = cvt_pk_bf16(a[0], a[1]); w.y = cvt_pk_bf16(a[2], a[3]); w.z = cvt_pk_bf16(a[4], a[5]); w.w = cvt_pk_bf16(a[6], a[7]);
;                 *(u32x4*)(O + (size_t)row * ldc + col0) = w; }
; template <class Epi, class Sched, bool ALIGN_EPI = false, bool SP2 = false>
; __device__ __forceinline__ void gemm_phase(PG8_LAS unsigned char* lds, const Gemm g, const Sched& S, const Epi& E) {
;     ...
;         if (!has_next) break;
; #pragma unroll
;         for (int a = 0; a < 2; ++a)
; #pragma unroll
;             for (int b = 0; b < 2; ++b)
; #pragma unroll
;                 for (int m = 0; m < 4; ++m)
; #pragma unroll
;                     for (int n = 0; n < 2; ++n) acc[a][b][m][n] = (f32x4){0.f, 0.f, 0.f, 0.f};
;         cur = nxt; cA = nA; cB = nB; ++ui;
	v_mul_f32_e32 v149, 0xbfb8aa3b, v85
	v_mul_f32_e32 v150, 0xbfb8aa3b, v86
	v_mul_f32_e32 v151, 0xbfb8aa3b, v87
	v_exp_f32_e32 v144, v144
	v_exp_f32_e32 v145, v145
	v_exp_f32_e32 v146, v146
	v_exp_f32_e32 v147, v147
	v_exp_f32_e32 v148, v148
	v_exp_f32_e32 v149, v149
	v_exp_f32_e32 v150, v150
	v_exp_f32_e32 v151, v151
	v_add_f32_e32 v144, 1.0, v144
	v_add_f32_e32 v145, 1.0, v145
	v_add_f32_e32 v146, 1.0, v146
	v_add_f32_e32 v147, 1.0, v147
	v_add_f32_e32 v148, 1.0, v148
	v_add_f32_e32 v149, 1.0, v149
	v_add_f32_e32 v150, 1.0, v150
	v_add_f32_e32 v151, 1.0, v151
	v_rcp_f32_e32 v144, v144
	v_rcp_f32_e32 v145, v145
	v_rcp_f32_e32 v146, v146
	v_rcp_f32_e32 v147, v147
	v_rcp_f32_e32 v148, v148
	v_rcp_f32_e32 v149, v149
	v_rcp_f32_e32 v150, v150
	v_rcp_f32_e32 v151, v151
	v_mul_f32_e32 v80, v80, v144
	v_mul_f32_e32 v81, v81, v145
	v_mul_f32_e32 v82, v82, v146
	v_mul_f32_e32 v83, v83, v147
	v_mul_f32_e32 v84, v84, v148
	v_mul_f32_e32 v85, v85, v149
	v_mul_f32_e32 v86, v86, v150
	v_mul_f32_e32 v87, v87, v151
	v_mul_f32_e32 v80, v112, v80
	v_mul_f32_e32 v81, v113, v81
	v_mul_f32_e32 v82, v114, v82
	v_mul_f32_e32 v83, v115, v83
	v_mul_f32_e32 v84, v116, v84
	v_mul_f32_e32 v85, v117, v85
	v_mul_f32_e32 v86, v118, v86
	v_mul_f32_e32 v87, v119, v87
	v_cvt_pk_bf16_f32 v152, v80, v81
	v_cvt_pk_bf16_f32 v153, v82, v83
	v_cvt_pk_bf16_f32 v154, v84, v85
	v_cvt_pk_bf16_f32 v155, v86, v87
	s_nop 1
	global_store_dwordx4 v132, v[152:155], s[50:51]
	s_nop 1
	v_fmamk_f32 v131, v141, 0x3a000000, v130
	v_add_u32_e32 v132, 0x1e4000, v129
	v_rsq_f32_e32 v131, v131
	s_nop 0
	v_mul_f32_e32 v88, v88, v131
	v_mul_f32_e32 v89, v89, v131
	v_mul_f32_e32 v90, v90, v131
	v_mul_f32_e32 v91, v91, v131
	v_mul_f32_e32 v92, v92, v131
	v_mul_f32_e32 v93, v93, v131
	v_mul_f32_e32 v94, v94, v131
	v_mul_f32_e32 v95, v95, v131
	v_mul_f32_e32 v120, v120, v131
	v_mul_f32_e32 v121, v121, v131
	v_mul_f32_e32 v122, v122, v131
	v_mul_f32_e32 v123, v123, v131
	v_mul_f32_e32 v124, v124, v131
	v_mul_f32_e32 v125, v125, v131
	v_mul_f32_e32 v126, v126, v131
	v_mul_f32_e32 v127, v127, v131
	v_mul_f32_e32 v144, 0xbfb8aa3b, v88
	v_mul_f32_e32 v145, 0xbfb8aa3b, v89
	v_mul_f32_e32 v146, 0xbfb8aa3b, v90
	v_mul_f32_e32 v147, 0xbfb8aa3b, v91
	v_mul_f32_e32 v148, 0xbfb8aa3b, v92
	v_mul_f32_e32 v149, 0xbfb8aa3b, v93
	v_mul_f32_e32 v150, 0xbfb8aa3b, v94
	v_mul_f32_e32 v151, 0xbfb8aa3b, v95
	v_exp_f32_e32 v144, v144
	v_exp_f32_e32 v145, v145
	v_exp_f32_e32 v146, v146
	v_exp_f32_e32 v147, v147
	v_exp_f32_e32 v148, v148
	v_exp_f32_e32 v149, v149
	v_exp_f32_e32 v150, v150
	v_exp_f32_e32 v151, v151
	v_add_f32_e32 v144, 1.0, v144
	v_add_f32_e32 v145, 1.0, v145
	v_add_f32_e32 v146, 1.0, v146
	v_add_f32_e32 v147, 1.0, v147
	v_add_f32_e32 v148, 1.0, v148
	v_add_f32_e32 v149, 1.0, v149
	v_add_f32_e32 v150, 1.0, v150
	v_add_f32_e32 v151, 1.0, v151
	v_rcp_f32_e32 v144, v144
	v_rcp_f32_e32 v145, v145
	v_rcp_f32_e32 v146, v146
	v_rcp_f32_e32 v147, v147
	v_rcp_f32_e32 v148, v148
	v_rcp_f32_e32 v149, v149
	v_rcp_f32_e32 v150, v150
	v_rcp_f32_e32 v151, v151
	v_mul_f32_e32 v88, v88, v144
	v_mul_f32_e32 v89, v89, v145
	v_mul_f32_e32 v90, v90, v146
	v_mul_f32_e32 v91, v91, v147
	v_mul_f32_e32 v92, v92, v148
	v_mul_f32_e32 v93, v93, v149
	v_mul_f32_e32 v94, v94, v150
	v_mul_f32_e32 v95, v95, v151
	v_mul_f32_e32 v88, v120, v88
	v_mul_f32_e32 v89, v121, v89
	v_mul_f32_e32 v90, v122, v90
	v_mul_f32_e32 v91, v123, v91
	v_mul_f32_e32 v92, v124, v92
	v_mul_f32_e32 v93, v125, v93
	v_mul_f32_e32 v94, v126, v94
	v_mul_f32_e32 v95, v127, v95
	v_cvt_pk_bf16_f32 v152, v88, v89
	v_cvt_pk_bf16_f32 v153, v90, v91
	v_cvt_pk_bf16_f32 v154, v92, v93
	v_cvt_pk_bf16_f32 v155, v94, v95
	s_nop 1
	global_store_dwordx4 v132, v[152:155], s[50:51]
	s_nop 1
	s_cmp_eq_u32 s19, 0
	s_cbranch_scc1 .Lp5_done
	s_mov_b32 s17, s20
	s_mov_b32 s18, s21
	s_mov_b64 s[22:23], s[26:27]
	s_mov_b64 s[24:25], s[28:29]
	s_add_u32 s16, s16, 1
	s_branch .Lp5_unit

; template <class Epi, class Sched, bool ALIGN_EPI = false, bool SP2 = false>
; __device__ __forceinline__ void gemm_phase(PG8_LAS unsigned char* lds, const Gemm g, const Sched& S, const Epi& E) {
;     ...
;     const int tid = tid_, wid = __builtin_amdgcn_readfirstlane(tid >> 6), lane = tid & 63, wr = wid >> 2, wc = wid & 3, fr = lane & 15, fq = lane >> 4;
;     const int K = g.K, nt = K / BK;
;     unsigned voffA[2], voffB[2];
; #pragma unroll
;     for (int i = 0; i < 2; ++i) { int R, C; stage_rc(tid * 16 + i * 8192, R, C); const int Rb = Epi::PERM ? ((R & ~31) + perm32(R & 31)) : R;
;         voffA[i] = (unsigned)(R * K + C) * 2u; voffB[i] = (unsigned)(Rb * K + C) * 2u; }
;     const size_t kstep = (size_t)(BK * 2);
;     const size_t hstep = (size_t)HALF * K * 2;
;     const size_t tstep = 2 * hstep;
;     const unsigned ldsw = (unsigned)wid * 1024u;
;     const int aoff = lds_byte(wr * 64 + fr, fq * 8), boff = lds_byte(wc * 32 + fr, fq * 8);
;     ...
;     Unit cur, nxt; int ui = 0;
;     if (!S.next(0, cur)) return;
;     f32x4 acc[2][2][4][2];
; #pragma unroll
;     for (int a = 0; a < 2; ++a)
; #pragma unroll
;         for (int b = 0; b < 2; ++b)
; #pragma unroll
;             for (int m = 0; m < 4; ++m)
; #pragma unroll
;                 for (int n = 0; n < 2; ++n) acc[a][b][m][n] = (f32x4){0.f, 0.f, 0.f, 0.f};
;     bf16x8 At[4][2], B0[2][2], B1[2][2];
;     const char* cA = (const char*)g.A + (size_t)cur.pm * tstep; const char* cB = (const char*)g.Bt + (size_t)cur.pn * tstep;
;     S.a_ready(cur);
;     if constexpr (SP2) {
;         PG8_STAGE(PG8_SB(0, 0), cB, voffB); PG8_STAGE(PG8_SB(0, 1), cB + hstep, voffB); PG8_STAGE(PG8_SA(0, 0), cA, voffA); PG8_STAGE(PG8_SA(0, 1), cA + hstep, voffA);
;         if (wr == 1) PG8_BAR;
;         PG8_WAIT_V(2); PG8_BAR;
;         PG8_STAGE(PG8_SB(1, 0), cB + kstep, voffB); PG8_STAGE(PG8_SA(1, 0), cA + kstep, voffA); PG8_STAGE(PG8_SB(1, 1), cB + hstep + kstep, voffB);
;         PG8_WAIT_V(6); PG8_BAR;
;     } else {
;         PG8_STAGE(PG8_SB(0, 0), cB, voffB); PG8_STAGE(PG8_SA(0, 0), cA, voffA); PG8_STAGE(PG8_SB(0, 1), cB + hstep, voffB); PG8_STAGE(PG8_SA(0, 1), cA + hstep, voffA);
;         if (wr == 1) PG8_BAR;
;         PG8_WAIT_V(4); PG8_BAR;
;         PG8_STAGE(PG8_SB(1, 0), cB + kstep, voffB); PG8_STAGE(PG8_SA(1, 0), cA + kstep, voffA); PG8_STAGE(PG8_SB(1, 1), cB + hstep + kstep, voffB);
;         PG8_WAIT_V(6); PG8_BAR;
.LBB0_840:
	s_cmp_lt_i32 s70, 7
	s_cselect_b64 s[4:5], -1, 0
	s_and_b64 s[8:9], s[4:5], s[0:1]
	s_andn2_b64 vcc, exec, s[8:9]
	s_cbranch_vccnz .LBB0_887
	v_readlane_b32 s100, v244, 4
	s_nop 3
	s_cmp_lg_u32 s100, 0x100
	s_cbranch_scc1 .Lp6_base
	v_writelane_b32 v253, s4, 0
	v_writelane_b32 v253, s5, 1
	v_writelane_b32 v253, s6, 2
	v_writelane_b32 v253, s7, 3
	v_writelane_b32 v253, s8, 4
	v_writelane_b32 v253, s9, 5
	v_writelane_b32 v253, s10, 6
	v_writelane_b32 v253, s11, 7
	v_writelane_b32 v253, s12, 8
	v_writelane_b32 v253, s13, 9
	v_writelane_b32 v253, s14, 10
	v_writelane_b32 v253, s15, 11
	v_writelane_b32 v253, s16, 12
	v_writelane_b32 v253, s17, 13
	v_writelane_b32 v253, s18, 14
	v_writelane_b32 v253, s19, 15
	v_writelane_b32 v253, s20, 16
	v_writelane_b32 v253, s21, 17
	v_writelane_b32 v253, s22, 18
	v_writelane_b32 v253, s23, 19
	v_writelane_b32 v253, s24, 20
	v_writelane_b32 v253, s25, 21
	v_writelane_b32 v253, s26, 22
	v_writelane_b32 v253, s27, 23
	v_writelane_b32 v253, s28, 24
	v_writelane_b32 v253, s29, 25
	v_writelane_b32 v253, s30, 26
	v_writelane_b32 v253, s31, 27
	v_writelane_b32 v253, s32, 28
	v_writelane_b32 v253, s33, 29
	v_writelane_b32 v253, s34, 30
	v_writelane_b32 v253, s35, 31
	v_writelane_b32 v253, s36, 32
	v_writelane_b32 v253, s37, 33
	v_writelane_b32 v253, s38, 34
	v_writelane_b32 v253, s39, 35
	v_writelane_b32 v253, s40, 36
	v_writelane_b32 v253, s41, 37
	v_writelane_b32 v253, s42, 38
	v_writelane_b32 v253, s43, 39
	v_writelane_b32 v253, s44, 40
	v_writelane_b32 v253, s45, 41
	v_writelane_b32 v253, s46, 42
	v_writelane_b32 v253, s47, 43
	v_writelane_b32 v253, s48, 44
	v_writelane_b32 v253, s49, 45
	v_writelane_b32 v253, s50, 46
	v_writelane_b32 v253, s51, 47
	v_writelane_b32 v253, s52, 48
	v_writelane_b32 v253, s53, 49
	v_writelane_b32 v253, s54, 50
	v_writelane_b32 v253, s55, 51
	v_writelane_b32 v253, s56, 52
	v_writelane_b32 v253, s57, 53
	v_writelane_b32 v253, s58, 54
	v_writelane_b32 v253, s59, 55
	s_mov_b32 s40, vcc_lo
	s_mov_b32 s41, vcc_hi
	v_writelane_b32 v253, s40, 60
	v_writelane_b32 v253, s41, 61
	v_lshrrev_b32_e32 v254, 6, v185
	v_readlane_b32 s14, v244, 4
	v_readfirstlane_b32 s36, v254
	s_nop 3
	s_lshr_b32 s37, s36, 2
	s_and_b32 s38, s36, 3
	s_lshl_b32 s35, s36, 10
	s_add_u32 s10, s76, 0xa800000
	s_addc_u32 s11, s77, 0
	s_add_u32 s12, s76, 0x5100000
	s_addc_u32 s13, s77, 0
	s_mov_b32 s16, 0
	s_mul_i32 s40, s16, s14
	s_add_u32 s40, s40, s2
	s_cmp_lt_u32 s40, 512
	s_cselect_b32 s44, 1, 0
	s_min_u32 s40, s40, 511
	s_and_b32 s41, s40, 7
	s_lshr_b32 s42, s40, 3
	s_mul_i32 s41, s41, 64
	s_add_u32 s41, s41, s42
	s_lshr_b32 s42, s41, 5
	s_and_b32 s43, s41, 31
	s_and_b32 s40, s43, 3
	s_lshl_b32 s42, s42, 2
	s_add_u32 s17, s42, s40
	s_lshr_b32 s18, s43, 2
	s_cmp_eq_u32 s44, 0
	s_cbranch_scc1 .Lp6_exit
	v_and_b32_e32 v254, 63, v185
	v_and_b32_e32 v255, 15, v254
	v_lshrrev_b32_e32 v226, 1, v255
	v_lshrrev_b32_e32 v227, 4, v254
	v_xor_b32_e32 v226, v226, v227
	v_lshlrev_b32_e32 v255, 7, v255
	v_lshl_or_b32 v255, v226, 4, v255
	s_lshl_b32 s40, s37, 13
	s_lshl_b32 s41, s38, 12
	s_add_u32 s41, s41, 0x10000
	v_add_u32_e32 v245, s40, v255
	v_add_u32_e32 v247, s41, v255
	v_xor_b32_e32 v246, 64, v245
	v_xor_b32_e32 v248, 64, v247
	v_lshrrev_b32_e32 v255, 3, v254
	v_and_b32_e32 v226, 7, v254
	s_and_b32 s40, s36, 1
	s_lshl_b32 s40, s40, 2
	v_lshrrev_b32_e32 v227, 1, v255
	v_add_u32_e32 v227, s40, v227
	v_xor_b32_e32 v226, v226, v227
	v_lshlrev_b32_e32 v226, 4, v226
	s_lshl_b32 s40, s36, 3
	v_add_u32_e32 v227, s40, v255
	v_mul_u32_u24_e32 v227, 0x2c00, v227
	v_add_u32_e32 v249, v227, v226
	v_add_u32_e32 v250, 0xb0000, v249
	s_and_b32 s40, s36, 3
	s_lshl_b32 s40, s40, 3
	v_add_u32_e32 v227, s40, v255
	v_lshrrev_b32_e32 v254, 4, v227
	v_lshlrev_b32_e32 v254, 2, v254
	v_and_b32_e32 v255, 3, v227
	v_add_u32_e32 v254, v254, v255
	v_and_b32_e32 v227, 12, v227
	v_lshl_add_u32 v254, v227, 1, v254
	s_lshr_b32 s40, s36, 2
	s_lshl_b32 s40, s40, 5
	v_add_u32_e32 v254, s40, v254
	v_mul_u32_u24_e32 v254, 0x2c00, v254
	v_add_u32_e32 v251, v254, v226
	v_add_u32_e32 v252, 0xb0000, v251
	s_mul_i32 s40, s17, 0x2c0000
	s_add_u32 s22, s10, s40
	s_addc_u32 s23, s11, 0
	s_mul_i32 s40, s18, 0x2c0000
	s_add_u32 s24, s12, s40
	s_addc_u32 s25, s13, 0
	s_add_u32 s30, s22, 0
	s_addc_u32 s31, s23, 0
	s_add_u32 s32, s24, 0
	s_addc_u32 s33, s25, 0
	s_add_u32 s56, s30, 0x160000
	s_addc_u32 s57, s31, 0
	s_add_u32 s58, s32, 0x160000
	s_addc_u32 s59, s33, 0
	s_add_i32 m0, s35, 0x0
	s_nop 0
	global_load_lds_dwordx4 v249, s[30:31]
	s_add_i32 m0, s35, 0x2000
	s_nop 0
	global_load_lds_dwordx4 v250, s[30:31]
	s_add_i32 m0, s35, 0x10000
	s_nop 0
	global_load_lds_dwordx4 v251, s[32:33]
	s_add_i32 m0, s35, 0x12000
	s_nop 0
	global_load_lds_dwordx4 v252, s[32:33]
	s_add_i32 m0, s35, 0x4000
	s_nop 0
	global_load_lds_dwordx4 v249, s[56:57]
	s_add_i32 m0, s35, 0x6000
	s_nop 0
	global_load_lds_dwordx4 v250, s[56:57]
	s_add_i32 m0, s35, 0x14000
	s_nop 0
	global_load_lds_dwordx4 v251, s[58:59]
	s_add_i32 m0, s35, 0x16000
	s_nop 0
	global_load_lds_dwordx4 v252, s[58:59]
	s_add_u32 s30, s30, 128
	s_addc_u32 s31, s31, 0
	s_add_u32 s56, s56, 128
	s_addc_u32 s57, s57, 0
	s_add_u32 s32, s32, 128
	s_addc_u32 s33, s33, 0
	s_add_u32 s58, s58, 128
	s_addc_u32 s59, s59, 0
	s_add_i32 m0, s35, 0x8000
	s_nop 0
	global_load_lds_dwordx4 v249, s[30:31]
	s_add_i32 m0, s35, 0xa000
	s_nop 0
	global_load_lds_dwordx4 v250, s[30:31]
	s_add_i32 m0, s35, 0x1c000
	s_nop 0
	global_load_lds_dwordx4 v251, s[58:59]
	s_add_i32 m0, s35, 0x1e000
	s_nop 0
	global_load_lds_dwordx4 v252, s[58:59]
	s_add_i32 m0, s35, 0xc000
	s_nop 0
	global_load_lds_dwordx4 v249, s[56:57]
	s_add_i32 m0, s35, 0xe000
	s_nop 0
	global_load_lds_dwordx4 v250, s[56:57]
	s_add_i32 m0, s35, 0x18000
	s_nop 0
	global_load_lds_dwordx4 v251, s[32:33]
	s_add_i32 m0, s35, 0x1a000
	s_nop 0
	global_load_lds_dwordx4 v252, s[32:33]
	s_add_u32 s30, s30, 128
	s_addc_u32 s31, s31, 0
	s_add_u32 s56, s56, 128
	s_addc_u32 s57, s57, 0
	s_add_u32 s32, s32, 128
	s_addc_u32 s33, s33, 0
	s_add_u32 s58, s58, 128
	s_addc_u32 s59, s59, 0
	s_waitcnt vmcnt(12)
	s_barrier
; #define PG8_STAGE(bufoff, gbase, voff) do { _Pragma("unroll") for (int _i = 0; _i < 2; ++_i) \
;         __builtin_amdgcn_global_load_lds((const unsigned*)((const char*)(gbase) + (voff)[_i]), (PG8_LAS unsigned*)(lds + (bufoff) + ldsw + _i * 8192), 16, 0, 0); } while (0)
; #define PG8_LDA(dst, b, h) do { _Pragma("unroll") for (int m = 0; m < 4; ++m) _Pragma("unroll") for (int k = 0; k < 2; ++k) dst[m][k] = *(const PG8_LAS bf16x8*)(lds + PG8_SA(b, h) + aoff + m * 2048 + k * 1024); } while (0)
; #define PG8_LDB(dst, b, h) do { _Pragma("unroll") for (int n = 0; n < 2; ++n) _Pragma("unroll") for (int k = 0; k < 2; ++k) dst[n][k] = *(const PG8_LAS bf16x8*)(lds + PG8_SB(b, h) + boff + n * 2048 + k * 1024); } while (0)
; #define PG8_SCHED __builtin_amdgcn_sched_barrier(0)
; template <class Epi, class Sched, bool ALIGN_EPI = false, bool SP2 = false>
; __device__ __forceinline__ void gemm_phase(PG8_LAS unsigned char* lds, const Gemm g, const Sched& S, const Epi& E) {
;     ...
;         const bool has_next = S.next(ui + 1, nxt);
;         const char* nA = has_next ? (const char*)g.A + (size_t)nxt.pm * tstep : cA; const char* nB = has_next ? (const char*)g.Bt + (size_t)nxt.pn * tstep : cB;
;         for (int t = 0; t < nt; t += 2) {
;             const bool last = (t == nt - 2);
;             const char* a1 = cA + (size_t)(t + 1) * kstep;
;             const char* a2 = last ? nA : cA + (size_t)(t + 2) * kstep; const char* b2 = last ? nB : cB + (size_t)(t + 2) * kstep;
;             const char* a3 = a2 + kstep; const char* b3 = b2 + kstep;
;             if (last && has_next) S.a_ready(nxt);
;             if constexpr (SP2) {
;             PG8_LDB(B0, 0, 0); PG8_LDB(B1, 0, 1); PG8_SCHED; PG8_LDA(At, 0, 0); PG8_STAGE(PG8_SA(1, 1), a1 + hstep, voffA);
;     ...
; #pragma unroll
;         for (int a = 0; a < 2; ++a)
; #pragma unroll
;             for (int b = 0; b < 2; ++b)
; #pragma unroll
;                 for (int m = 0; m < 4; ++m)
; #pragma unroll
;                     for (int n = 0; n < 2; ++n) acc[a][b][m][n] = (f32x4){0.f, 0.f, 0.f, 0.f};
;         cur = nxt; cA = nA; cB = nB; ++ui;
.Lp6_unit:
	s_add_u32 s45, s16, 1
	s_mul_i32 s40, s45, s14
	s_add_u32 s40, s40, s2
	s_cmp_lt_u32 s40, 512
	s_cselect_b32 s19, 1, 0
	s_min_u32 s40, s40, 511
	s_and_b32 s41, s40, 7
	s_lshr_b32 s42, s40, 3
	s_mul_i32 s41, s41, 64
	s_add_u32 s41, s41, s42
	s_lshr_b32 s42, s41, 5
	s_and_b32 s43, s41, 31
	s_and_b32 s40, s43, 3
	s_lshl_b32 s42, s42, 2
	s_add_u32 s20, s42, s40
	s_lshr_b32 s21, s43, 2
	s_mul_i32 s40, s20, 0x2c0000
	s_add_u32 s26, s10, s40
	s_addc_u32 s27, s11, 0
	s_mul_i32 s40, s21, 0x2c0000
	s_add_u32 s28, s12, s40
	s_addc_u32 s29, s13, 0
	s_cmp_eq_u32 s19, 0
	s_cselect_b32 s26, s22, s26
	s_cselect_b32 s27, s23, s27
	s_cselect_b32 s28, s24, s28
	s_cselect_b32 s29, s25, s29
	s_add_u32 s30, s22, 256
	s_addc_u32 s31, s23, 0
	s_add_u32 s32, s24, 256
	s_addc_u32 s33, s25, 0
	s_add_u32 s56, s30, 0x160000
	s_addc_u32 s57, s31, 0
	s_add_u32 s58, s32, 0x160000
	s_addc_u32 s59, s33, 0
	s_movk_i32 s34, 44
	v_mov_b32_e32 v0, 0
	v_mov_b32_e32 v1, 0
	v_mov_b32_e32 v2, 0
	v_mov_b32_e32 v3, 0
	v_mov_b32_e32 v4, 0
	v_mov_b32_e32 v5, 0
	v_mov_b32_e32 v6, 0
	v_mov_b32_e32 v7, 0
	v_mov_b32_e32 v8, 0
	v_mov_b32_e32 v9, 0
	v_mov_b32_e32 v10, 0
	v_mov_b32_e32 v11, 0
	v_mov_b32_e32 v12, 0
	v_mov_b32_e32 v13, 0
	v_mov_b32_e32 v14, 0
	v_mov_b32_e32 v15, 0
	v_mov_b32_e32 v16, 0
	v_mov_b32_e32 v17, 0
	v_mov_b32_e32 v18, 0
	v_mov_b32_e32 v19, 0
	v_mov_b32_e32 v20, 0
	v_mov_b32_e32 v21, 0
	v_mov_b32_e32 v22, 0
	v_mov_b32_e32 v23, 0
	v_mov_b32_e32 v24, 0
	v_mov_b32_e32 v25, 0
	v_mov_b32_e32 v26, 0
	v_mov_b32_e32 v27, 0
	v_mov_b32_e32 v28, 0
	v_mov_b32_e32 v29, 0
	v_mov_b32_e32 v30, 0
	v_mov_b32_e32 v31, 0
	v_mov_b32_e32 v32, 0
	v_mov_b32_e32 v33, 0
	v_mov_b32_e32 v34, 0
	v_mov_b32_e32 v35, 0
	v_mov_b32_e32 v36, 0
	v_mov_b32_e32 v37, 0
	v_mov_b32_e32 v38, 0
	v_mov_b32_e32 v39, 0
	v_mov_b32_e32 v40, 0
	v_mov_b32_e32 v41, 0
	v_mov_b32_e32 v42, 0
	v_mov_b32_e32 v43, 0
	v_mov_b32_e32 v44, 0
	v_mov_b32_e32 v45, 0
	v_mov_b32_e32 v46, 0
	v_mov_b32_e32 v47, 0
	v_mov_b32_e32 v48, 0
	v_mov_b32_e32 v49, 0
	v_mov_b32_e32 v50, 0
	v_mov_b32_e32 v51, 0
	v_mov_b32_e32 v52, 0
	v_mov_b32_e32 v53, 0
	v_mov_b32_e32 v54, 0
	v_mov_b32_e32 v55, 0
	v_mov_b32_e32 v56, 0
	v_mov_b32_e32 v57, 0
	v_mov_b32_e32 v58, 0
	v_mov_b32_e32 v59, 0
	v_mov_b32_e32 v60, 0
	v_mov_b32_e32 v61, 0
	v_mov_b32_e32 v62, 0
	v_mov_b32_e32 v63, 0
	v_mov_b32_e32 v64, 0
	v_mov_b32_e32 v65, 0
	v_mov_b32_e32 v66, 0
	v_mov_b32_e32 v67, 0
	v_mov_b32_e32 v68, 0
	v_mov_b32_e32 v69, 0
	v_mov_b32_e32 v70, 0
	v_mov_b32_e32 v71, 0
	v_mov_b32_e32 v72, 0
	v_mov_b32_e32 v73, 0
	v_mov_b32_e32 v74, 0
	v_mov_b32_e32 v75, 0
	v_mov_b32_e32 v76, 0
	v_mov_b32_e32 v77, 0
	v_mov_b32_e32 v78, 0
	v_mov_b32_e32 v79, 0
	v_mov_b32_e32 v80, 0
	v_mov_b32_e32 v81, 0
	v_mov_b32_e32 v82, 0
	v_mov_b32_e32 v83, 0
	v_mov_b32_e32 v84, 0
	v_mov_b32_e32 v85, 0
	v_mov_b32_e32 v86, 0
	v_mov_b32_e32 v87, 0
	v_mov_b32_e32 v88, 0
	v_mov_b32_e32 v89, 0
	v_mov_b32_e32 v90, 0
	v_mov_b32_e32 v91, 0
	v_mov_b32_e32 v92, 0
	v_mov_b32_e32 v93, 0
	v_mov_b32_e32 v94, 0
	v_mov_b32_e32 v95, 0
	v_mov_b32_e32 v96, 0
	v_mov_b32_e32 v97, 0
	v_mov_b32_e32 v98, 0
	v_mov_b32_e32 v99, 0
	v_mov_b32_e32 v100, 0
	v_mov_b32_e32 v101, 0
	v_mov_b32_e32 v102, 0
	v_mov_b32_e32 v103, 0
	v_mov_b32_e32 v104, 0
	v_mov_b32_e32 v105, 0
	v_mov_b32_e32 v106, 0
	v_mov_b32_e32 v107, 0
	v_mov_b32_e32 v108, 0
	v_mov_b32_e32 v109, 0
	v_mov_b32_e32 v110, 0
	v_mov_b32_e32 v111, 0
	v_mov_b32_e32 v112, 0
	v_mov_b32_e32 v113, 0
	v_mov_b32_e32 v114, 0
	v_mov_b32_e32 v115, 0
	v_mov_b32_e32 v116, 0
	v_mov_b32_e32 v117, 0
	v_mov_b32_e32 v118, 0
	v_mov_b32_e32 v119, 0
	v_mov_b32_e32 v120, 0
	v_mov_b32_e32 v121, 0
	v_mov_b32_e32 v122, 0
	v_mov_b32_e32 v123, 0
	v_mov_b32_e32 v124, 0
	v_mov_b32_e32 v125, 0
	v_mov_b32_e32 v126, 0
	v_mov_b32_e32 v127, 0
	ds_read_b128 v[194:197], v247 offset:0
	ds_read_b128 v[198:201], v248 offset:0
	ds_read_b128 v[202:205], v247 offset:2048
	ds_read_b128 v[206:209], v248 offset:2048
	ds_read_b128 v[128:131], v245 offset:0
	ds_read_b128 v[132:135], v246 offset:0
	ds_read_b128 v[136:139], v245 offset:2048
	ds_read_b128 v[140:143], v246 offset:2048
	ds_read_b128 v[144:147], v245 offset:4096
	ds_read_b128 v[148:151], v246 offset:4096
	ds_read_b128 v[152:155], v245 offset:6144
	ds_read_b128 v[156:159], v246 offset:6144
	s_cmp_ge_u32 s36, 4
	s_cbranch_scc1 .Lp6_kloop1
; #define PG8_STAGE(bufoff, gbase, voff) do { _Pragma("unroll") for (int _i = 0; _i < 2; ++_i) \
;         __builtin_amdgcn_global_load_lds((const unsigned*)((const char*)(gbase) + (voff)[_i]), (PG8_LAS unsigned*)(lds + (bufoff) + ldsw + _i * 8192), 16, 0, 0); } while (0)
; #define PG8_LDA(dst, b, h) do { _Pragma("unroll") for (int m = 0; m < 4; ++m) _Pragma("unroll") for (int k = 0; k < 2; ++k) dst[m][k] = *(const PG8_LAS bf16x8*)(lds + PG8_SA(b, h) + aoff + m * 2048 + k * 1024); } while (0)
; #define PG8_LDB(dst, b, h) do { _Pragma("unroll") for (int n = 0; n < 2; ++n) _Pragma("unroll") for (int k = 0; k < 2; ++k) dst[n][k] = *(const PG8_LAS bf16x8*)(lds + PG8_SB(b, h) + boff + n * 2048 + k * 1024); } while (0)
; template <class Epi, class Sched, bool ALIGN_EPI = false, bool SP2 = false>
; __device__ __forceinline__ void gemm_phase(PG8_LAS unsigned char* lds, const Gemm g, const Sched& S, const Epi& E) {
;     ...
;         for (int t = 0; t < nt; t += 2) {
;             const bool last = (t == nt - 2);
;             const char* a1 = cA + (size_t)(t + 1) * kstep;
;             const char* a2 = last ? nA : cA + (size_t)(t + 2) * kstep; const char* b2 = last ? nB : cB + (size_t)(t + 2) * kstep;
;             const char* a3 = a2 + kstep; const char* b3 = b2 + kstep;
;             if (last && has_next) S.a_ready(nxt);
;             if constexpr (SP2) {
;             PG8_LDB(B0, 0, 0); PG8_LDB(B1, 0, 1); PG8_SCHED; PG8_LDA(At, 0, 0); PG8_STAGE(PG8_SA(1, 1), a1 + hstep, voffA);
;             PG8_WAIT_V(8); PG8_WAIT_L(0); PG8_BAR; PG8_MMA(0, 0, At, B0); PG8_MMA(0, 1, At, B1); PG8_BAR; PG8_SCHED;
;             PG8_LDA(At, 0, 1); PG8_STAGE(PG8_SB(0, 0), b2, voffB); PG8_STAGE(PG8_SB(0, 1), b2 + hstep, voffB); PG8_STAGE(PG8_SA(0, 0), a2, voffA);
;             PG8_WAIT_V(8); PG8_WAIT_L(0); PG8_BAR; PG8_MMA(1, 0, At, B0); PG8_MMA(1, 1, At, B1); PG8_BAR; PG8_SCHED;
;             PG8_LDB(B0, 1, 0); PG8_LDB(B1, 1, 1); PG8_SCHED; PG8_LDA(At, 1, 0); PG8_STAGE(PG8_SA(0, 1), a2 + hstep, voffA);
;             PG8_WAIT_V(8); PG8_WAIT_L(0); PG8_BAR; PG8_MMA(0, 0, At, B0); PG8_MMA(0, 1, At, B1); PG8_BAR; PG8_SCHED;
;             PG8_LDA(At, 1, 1); PG8_STAGE(PG8_SB(1, 0), b3, voffB); PG8_STAGE(PG8_SB(1, 1), b3 + hstep, voffB); PG8_STAGE(PG8_SA(1, 0), a3, voffA);
;             PG8_WAIT_V(8); PG8_WAIT_L(0); PG8_BAR; PG8_MMA(1, 0, At, B0); PG8_MMA(1, 1, At, B1); PG8_BAR; PG8_SCHED;
.Lp6_kloop0:
	s_waitcnt vmcnt(8)
	s_waitcnt lgkmcnt(0)
	s_barrier
	v_mfma_f32_16x16x32_bf16 v[0:3], v[194:197], v[128:131], v[0:3]
	ds_read_b128 v[210:213], v247 offset:16384
	v_mfma_f32_16x16x32_bf16 v[4:7], v[202:205], v[128:131], v[4:7]
	ds_read_b128 v[214:217], v248 offset:16384
	v_mfma_f32_16x16x32_bf16 v[8:11], v[194:197], v[136:139], v[8:11]
	ds_read_b128 v[218:221], v247 offset:18432
	v_mfma_f32_16x16x32_bf16 v[12:15], v[202:205], v[136:139], v[12:15]
	ds_read_b128 v[222:225], v248 offset:18432
	v_mfma_f32_16x16x32_bf16 v[16:19], v[194:197], v[144:147], v[16:19]
	s_add_i32 m0, s35, 0x0
	v_mfma_f32_16x16x32_bf16 v[20:23], v[202:205], v[144:147], v[20:23]
	global_load_lds_dwordx4 v249, s[30:31]
	v_mfma_f32_16x16x32_bf16 v[24:27], v[194:197], v[152:155], v[24:27]
	s_add_i32 m0, s35, 0x2000
	v_mfma_f32_16x16x32_bf16 v[28:31], v[202:205], v[152:155], v[28:31]
	global_load_lds_dwordx4 v250, s[30:31]
	v_mfma_f32_16x16x32_bf16 v[0:3], v[198:201], v[132:135], v[0:3]
	s_add_i32 m0, s35, 0x10000
	v_mfma_f32_16x16x32_bf16 v[4:7], v[206:209], v[132:135], v[4:7]
	global_load_lds_dwordx4 v251, s[32:33]
	v_mfma_f32_16x16x32_bf16 v[8:11], v[198:201], v[140:143], v[8:11]
	s_add_i32 m0, s35, 0x12000
	v_mfma_f32_16x16x32_bf16 v[12:15], v[206:209], v[140:143], v[12:15]
	global_load_lds_dwordx4 v252, s[32:33]
	v_mfma_f32_16x16x32_bf16 v[16:19], v[198:201], v[148:151], v[16:19]
	ds_read_b128 v[160:163], v245 offset:16384
	v_mfma_f32_16x16x32_bf16 v[20:23], v[206:209], v[148:151], v[20:23]
	ds_read_b128 v[164:167], v246 offset:16384
	v_mfma_f32_16x16x32_bf16 v[24:27], v[198:201], v[156:159], v[24:27]
	ds_read_b128 v[168:171], v245 offset:18432
	v_mfma_f32_16x16x32_bf16 v[28:31], v[206:209], v[156:159], v[28:31]
	ds_read_b128 v[172:175], v246 offset:18432
	s_waitcnt lgkmcnt(4)
	v_mfma_f32_16x16x32_bf16 v[32:35], v[210:213], v[128:131], v[32:35]
	ds_read_b128 v[176:179], v245 offset:20480
	v_mfma_f32_16x16x32_bf16 v[36:39], v[218:221], v[128:131], v[36:39]
	ds_read_b128 v[180:183], v246 offset:20480
	v_mfma_f32_16x16x32_bf16 v[40:43], v[210:213], v[136:139], v[40:43]
	ds_read_b128 v[186:189], v245 offset:22528
	v_mfma_f32_16x16x32_bf16 v[44:47], v[218:221], v[136:139], v[44:47]
	ds_read_b128 v[190:193], v246 offset:22528
	v_mfma_f32_16x16x32_bf16 v[48:51], v[210:213], v[144:147], v[48:51]
	v_mfma_f32_16x16x32_bf16 v[52:55], v[218:221], v[144:147], v[52:55]
	v_mfma_f32_16x16x32_bf16 v[56:59], v[210:213], v[152:155], v[56:59]
	v_mfma_f32_16x16x32_bf16 v[60:63], v[218:221], v[152:155], v[60:63]
	v_mfma_f32_16x16x32_bf16 v[32:35], v[214:217], v[132:135], v[32:35]
	v_mfma_f32_16x16x32_bf16 v[36:39], v[222:225], v[132:135], v[36:39]
	v_mfma_f32_16x16x32_bf16 v[40:43], v[214:217], v[140:143], v[40:43]
	v_mfma_f32_16x16x32_bf16 v[44:47], v[222:225], v[140:143], v[44:47]
	v_mfma_f32_16x16x32_bf16 v[48:51], v[214:217], v[148:151], v[48:51]
	v_mfma_f32_16x16x32_bf16 v[52:55], v[222:225], v[148:151], v[52:55]
	v_mfma_f32_16x16x32_bf16 v[56:59], v[214:217], v[156:159], v[56:59]
	v_mfma_f32_16x16x32_bf16 v[60:63], v[222:225], v[156:159], v[60:63]
	s_waitcnt vmcnt(8)
	s_waitcnt lgkmcnt(0)
	s_barrier
	v_mfma_f32_16x16x32_bf16 v[96:99], v[210:213], v[160:163], v[96:99]
	s_add_i32 m0, s35, 0x4000
	v_mfma_f32_16x16x32_bf16 v[100:103], v[218:221], v[160:163], v[100:103]
	global_load_lds_dwordx4 v249, s[56:57]
	v_mfma_f32_16x16x32_bf16 v[104:107], v[210:213], v[168:171], v[104:107]
	s_add_i32 m0, s35, 0x6000
	v_mfma_f32_16x16x32_bf16 v[108:111], v[218:221], v[168:171], v[108:111]
	global_load_lds_dwordx4 v250, s[56:57]
	v_mfma_f32_16x16x32_bf16 v[112:115], v[210:213], v[176:179], v[112:115]
	s_add_i32 m0, s35, 0x14000
	v_mfma_f32_16x16x32_bf16 v[116:119], v[218:221], v[176:179], v[116:119]
	global_load_lds_dwordx4 v251, s[58:59]
	v_mfma_f32_16x16x32_bf16 v[120:123], v[210:213], v[186:189], v[120:123]
	s_add_i32 m0, s35, 0x16000
	v_mfma_f32_16x16x32_bf16 v[124:127], v[218:221], v[186:189], v[124:127]
	global_load_lds_dwordx4 v252, s[58:59]
	v_mfma_f32_16x16x32_bf16 v[96:99], v[214:217], v[164:167], v[96:99]
	ds_read_b128 v[128:131], v245 offset:32768
	v_mfma_f32_16x16x32_bf16 v[100:103], v[222:225], v[164:167], v[100:103]
	ds_read_b128 v[132:135], v246 offset:32768
	v_mfma_f32_16x16x32_bf16 v[104:107], v[214:217], v[172:175], v[104:107]
	ds_read_b128 v[136:139], v245 offset:34816
	v_mfma_f32_16x16x32_bf16 v[108:111], v[222:225], v[172:175], v[108:111]
	ds_read_b128 v[140:143], v246 offset:34816
	v_mfma_f32_16x16x32_bf16 v[112:115], v[214:217], v[180:183], v[112:115]
	ds_read_b128 v[144:147], v245 offset:36864
	v_mfma_f32_16x16x32_bf16 v[116:119], v[222:225], v[180:183], v[116:119]
	ds_read_b128 v[148:151], v246 offset:36864
	v_mfma_f32_16x16x32_bf16 v[120:123], v[214:217], v[190:193], v[120:123]
	ds_read_b128 v[152:155], v245 offset:38912
	v_mfma_f32_16x16x32_bf16 v[124:127], v[222:225], v[190:193], v[124:127]
	ds_read_b128 v[156:159], v246 offset:38912
	v_mfma_f32_16x16x32_bf16 v[64:67], v[194:197], v[160:163], v[64:67]
	ds_read_b128 v[210:213], v247 offset:49152
	v_mfma_f32_16x16x32_bf16 v[68:71], v[202:205], v[160:163], v[68:71]
	ds_read_b128 v[214:217], v248 offset:49152
	v_mfma_f32_16x16x32_bf16 v[72:75], v[194:197], v[168:171], v[72:75]
	ds_read_b128 v[218:221], v247 offset:51200
	v_mfma_f32_16x16x32_bf16 v[76:79], v[202:205], v[168:171], v[76:79]
	ds_read_b128 v[222:225], v248 offset:51200
	v_mfma_f32_16x16x32_bf16 v[80:83], v[194:197], v[176:179], v[80:83]
	s_add_u32 s30, s30, 128
	s_addc_u32 s31, s31, 0
	v_mfma_f32_16x16x32_bf16 v[84:87], v[202:205], v[176:179], v[84:87]
	s_add_u32 s56, s56, 128
	s_addc_u32 s57, s57, 0
	v_mfma_f32_16x16x32_bf16 v[88:91], v[194:197], v[186:189], v[88:91]
	s_add_u32 s32, s32, 128
	s_addc_u32 s33, s33, 0
	v_mfma_f32_16x16x32_bf16 v[92:95], v[202:205], v[186:189], v[92:95]
	s_add_u32 s58, s58, 128
	s_addc_u32 s59, s59, 0
	v_mfma_f32_16x16x32_bf16 v[64:67], v[198:201], v[164:167], v[64:67]
	v_mfma_f32_16x16x32_bf16 v[68:71], v[206:209], v[164:167], v[68:71]
	v_mfma_f32_16x16x32_bf16 v[72:75], v[198:201], v[172:175], v[72:75]
	v_mfma_f32_16x16x32_bf16 v[76:79], v[206:209], v[172:175], v[76:79]
	v_mfma_f32_16x16x32_bf16 v[80:83], v[198:201], v[180:183], v[80:83]
	v_mfma_f32_16x16x32_bf16 v[84:87], v[206:209], v[180:183], v[84:87]
	v_mfma_f32_16x16x32_bf16 v[88:91], v[198:201], v[190:193], v[88:91]
	v_mfma_f32_16x16x32_bf16 v[92:95], v[206:209], v[190:193], v[92:95]
	s_waitcnt vmcnt(8)
	s_waitcnt lgkmcnt(0)
	s_barrier
; #define PG8_STAGE(bufoff, gbase, voff) do { _Pragma("unroll") for (int _i = 0; _i < 2; ++_i) \
;         __builtin_amdgcn_global_load_lds((const unsigned*)((const char*)(gbase) + (voff)[_i]), (PG8_LAS unsigned*)(lds + (bufoff) + ldsw + _i * 8192), 16, 0, 0); } while (0)
; #define PG8_LDA(dst, b, h) do { _Pragma("unroll") for (int m = 0; m < 4; ++m) _Pragma("unroll") for (int k = 0; k < 2; ++k) dst[m][k] = *(const PG8_LAS bf16x8*)(lds + PG8_SA(b, h) + aoff + m * 2048 + k * 1024); } while (0)
; #define PG8_LDB(dst, b, h) do { _Pragma("unroll") for (int n = 0; n < 2; ++n) _Pragma("unroll") for (int k = 0; k < 2; ++k) dst[n][k] = *(const PG8_LAS bf16x8*)(lds + PG8_SB(b, h) + boff + n * 2048 + k * 1024); } while (0)
; template <class Epi, class Sched, bool ALIGN_EPI = false, bool SP2 = false>
; __device__ __forceinline__ void gemm_phase(PG8_LAS unsigned char* lds, const Gemm g, const Sched& S, const Epi& E) {
;     ...
;         for (int t = 0; t < nt; t += 2) {
;             const bool last = (t == nt - 2);
;             const char* a1 = cA + (size_t)(t + 1) * kstep;
;             const char* a2 = last ? nA : cA + (size_t)(t + 2) * kstep; const char* b2 = last ? nB : cB + (size_t)(t + 2) * kstep;
;             const char* a3 = a2 + kstep; const char* b3 = b2 + kstep;
;             if (last && has_next) S.a_ready(nxt);
;             if constexpr (SP2) {
;             PG8_LDB(B0, 0, 0); PG8_LDB(B1, 0, 1); PG8_SCHED; PG8_LDA(At, 0, 0); PG8_STAGE(PG8_SA(1, 1), a1 + hstep, voffA);
;             PG8_WAIT_V(8); PG8_WAIT_L(0); PG8_BAR; PG8_MMA(0, 0, At, B0); PG8_MMA(0, 1, At, B1); PG8_BAR; PG8_SCHED;
;             PG8_LDA(At, 0, 1); PG8_STAGE(PG8_SB(0, 0), b2, voffB); PG8_STAGE(PG8_SB(0, 1), b2 + hstep, voffB); PG8_STAGE(PG8_SA(0, 0), a2, voffA);
;             PG8_WAIT_V(8); PG8_WAIT_L(0); PG8_BAR; PG8_MMA(1, 0, At, B0); PG8_MMA(1, 1, At, B1); PG8_BAR; PG8_SCHED;
;             PG8_LDB(B0, 1, 0); PG8_LDB(B1, 1, 1); PG8_SCHED; PG8_LDA(At, 1, 0); PG8_STAGE(PG8_SA(0, 1), a2 + hstep, voffA);
;             PG8_WAIT_V(8); PG8_WAIT_L(0); PG8_BAR; PG8_MMA(0, 0, At, B0); PG8_MMA(0, 1, At, B1); PG8_BAR; PG8_SCHED;
;             PG8_LDA(At, 1, 1); PG8_STAGE(PG8_SB(1, 0), b3, voffB); PG8_STAGE(PG8_SB(1, 1), b3 + hstep, voffB); PG8_STAGE(PG8_SA(1, 0), a3, voffA);
;             PG8_WAIT_V(8); PG8_WAIT_L(0); PG8_BAR; PG8_MMA(1, 0, At, B0); PG8_MMA(1, 1, At, B1); PG8_BAR; PG8_SCHED;
	v_mfma_f32_16x16x32_bf16 v[32:35], v[210:213], v[128:131], v[32:35]
	ds_read_b128 v[194:197], v247 offset:32768
	v_mfma_f32_16x16x32_bf16 v[36:39], v[218:221], v[128:131], v[36:39]
	ds_read_b128 v[198:201], v248 offset:32768
	v_mfma_f32_16x16x32_bf16 v[40:43], v[210:213], v[136:139], v[40:43]
	ds_read_b128 v[202:205], v247 offset:34816
	v_mfma_f32_16x16x32_bf16 v[44:47], v[218:221], v[136:139], v[44:47]
	ds_read_b128 v[206:209], v248 offset:34816
	v_mfma_f32_16x16x32_bf16 v[48:51], v[210:213], v[144:147], v[48:51]
	s_add_i32 m0, s35, 0x8000
	v_mfma_f32_16x16x32_bf16 v[52:55], v[218:221], v[144:147], v[52:55]
	global_load_lds_dwordx4 v249, s[30:31]
	v_mfma_f32_16x16x32_bf16 v[56:59], v[210:213], v[152:155], v[56:59]
	s_add_i32 m0, s35, 0xa000
	v_mfma_f32_16x16x32_bf16 v[60:63], v[218:221], v[152:155], v[60:63]
	global_load_lds_dwordx4 v250, s[30:31]
	v_mfma_f32_16x16x32_bf16 v[32:35], v[214:217], v[132:135], v[32:35]
	s_add_i32 m0, s35, 0x1c000
	v_mfma_f32_16x16x32_bf16 v[36:39], v[222:225], v[132:135], v[36:39]
	global_load_lds_dwordx4 v251, s[58:59]
	v_mfma_f32_16x16x32_bf16 v[40:43], v[214:217], v[140:143], v[40:43]
	s_add_i32 m0, s35, 0x1e000
	v_mfma_f32_16x16x32_bf16 v[44:47], v[222:225], v[140:143], v[44:47]
	global_load_lds_dwordx4 v252, s[58:59]
	v_mfma_f32_16x16x32_bf16 v[48:51], v[214:217], v[148:151], v[48:51]
	ds_read_b128 v[160:163], v245 offset:49152
	v_mfma_f32_16x16x32_bf16 v[52:55], v[222:225], v[148:151], v[52:55]
	ds_read_b128 v[164:167], v246 offset:49152
	v_mfma_f32_16x16x32_bf16 v[56:59], v[214:217], v[156:159], v[56:59]
	ds_read_b128 v[168:171], v245 offset:51200
	v_mfma_f32_16x16x32_bf16 v[60:63], v[222:225], v[156:159], v[60:63]
	ds_read_b128 v[172:175], v246 offset:51200
	s_waitcnt lgkmcnt(4)
	v_mfma_f32_16x16x32_bf16 v[0:3], v[194:197], v[128:131], v[0:3]
	ds_read_b128 v[176:179], v245 offset:53248
	v_mfma_f32_16x16x32_bf16 v[4:7], v[202:205], v[128:131], v[4:7]
	ds_read_b128 v[180:183], v246 offset:53248
	v_mfma_f32_16x16x32_bf16 v[8:11], v[194:197], v[136:139], v[8:11]
	ds_read_b128 v[186:189], v245 offset:55296
	v_mfma_f32_16x16x32_bf16 v[12:15], v[202:205], v[136:139], v[12:15]
	ds_read_b128 v[190:193], v246 offset:55296
	v_mfma_f32_16x16x32_bf16 v[16:19], v[194:197], v[144:147], v[16:19]
	v_mfma_f32_16x16x32_bf16 v[20:23], v[202:205], v[144:147], v[20:23]
	v_mfma_f32_16x16x32_bf16 v[24:27], v[194:197], v[152:155], v[24:27]
	v_mfma_f32_16x16x32_bf16 v[28:31], v[202:205], v[152:155], v[28:31]
	v_mfma_f32_16x16x32_bf16 v[0:3], v[198:201], v[132:135], v[0:3]
	v_mfma_f32_16x16x32_bf16 v[4:7], v[206:209], v[132:135], v[4:7]
	v_mfma_f32_16x16x32_bf16 v[8:11], v[198:201], v[140:143], v[8:11]
	v_mfma_f32_16x16x32_bf16 v[12:15], v[206:209], v[140:143], v[12:15]
	v_mfma_f32_16x16x32_bf16 v[16:19], v[198:201], v[148:151], v[16:19]
	v_mfma_f32_16x16x32_bf16 v[20:23], v[206:209], v[148:151], v[20:23]
	v_mfma_f32_16x16x32_bf16 v[24:27], v[198:201], v[156:159], v[24:27]
	v_mfma_f32_16x16x32_bf16 v[28:31], v[206:209], v[156:159], v[28:31]
	s_waitcnt vmcnt(8)
	s_waitcnt lgkmcnt(0)
	s_barrier
	v_mfma_f32_16x16x32_bf16 v[64:67], v[194:197], v[160:163], v[64:67]
	s_add_i32 m0, s35, 0xc000
	v_mfma_f32_16x16x32_bf16 v[68:71], v[202:205], v[160:163], v[68:71]
	global_load_lds_dwordx4 v249, s[56:57]
	v_mfma_f32_16x16x32_bf16 v[72:75], v[194:197], v[168:171], v[72:75]
	s_add_i32 m0, s35, 0xe000
	v_mfma_f32_16x16x32_bf16 v[76:79], v[202:205], v[168:171], v[76:79]
	global_load_lds_dwordx4 v250, s[56:57]
	v_mfma_f32_16x16x32_bf16 v[80:83], v[194:197], v[176:179], v[80:83]
	s_add_i32 m0, s35, 0x18000
	v_mfma_f32_16x16x32_bf16 v[84:87], v[202:205], v[176:179], v[84:87]
	global_load_lds_dwordx4 v251, s[32:33]
	v_mfma_f32_16x16x32_bf16 v[88:91], v[194:197], v[186:189], v[88:91]
	s_add_i32 m0, s35, 0x1a000
	v_mfma_f32_16x16x32_bf16 v[92:95], v[202:205], v[186:189], v[92:95]
	global_load_lds_dwordx4 v252, s[32:33]
	v_mfma_f32_16x16x32_bf16 v[64:67], v[198:201], v[164:167], v[64:67]
	ds_read_b128 v[128:131], v245 offset:0
	v_mfma_f32_16x16x32_bf16 v[68:71], v[206:209], v[164:167], v[68:71]
	ds_read_b128 v[132:135], v246 offset:0
	v_mfma_f32_16x16x32_bf16 v[72:75], v[198:201], v[172:175], v[72:75]
	ds_read_b128 v[136:139], v245 offset:2048
	v_mfma_f32_16x16x32_bf16 v[76:79], v[206:209], v[172:175], v[76:79]
	ds_read_b128 v[140:143], v246 offset:2048
	v_mfma_f32_16x16x32_bf16 v[80:83], v[198:201], v[180:183], v[80:83]
	ds_read_b128 v[144:147], v245 offset:4096
	v_mfma_f32_16x16x32_bf16 v[84:87], v[206:209], v[180:183], v[84:87]
	ds_read_b128 v[148:151], v246 offset:4096
	v_mfma_f32_16x16x32_bf16 v[88:91], v[198:201], v[190:193], v[88:91]
	ds_read_b128 v[152:155], v245 offset:6144
	v_mfma_f32_16x16x32_bf16 v[92:95], v[206:209], v[190:193], v[92:95]
	ds_read_b128 v[156:159], v246 offset:6144
	v_mfma_f32_16x16x32_bf16 v[96:99], v[210:213], v[160:163], v[96:99]
	ds_read_b128 v[194:197], v247 offset:0
	v_mfma_f32_16x16x32_bf16 v[100:103], v[218:221], v[160:163], v[100:103]
	ds_read_b128 v[198:201], v248 offset:0
	v_mfma_f32_16x16x32_bf16 v[104:107], v[210:213], v[168:171], v[104:107]
	ds_read_b128 v[202:205], v247 offset:2048
	v_mfma_f32_16x16x32_bf16 v[108:111], v[218:221], v[168:171], v[108:111]
	ds_read_b128 v[206:209], v248 offset:2048
	v_mfma_f32_16x16x32_bf16 v[112:115], v[210:213], v[176:179], v[112:115]
	s_add_u32 s30, s30, 128
	s_addc_u32 s31, s31, 0
	v_mfma_f32_16x16x32_bf16 v[116:119], v[218:221], v[176:179], v[116:119]
	s_add_u32 s56, s56, 128
	s_addc_u32 s57, s57, 0
	v_mfma_f32_16x16x32_bf16 v[120:123], v[210:213], v[186:189], v[120:123]
	s_add_u32 s32, s32, 128
	s_addc_u32 s33, s33, 0
	v_mfma_f32_16x16x32_bf16 v[124:127], v[218:221], v[186:189], v[124:127]
	s_add_u32 s58, s58, 128
	s_addc_u32 s59, s59, 0
	v_mfma_f32_16x16x32_bf16 v[96:99], v[214:217], v[164:167], v[96:99]
	v_mfma_f32_16x16x32_bf16 v[100:103], v[222:225], v[164:167], v[100:103]
	v_mfma_f32_16x16x32_bf16 v[104:107], v[214:217], v[172:175], v[104:107]
	v_mfma_f32_16x16x32_bf16 v[108:111], v[222:225], v[172:175], v[108:111]
	v_mfma_f32_16x16x32_bf16 v[112:115], v[214:217], v[180:183], v[112:115]
	v_mfma_f32_16x16x32_bf16 v[116:119], v[222:225], v[180:183], v[116:119]
	v_mfma_f32_16x16x32_bf16 v[120:123], v[214:217], v[190:193], v[120:123]
	v_mfma_f32_16x16x32_bf16 v[124:127], v[222:225], v[190:193], v[124:127]
	s_add_i32 s34, s34, -1
	s_cmp_lg_u32 s34, 1
	s_cbranch_scc1 .Lp6_nosw0
	s_add_u32 s30, s26, 0
	s_addc_u32 s31, s27, 0
	s_add_u32 s32, s28, 0
	s_addc_u32 s33, s29, 0
	s_add_u32 s56, s30, 0x160000
	s_addc_u32 s57, s31, 0
	s_add_u32 s58, s32, 0x160000
	s_addc_u32 s59, s33, 0

; #define PG8_STAGE(bufoff, gbase, voff) do { _Pragma("unroll") for (int _i = 0; _i < 2; ++_i) \
;         __builtin_amdgcn_global_load_lds((const unsigned*)((const char*)(gbase) + (voff)[_i]), (PG8_LAS unsigned*)(lds + (bufoff) + ldsw + _i * 8192), 16, 0, 0); } while (0)
; #define PG8_LDA(dst, b, h) do { _Pragma("unroll") for (int m = 0; m < 4; ++m) _Pragma("unroll") for (int k = 0; k < 2; ++k) dst[m][k] = *(const PG8_LAS bf16x8*)(lds + PG8_SA(b, h) + aoff + m * 2048 + k * 1024); } while (0)
; #define PG8_LDB(dst, b, h) do { _Pragma("unroll") for (int n = 0; n < 2; ++n) _Pragma("unroll") for (int k = 0; k < 2; ++k) dst[n][k] = *(const PG8_LAS bf16x8*)(lds + PG8_SB(b, h) + boff + n * 2048 + k * 1024); } while (0)
; template <class Epi, class Sched, bool ALIGN_EPI = false, bool SP2 = false>
; __device__ __forceinline__ void gemm_phase(PG8_LAS unsigned char* lds, const Gemm g, const Sched& S, const Epi& E) {
;     ...
;         for (int t = 0; t < nt; t += 2) {
;             const bool last = (t == nt - 2);
;             const char* a1 = cA + (size_t)(t + 1) * kstep;
;             const char* a2 = last ? nA : cA + (size_t)(t + 2) * kstep; const char* b2 = last ? nB : cB + (size_t)(t + 2) * kstep;
;             const char* a3 = a2 + kstep; const char* b3 = b2 + kstep;
;             if (last && has_next) S.a_ready(nxt);
;             if constexpr (SP2) {
;             PG8_LDB(B0, 0, 0); PG8_LDB(B1, 0, 1); PG8_SCHED; PG8_LDA(At, 0, 0); PG8_STAGE(PG8_SA(1, 1), a1 + hstep, voffA);
;             PG8_WAIT_V(8); PG8_WAIT_L(0); PG8_BAR; PG8_MMA(0, 0, At, B0); PG8_MMA(0, 1, At, B1); PG8_BAR; PG8_SCHED;
;             PG8_LDA(At, 0, 1); PG8_STAGE(PG8_SB(0, 0), b2, voffB); PG8_STAGE(PG8_SB(0, 1), b2 + hstep, voffB); PG8_STAGE(PG8_SA(0, 0), a2, voffA);
;             PG8_WAIT_V(8); PG8_WAIT_L(0); PG8_BAR; PG8_MMA(1, 0, At, B0); PG8_MMA(1, 1, At, B1); PG8_BAR; PG8_SCHED;
;             PG8_LDB(B0, 1, 0); PG8_LDB(B1, 1, 1); PG8_SCHED; PG8_LDA(At, 1, 0); PG8_STAGE(PG8_SA(0, 1), a2 + hstep, voffA);
;             PG8_WAIT_V(8); PG8_WAIT_L(0); PG8_BAR; PG8_MMA(0, 0, At, B0); PG8_MMA(0, 1, At, B1); PG8_BAR; PG8_SCHED;
;             PG8_LDA(At, 1, 1); PG8_STAGE(PG8_SB(1, 0), b3, voffB); PG8_STAGE(PG8_SB(1, 1), b3 + hstep, voffB); PG8_STAGE(PG8_SA(1, 0), a3, voffA);
;             PG8_WAIT_V(8); PG8_WAIT_L(0); PG8_BAR; PG8_MMA(1, 0, At, B0); PG8_MMA(1, 1, At, B1); PG8_BAR; PG8_SCHED;
.Lp6_kloop1:
	s_waitcnt vmcnt(8)
	s_waitcnt lgkmcnt(0)
	s_barrier
	v_mfma_f32_16x16x32_bf16 v[0:3], v[194:197], v[128:131], v[0:3]
	ds_read_b128 v[210:213], v247 offset:16384
	v_mfma_f32_16x16x32_bf16 v[4:7], v[202:205], v[128:131], v[4:7]
	ds_read_b128 v[214:217], v248 offset:16384
	v_mfma_f32_16x16x32_bf16 v[8:11], v[194:197], v[136:139], v[8:11]
	ds_read_b128 v[218:221], v247 offset:18432
	v_mfma_f32_16x16x32_bf16 v[12:15], v[202:205], v[136:139], v[12:15]
	ds_read_b128 v[222:225], v248 offset:18432
	v_mfma_f32_16x16x32_bf16 v[16:19], v[194:197], v[144:147], v[16:19]
	ds_read_b128 v[160:163], v245 offset:16384
	v_mfma_f32_16x16x32_bf16 v[20:23], v[202:205], v[144:147], v[20:23]
	ds_read_b128 v[164:167], v246 offset:16384
	v_mfma_f32_16x16x32_bf16 v[24:27], v[194:197], v[152:155], v[24:27]
	ds_read_b128 v[168:171], v245 offset:18432
	v_mfma_f32_16x16x32_bf16 v[28:31], v[202:205], v[152:155], v[28:31]
	ds_read_b128 v[172:175], v246 offset:18432
	v_mfma_f32_16x16x32_bf16 v[0:3], v[198:201], v[132:135], v[0:3]
	ds_read_b128 v[176:179], v245 offset:20480
	v_mfma_f32_16x16x32_bf16 v[4:7], v[206:209], v[132:135], v[4:7]
	ds_read_b128 v[180:183], v246 offset:20480
	v_mfma_f32_16x16x32_bf16 v[8:11], v[198:201], v[140:143], v[8:11]
	ds_read_b128 v[186:189], v245 offset:22528
	v_mfma_f32_16x16x32_bf16 v[12:15], v[206:209], v[140:143], v[12:15]
	ds_read_b128 v[190:193], v246 offset:22528
	v_mfma_f32_16x16x32_bf16 v[16:19], v[198:201], v[148:151], v[16:19]
	v_mfma_f32_16x16x32_bf16 v[20:23], v[206:209], v[148:151], v[20:23]
	v_mfma_f32_16x16x32_bf16 v[24:27], v[198:201], v[156:159], v[24:27]
	v_mfma_f32_16x16x32_bf16 v[28:31], v[206:209], v[156:159], v[28:31]
	s_waitcnt lgkmcnt(8)
	v_mfma_f32_16x16x32_bf16 v[32:35], v[210:213], v[128:131], v[32:35]
	v_mfma_f32_16x16x32_bf16 v[36:39], v[218:221], v[128:131], v[36:39]
	s_add_i32 m0, s35, 0x0
	v_mfma_f32_16x16x32_bf16 v[40:43], v[210:213], v[136:139], v[40:43]
	global_load_lds_dwordx4 v249, s[30:31]
	v_mfma_f32_16x16x32_bf16 v[44:47], v[218:221], v[136:139], v[44:47]
	v_mfma_f32_16x16x32_bf16 v[48:51], v[210:213], v[144:147], v[48:51]
	s_add_i32 m0, s35, 0x2000
	v_mfma_f32_16x16x32_bf16 v[52:55], v[218:221], v[144:147], v[52:55]
	global_load_lds_dwordx4 v250, s[30:31]
	v_mfma_f32_16x16x32_bf16 v[56:59], v[210:213], v[152:155], v[56:59]
	v_mfma_f32_16x16x32_bf16 v[60:63], v[218:221], v[152:155], v[60:63]
	s_add_i32 m0, s35, 0x10000
	v_mfma_f32_16x16x32_bf16 v[32:35], v[214:217], v[132:135], v[32:35]
	global_load_lds_dwordx4 v251, s[32:33]
	v_mfma_f32_16x16x32_bf16 v[36:39], v[222:225], v[132:135], v[36:39]
	v_mfma_f32_16x16x32_bf16 v[40:43], v[214:217], v[140:143], v[40:43]
	s_add_i32 m0, s35, 0x12000
	v_mfma_f32_16x16x32_bf16 v[44:47], v[222:225], v[140:143], v[44:47]
	global_load_lds_dwordx4 v252, s[32:33]
	v_mfma_f32_16x16x32_bf16 v[48:51], v[214:217], v[148:151], v[48:51]
	v_mfma_f32_16x16x32_bf16 v[52:55], v[222:225], v[148:151], v[52:55]
	v_mfma_f32_16x16x32_bf16 v[56:59], v[214:217], v[156:159], v[56:59]
	v_mfma_f32_16x16x32_bf16 v[60:63], v[222:225], v[156:159], v[60:63]
	s_waitcnt vmcnt(8)
	s_waitcnt lgkmcnt(0)
	s_barrier
	v_mfma_f32_16x16x32_bf16 v[96:99], v[210:213], v[160:163], v[96:99]
	ds_read_b128 v[128:131], v245 offset:32768
	v_mfma_f32_16x16x32_bf16 v[100:103], v[218:221], v[160:163], v[100:103]
	ds_read_b128 v[132:135], v246 offset:32768
	v_mfma_f32_16x16x32_bf16 v[104:107], v[210:213], v[168:171], v[104:107]
	ds_read_b128 v[136:139], v245 offset:34816
	v_mfma_f32_16x16x32_bf16 v[108:111], v[218:221], v[168:171], v[108:111]
	ds_read_b128 v[140:143], v246 offset:34816
	v_mfma_f32_16x16x32_bf16 v[112:115], v[210:213], v[176:179], v[112:115]
	ds_read_b128 v[144:147], v245 offset:36864
	v_mfma_f32_16x16x32_bf16 v[116:119], v[218:221], v[176:179], v[116:119]
	ds_read_b128 v[148:151], v246 offset:36864
	v_mfma_f32_16x16x32_bf16 v[120:123], v[210:213], v[186:189], v[120:123]
	ds_read_b128 v[152:155], v245 offset:38912
	v_mfma_f32_16x16x32_bf16 v[124:127], v[218:221], v[186:189], v[124:127]
	ds_read_b128 v[156:159], v246 offset:38912
	v_mfma_f32_16x16x32_bf16 v[96:99], v[214:217], v[164:167], v[96:99]
	v_mfma_f32_16x16x32_bf16 v[100:103], v[222:225], v[164:167], v[100:103]
	v_mfma_f32_16x16x32_bf16 v[104:107], v[214:217], v[172:175], v[104:107]
	v_mfma_f32_16x16x32_bf16 v[108:111], v[222:225], v[172:175], v[108:111]
	v_mfma_f32_16x16x32_bf16 v[112:115], v[214:217], v[180:183], v[112:115]
	v_mfma_f32_16x16x32_bf16 v[116:119], v[222:225], v[180:183], v[116:119]
	v_mfma_f32_16x16x32_bf16 v[120:123], v[214:217], v[190:193], v[120:123]
	v_mfma_f32_16x16x32_bf16 v[124:127], v[222:225], v[190:193], v[124:127]
	v_mfma_f32_16x16x32_bf16 v[64:67], v[194:197], v[160:163], v[64:67]
	ds_read_b128 v[210:213], v247 offset:49152
	v_mfma_f32_16x16x32_bf16 v[68:71], v[202:205], v[160:163], v[68:71]
	ds_read_b128 v[214:217], v248 offset:49152
	v_mfma_f32_16x16x32_bf16 v[72:75], v[194:197], v[168:171], v[72:75]
	ds_read_b128 v[218:221], v247 offset:51200
	v_mfma_f32_16x16x32_bf16 v[76:79], v[202:205], v[168:171], v[76:79]
	ds_read_b128 v[222:225], v248 offset:51200
	v_mfma_f32_16x16x32_bf16 v[80:83], v[194:197], v[176:179], v[80:83]
	s_add_i32 m0, s35, 0x4000
	v_mfma_f32_16x16x32_bf16 v[84:87], v[202:205], v[176:179], v[84:87]
	global_load_lds_dwordx4 v249, s[56:57]
	v_mfma_f32_16x16x32_bf16 v[88:91], v[194:197], v[186:189], v[88:91]
	s_add_i32 m0, s35, 0x6000
	v_mfma_f32_16x16x32_bf16 v[92:95], v[202:205], v[186:189], v[92:95]
	global_load_lds_dwordx4 v250, s[56:57]
	v_mfma_f32_16x16x32_bf16 v[64:67], v[198:201], v[164:167], v[64:67]
	s_add_i32 m0, s35, 0x14000
	v_mfma_f32_16x16x32_bf16 v[68:71], v[206:209], v[164:167], v[68:71]
	global_load_lds_dwordx4 v251, s[58:59]
	v_mfma_f32_16x16x32_bf16 v[72:75], v[198:201], v[172:175], v[72:75]
	s_add_i32 m0, s35, 0x16000
	v_mfma_f32_16x16x32_bf16 v[76:79], v[206:209], v[172:175], v[76:79]
	global_load_lds_dwordx4 v252, s[58:59]
	v_mfma_f32_16x16x32_bf16 v[80:83], v[198:201], v[180:183], v[80:83]
	s_add_u32 s30, s30, 128
	s_addc_u32 s31, s31, 0
	v_mfma_f32_16x16x32_bf16 v[84:87], v[206:209], v[180:183], v[84:87]
	s_add_u32 s56, s56, 128
	s_addc_u32 s57, s57, 0
	v_mfma_f32_16x16x32_bf16 v[88:91], v[198:201], v[190:193], v[88:91]
	s_add_u32 s32, s32, 128
	s_addc_u32 s33, s33, 0
	v_mfma_f32_16x16x32_bf16 v[92:95], v[206:209], v[190:193], v[92:95]
	s_add_u32 s58, s58, 128
	s_addc_u32 s59, s59, 0
	s_waitcnt vmcnt(8)
	s_waitcnt lgkmcnt(0)
	s_barrier
; #define PG8_STAGE(bufoff, gbase, voff) do { _Pragma("unroll") for (int _i = 0; _i < 2; ++_i) \
;         __builtin_amdgcn_global_load_lds((const unsigned*)((const char*)(gbase) + (voff)[_i]), (PG8_LAS unsigned*)(lds + (bufoff) + ldsw + _i * 8192), 16, 0, 0); } while (0)
; #define PG8_LDA(dst, b, h) do { _Pragma("unroll") for (int m = 0; m < 4; ++m) _Pragma("unroll") for (int k = 0; k < 2; ++k) dst[m][k] = *(const PG8_LAS bf16x8*)(lds + PG8_SA(b, h) + aoff + m * 2048 + k * 1024); } while (0)
; #define PG8_LDB(dst, b, h) do { _Pragma("unroll") for (int n = 0; n < 2; ++n) _Pragma("unroll") for (int k = 0; k < 2; ++k) dst[n][k] = *(const PG8_LAS bf16x8*)(lds + PG8_SB(b, h) + boff + n * 2048 + k * 1024); } while (0)
; template <class Epi, class Sched, bool ALIGN_EPI = false, bool SP2 = false>
; __device__ __forceinline__ void gemm_phase(PG8_LAS unsigned char* lds, const Gemm g, const Sched& S, const Epi& E) {
;     ...
;         for (int t = 0; t < nt; t += 2) {
;             const bool last = (t == nt - 2);
;             const char* a1 = cA + (size_t)(t + 1) * kstep;
;             const char* a2 = last ? nA : cA + (size_t)(t + 2) * kstep; const char* b2 = last ? nB : cB + (size_t)(t + 2) * kstep;
;             const char* a3 = a2 + kstep; const char* b3 = b2 + kstep;
;             if (last && has_next) S.a_ready(nxt);
;             if constexpr (SP2) {
;             PG8_LDB(B0, 0, 0); PG8_LDB(B1, 0, 1); PG8_SCHED; PG8_LDA(At, 0, 0); PG8_STAGE(PG8_SA(1, 1), a1 + hstep, voffA);
;             PG8_WAIT_V(8); PG8_WAIT_L(0); PG8_BAR; PG8_MMA(0, 0, At, B0); PG8_MMA(0, 1, At, B1); PG8_BAR; PG8_SCHED;
;             PG8_LDA(At, 0, 1); PG8_STAGE(PG8_SB(0, 0), b2, voffB); PG8_STAGE(PG8_SB(0, 1), b2 + hstep, voffB); PG8_STAGE(PG8_SA(0, 0), a2, voffA);
;             PG8_WAIT_V(8); PG8_WAIT_L(0); PG8_BAR; PG8_MMA(1, 0, At, B0); PG8_MMA(1, 1, At, B1); PG8_BAR; PG8_SCHED;
;             PG8_LDB(B0, 1, 0); PG8_LDB(B1, 1, 1); PG8_SCHED; PG8_LDA(At, 1, 0); PG8_STAGE(PG8_SA(0, 1), a2 + hstep, voffA);
;             PG8_WAIT_V(8); PG8_WAIT_L(0); PG8_BAR; PG8_MMA(0, 0, At, B0); PG8_MMA(0, 1, At, B1); PG8_BAR; PG8_SCHED;
;             PG8_LDA(At, 1, 1); PG8_STAGE(PG8_SB(1, 0), b3, voffB); PG8_STAGE(PG8_SB(1, 1), b3 + hstep, voffB); PG8_STAGE(PG8_SA(1, 0), a3, voffA);
;             PG8_WAIT_V(8); PG8_WAIT_L(0); PG8_BAR; PG8_MMA(1, 0, At, B0); PG8_MMA(1, 1, At, B1); PG8_BAR; PG8_SCHED;
	v_mfma_f32_16x16x32_bf16 v[32:35], v[210:213], v[128:131], v[32:35]
	ds_read_b128 v[194:197], v247 offset:32768
	v_mfma_f32_16x16x32_bf16 v[36:39], v[218:221], v[128:131], v[36:39]
	ds_read_b128 v[198:201], v248 offset:32768
	v_mfma_f32_16x16x32_bf16 v[40:43], v[210:213], v[136:139], v[40:43]
	ds_read_b128 v[202:205], v247 offset:34816
	v_mfma_f32_16x16x32_bf16 v[44:47], v[218:221], v[136:139], v[44:47]
	ds_read_b128 v[206:209], v248 offset:34816
	v_mfma_f32_16x16x32_bf16 v[48:51], v[210:213], v[144:147], v[48:51]
	ds_read_b128 v[160:163], v245 offset:49152
	v_mfma_f32_16x16x32_bf16 v[52:55], v[218:221], v[144:147], v[52:55]
	ds_read_b128 v[164:167], v246 offset:49152
	v_mfma_f32_16x16x32_bf16 v[56:59], v[210:213], v[152:155], v[56:59]
	ds_read_b128 v[168:171], v245 offset:51200
	v_mfma_f32_16x16x32_bf16 v[60:63], v[218:221], v[152:155], v[60:63]
	ds_read_b128 v[172:175], v246 offset:51200
	v_mfma_f32_16x16x32_bf16 v[32:35], v[214:217], v[132:135], v[32:35]
	ds_read_b128 v[176:179], v245 offset:53248
	v_mfma_f32_16x16x32_bf16 v[36:39], v[222:225], v[132:135], v[36:39]
	ds_read_b128 v[180:183], v246 offset:53248
	v_mfma_f32_16x16x32_bf16 v[40:43], v[214:217], v[140:143], v[40:43]
	ds_read_b128 v[186:189], v245 offset:55296
	v_mfma_f32_16x16x32_bf16 v[44:47], v[222:225], v[140:143], v[44:47]
	ds_read_b128 v[190:193], v246 offset:55296
	v_mfma_f32_16x16x32_bf16 v[48:51], v[214:217], v[148:151], v[48:51]
	v_mfma_f32_16x16x32_bf16 v[52:55], v[222:225], v[148:151], v[52:55]
	v_mfma_f32_16x16x32_bf16 v[56:59], v[214:217], v[156:159], v[56:59]
	v_mfma_f32_16x16x32_bf16 v[60:63], v[222:225], v[156:159], v[60:63]
	s_waitcnt lgkmcnt(8)
	v_mfma_f32_16x16x32_bf16 v[0:3], v[194:197], v[128:131], v[0:3]
	v_mfma_f32_16x16x32_bf16 v[4:7], v[202:205], v[128:131], v[4:7]
	s_add_i32 m0, s35, 0x8000
	v_mfma_f32_16x16x32_bf16 v[8:11], v[194:197], v[136:139], v[8:11]
	global_load_lds_dwordx4 v249, s[30:31]
	v_mfma_f32_16x16x32_bf16 v[12:15], v[202:205], v[136:139], v[12:15]
	v_mfma_f32_16x16x32_bf16 v[16:19], v[194:197], v[144:147], v[16:19]
	s_add_i32 m0, s35, 0xa000
	v_mfma_f32_16x16x32_bf16 v[20:23], v[202:205], v[144:147], v[20:23]
	global_load_lds_dwordx4 v250, s[30:31]
	v_mfma_f32_16x16x32_bf16 v[24:27], v[194:197], v[152:155], v[24:27]
	v_mfma_f32_16x16x32_bf16 v[28:31], v[202:205], v[152:155], v[28:31]
	s_add_i32 m0, s35, 0x1c000
	v_mfma_f32_16x16x32_bf16 v[0:3], v[198:201], v[132:135], v[0:3]
	global_load_lds_dwordx4 v251, s[58:59]
	v_mfma_f32_16x16x32_bf16 v[4:7], v[206:209], v[132:135], v[4:7]
	v_mfma_f32_16x16x32_bf16 v[8:11], v[198:201], v[140:143], v[8:11]
	s_add_i32 m0, s35, 0x1e000
	v_mfma_f32_16x16x32_bf16 v[12:15], v[206:209], v[140:143], v[12:15]
	global_load_lds_dwordx4 v252, s[58:59]
	v_mfma_f32_16x16x32_bf16 v[16:19], v[198:201], v[148:151], v[16:19]
	v_mfma_f32_16x16x32_bf16 v[20:23], v[206:209], v[148:151], v[20:23]
	v_mfma_f32_16x16x32_bf16 v[24:27], v[198:201], v[156:159], v[24:27]
	v_mfma_f32_16x16x32_bf16 v[28:31], v[206:209], v[156:159], v[28:31]
	s_waitcnt vmcnt(8)
	s_waitcnt lgkmcnt(0)
	s_barrier
	v_mfma_f32_16x16x32_bf16 v[64:67], v[194:197], v[160:163], v[64:67]
	ds_read_b128 v[128:131], v245 offset:0
	v_mfma_f32_16x16x32_bf16 v[68:71], v[202:205], v[160:163], v[68:71]
	ds_read_b128 v[132:135], v246 offset:0
	v_mfma_f32_16x16x32_bf16 v[72:75], v[194:197], v[168:171], v[72:75]
	ds_read_b128 v[136:139], v245 offset:2048
	v_mfma_f32_16x16x32_bf16 v[76:79], v[202:205], v[168:171], v[76:79]
	ds_read_b128 v[140:143], v246 offset:2048
	v_mfma_f32_16x16x32_bf16 v[80:83], v[194:197], v[176:179], v[80:83]
	ds_read_b128 v[144:147], v245 offset:4096
	v_mfma_f32_16x16x32_bf16 v[84:87], v[202:205], v[176:179], v[84:87]
	ds_read_b128 v[148:151], v246 offset:4096
	v_mfma_f32_16x16x32_bf16 v[88:91], v[194:197], v[186:189], v[88:91]
	ds_read_b128 v[152:155], v245 offset:6144
	v_mfma_f32_16x16x32_bf16 v[92:95], v[202:205], v[186:189], v[92:95]
	ds_read_b128 v[156:159], v246 offset:6144
	v_mfma_f32_16x16x32_bf16 v[64:67], v[198:201], v[164:167], v[64:67]
	v_mfma_f32_16x16x32_bf16 v[68:71], v[206:209], v[164:167], v[68:71]
	v_mfma_f32_16x16x32_bf16 v[72:75], v[198:201], v[172:175], v[72:75]
	v_mfma_f32_16x16x32_bf16 v[76:79], v[206:209], v[172:175], v[76:79]
	v_mfma_f32_16x16x32_bf16 v[80:83], v[198:201], v[180:183], v[80:83]
	v_mfma_f32_16x16x32_bf16 v[84:87], v[206:209], v[180:183], v[84:87]
	v_mfma_f32_16x16x32_bf16 v[88:91], v[198:201], v[190:193], v[88:91]
	v_mfma_f32_16x16x32_bf16 v[92:95], v[206:209], v[190:193], v[92:95]
	v_mfma_f32_16x16x32_bf16 v[96:99], v[210:213], v[160:163], v[96:99]
	ds_read_b128 v[194:197], v247 offset:0
	v_mfma_f32_16x16x32_bf16 v[100:103], v[218:221], v[160:163], v[100:103]
	ds_read_b128 v[198:201], v248 offset:0
	v_mfma_f32_16x16x32_bf16 v[104:107], v[210:213], v[168:171], v[104:107]
	ds_read_b128 v[202:205], v247 offset:2048
	v_mfma_f32_16x16x32_bf16 v[108:111], v[218:221], v[168:171], v[108:111]
	ds_read_b128 v[206:209], v248 offset:2048
	v_mfma_f32_16x16x32_bf16 v[112:115], v[210:213], v[176:179], v[112:115]
	s_add_i32 m0, s35, 0xc000
	v_mfma_f32_16x16x32_bf16 v[116:119], v[218:221], v[176:179], v[116:119]
	global_load_lds_dwordx4 v249, s[56:57]
	v_mfma_f32_16x16x32_bf16 v[120:123], v[210:213], v[186:189], v[120:123]
	s_add_i32 m0, s35, 0xe000
	v_mfma_f32_16x16x32_bf16 v[124:127], v[218:221], v[186:189], v[124:127]
	global_load_lds_dwordx4 v250, s[56:57]
	v_mfma_f32_16x16x32_bf16 v[96:99], v[214:217], v[164:167], v[96:99]
	s_add_i32 m0, s35, 0x18000
	v_mfma_f32_16x16x32_bf16 v[100:103], v[222:225], v[164:167], v[100:103]
	global_load_lds_dwordx4 v251, s[32:33]
	v_mfma_f32_16x16x32_bf16 v[104:107], v[214:217], v[172:175], v[104:107]
	s_add_i32 m0, s35, 0x1a000
	v_mfma_f32_16x16x32_bf16 v[108:111], v[222:225], v[172:175], v[108:111]
	global_load_lds_dwordx4 v252, s[32:33]
	v_mfma_f32_16x16x32_bf16 v[112:115], v[214:217], v[180:183], v[112:115]
	s_add_u32 s30, s30, 128
	s_addc_u32 s31, s31, 0
	v_mfma_f32_16x16x32_bf16 v[116:119], v[222:225], v[180:183], v[116:119]
	s_add_u32 s56, s56, 128
	s_addc_u32 s57, s57, 0
	v_mfma_f32_16x16x32_bf16 v[120:123], v[214:217], v[190:193], v[120:123]
	s_add_u32 s32, s32, 128
	s_addc_u32 s33, s33, 0
	v_mfma_f32_16x16x32_bf16 v[124:127], v[222:225], v[190:193], v[124:127]
	s_add_u32 s58, s58, 128
	s_addc_u32 s59, s59, 0
	s_add_i32 s34, s34, -1
	s_cmp_lg_u32 s34, 1
	s_cbranch_scc1 .Lp6_nosw1
	s_add_u32 s30, s26, 0
	s_addc_u32 s31, s27, 0
	s_add_u32 s32, s28, 0
	s_addc_u32 s33, s29, 0
	s_add_u32 s56, s30, 0x160000
	s_addc_u32 s57, s31, 0
	s_add_u32 s58, s32, 0x160000
	s_addc_u32 s59, s33, 0

; __device__ __forceinline__ unsigned cvt_pk_bf16(float lo, float hi) { unsigned r; asm volatile("v_cvt_pk_bf16_f32 %0, %1, %2" : "=v"(r) : "v"(lo), "v"(hi)); return r; }
;     __device__ __forceinline__ void tail(const f32x4& b0, const f32x4& b1, const f32x4& a0, const f32x4& a1, bf16_t* dst, float& s) const {
;         const f32x4 o0 = b0 + a0, o1 = b1 + a1;
;         s += ((o0[0] * o0[0] + o0[1] * o0[1]) + (o0[2] * o0[2] + o0[3] * o0[3])) + ((o1[0] * o1[0] + o1[1] * o1[1]) + (o1[2] * o1[2] + o1[3] * o1[3]));
;         u32x4 w; w.x = cvt_pk_bf16(o0[0], o0[1]); w.y = cvt_pk_bf16(o0[2], o0[3]); w.z = cvt_pk_bf16(o1[0], o1[1]); w.w = cvt_pk_bf16(o1[2], o1[3]);
;         *(u32x4*)dst = w;
;     __device__ __forceinline__ void operator()(const f32x4 (&acc)[2][2][4][2], const Unit& u, int wr, int wc, int fr, int fq) const {
;     ...
;         if constexpr (BASE_BF16) {
;             u32x4 raw[2][4][2];
; #pragma unroll
;             for (int ai = 0; ai < 2; ++ai)
; #pragma unroll
;                 for (int m = 0; m < 4; ++m) { const int row = u.pm * BM + ai * HALF + wr * 64 + m * 16 + fr; const size_t off = (size_t)row * ldc + col0;
; #pragma unroll
;                     for (int bj = 0; bj < 2; ++bj) raw[ai][m][bj] = *(const u32x4*)((const bf16_t*)base + off + bj * HALF); }
;             asm volatile("" ::: "memory");
; #pragma unroll
;             for (int ai = 0; ai < 2; ++ai)
; #pragma unroll
;                 for (int m = 0; m < 4; ++m) { const int row = u.pm * BM + ai * HALF + wr * 64 + m * 16 + fr; const size_t off = (size_t)row * ldc + col0; float s = 0.f;
; #pragma unroll
;                     for (int bj = 0; bj < 2; ++bj) { const u32x4 r = raw[ai][m][bj];
;                         const f32x4 b0 = {__uint_as_float(r.x << 16), __uint_as_float(r.x & 0xffff0000u), __uint_as_float(r.y << 16), __uint_as_float(r.y & 0xffff0000u)};
;                         const f32x4 b1 = {__uint_as_float(r.z << 16), __uint_as_float(r.z & 0xffff0000u), __uint_as_float(r.w << 16), __uint_as_float(r.w & 0xffff0000u)};
;                         tail(b0, b1, acc[ai][bj][m][0], acc[ai][bj][m][1], out + off + bj * HALF, s); }
;                     s += __shfl_xor(s, 16); s += __shfl_xor(s, 32);
;                     if (fq == 0) atomicAdd(ss + row, s); }
.Lp6_kdone:
	s_waitcnt lgkmcnt(0)
	s_nop 7
	s_nop 7
	v_and_b32_e32 v254, 63, v185
	v_and_b32_e32 v255, 15, v254
	v_lshrrev_b32_e32 v234, 4, v254
	s_lshl_b32 s40, s37, 6
	v_add_u32_e32 v255, s40, v255
	v_lshlrev_b32_e32 v230, 2, v255
	v_lshlrev_b32_e32 v228, 12, v255
	v_lshlrev_b32_e32 v229, 13, v255
	s_lshl_b32 s41, s38, 6
	v_lshl_add_u32 v228, v234, 4, v228
	v_add_u32_e32 v228, s41, v228
	s_lshl_b32 s41, s38, 7
	v_lshl_add_u32 v229, v234, 5, v229
	v_add_u32_e32 v229, s41, v229
	v_mov_b32_e32 v231, 0x358637bd
	v_xor_b32_e32 v232, 16, v254
	v_lshlrev_b32_e32 v232, 2, v232
	v_xor_b32_e32 v233, 32, v254
	v_lshlrev_b32_e32 v233, 2, v233
	s_lshl_b32 s40, s17, 20
	s_lshl_b32 s41, s18, 9
	s_add_u32 s40, s40, s41
	s_add_u32 s48, s76, 0x6800000
	s_addc_u32 s49, s77, 0
	s_add_u32 s48, s48, s40
	s_addc_u32 s49, s49, 0
	s_lshl_b32 s40, s17, 10
	s_add_u32 s40, s40, 0x10000
	s_add_u32 s50, s76, s40
	s_addc_u32 s51, s77, 0
	v_readlane_b32 s52, v244, 2
	v_readlane_b32 s53, v244, 3
	s_lshl_b32 s40, s17, 21
	s_lshl_b32 s41, s18, 10
	s_add_u32 s40, s40, s41
	s_add_u32 s52, s52, s40
	s_addc_u32 s53, s53, 0
	s_lshl_b32 s40, s17, 6
	s_add_u32 s40, s40, 0x28000
	s_add_u32 s54, s76, s40
	s_addc_u32 s55, s77, 0
	v_add_u32_e32 v234, 0x0, v228
	global_load_dwordx4 v[128:131], v234, s[48:49] offset:0
	global_load_dwordx4 v[132:135], v234, s[48:49] offset:256
	v_add_u32_e32 v234, 0x10000, v228
	global_load_dwordx4 v[136:139], v234, s[48:49] offset:0
	global_load_dwordx4 v[140:143], v234, s[48:49] offset:256
	v_add_u32_e32 v234, 0x20000, v228
	global_load_dwordx4 v[144:147], v234, s[48:49] offset:0
	global_load_dwordx4 v[148:151], v234, s[48:49] offset:256
	v_add_u32_e32 v234, 0x30000, v228
	global_load_dwordx4 v[152:155], v234, s[48:49] offset:0
	global_load_dwordx4 v[156:159], v234, s[48:49] offset:256
	v_add_u32_e32 v234, 0x80000, v228
	global_load_dwordx4 v[160:163], v234, s[48:49] offset:0
	global_load_dwordx4 v[164:167], v234, s[48:49] offset:256
	v_add_u32_e32 v234, 0x90000, v228
	global_load_dwordx4 v[168:171], v234, s[48:49] offset:0
	global_load_dwordx4 v[172:175], v234, s[48:49] offset:256
	v_add_u32_e32 v234, 0xa0000, v228
	global_load_dwordx4 v[176:179], v234, s[48:49] offset:0
	global_load_dwordx4 v[180:183], v234, s[48:49] offset:256
	v_add_u32_e32 v234, 0xb0000, v228
	global_load_dwordx4 v[186:189], v234, s[48:49] offset:0
	global_load_dwordx4 v[190:193], v234, s[48:49] offset:256
	s_waitcnt vmcnt(0)
	v_lshlrev_b32_e32 v254, 16, v128
	v_and_b32_e32 v255, 0xffff0000, v128
	v_add_f32_e32 v0, v0, v254
	v_add_f32_e32 v1, v1, v255
	v_mul_f32_e32 v238, v0, v0
	v_fmac_f32_e32 v238, v1, v1
	v_lshlrev_b32_e32 v254, 16, v129
	v_and_b32_e32 v255, 0xffff0000, v129
	v_add_f32_e32 v2, v2, v254
	v_add_f32_e32 v3, v3, v255
	v_fmac_f32_e32 v238, v2, v2
	v_fmac_f32_e32 v238, v3, v3
	v_lshlrev_b32_e32 v254, 16, v130
	v_and_b32_e32 v255, 0xffff0000, v130
	v_add_f32_e32 v4, v4, v254
	v_add_f32_e32 v5, v5, v255
	v_fmac_f32_e32 v238, v4, v4
	v_fmac_f32_e32 v238, v5, v5
	v_lshlrev_b32_e32 v254, 16, v131
	v_and_b32_e32 v255, 0xffff0000, v131
	v_add_f32_e32 v6, v6, v254
	v_add_f32_e32 v7, v7, v255
	v_fmac_f32_e32 v238, v6, v6
	v_fmac_f32_e32 v238, v7, v7
	v_lshlrev_b32_e32 v254, 16, v132
	v_and_b32_e32 v255, 0xffff0000, v132
	v_add_f32_e32 v32, v32, v254
	v_add_f32_e32 v33, v33, v255
	v_fmac_f32_e32 v238, v32, v32
	v_fmac_f32_e32 v238, v33, v33
	v_lshlrev_b32_e32 v254, 16, v133
	v_and_b32_e32 v255, 0xffff0000, v133
	v_add_f32_e32 v34, v34, v254
	v_add_f32_e32 v35, v35, v255
	v_fmac_f32_e32 v238, v34, v34
	v_fmac_f32_e32 v238, v35, v35
	v_lshlrev_b32_e32 v254, 16, v134
	v_and_b32_e32 v255, 0xffff0000, v134
	v_add_f32_e32 v36, v36, v254
	v_add_f32_e32 v37, v37, v255
	v_fmac_f32_e32 v238, v36, v36
	v_fmac_f32_e32 v238, v37, v37
	v_lshlrev_b32_e32 v254, 16, v135
	v_and_b32_e32 v255, 0xffff0000, v135
	v_add_f32_e32 v38, v38, v254
	v_add_f32_e32 v39, v39, v255
	v_fmac_f32_e32 v238, v38, v38
	v_fmac_f32_e32 v238, v39, v39
	v_lshlrev_b32_e32 v254, 16, v136
	v_and_b32_e32 v255, 0xffff0000, v136
	v_add_f32_e32 v8, v8, v254
	v_add_f32_e32 v9, v9, v255
	v_mul_f32_e32 v239, v8, v8
	v_fmac_f32_e32 v239, v9, v9
	v_lshlrev_b32_e32 v254, 16, v137
	v_and_b32_e32 v255, 0xffff0000, v137
	v_add_f32_e32 v10, v10, v254
	v_add_f32_e32 v11, v11, v255
	v_fmac_f32_e32 v239, v10, v10
	v_fmac_f32_e32 v239, v11, v11
	v_lshlrev_b32_e32 v254, 16, v138
	v_and_b32_e32 v255, 0xffff0000, v138
	v_add_f32_e32 v12, v12, v254
	v_add_f32_e32 v13, v13, v255
	v_fmac_f32_e32 v239, v12, v12
	v_fmac_f32_e32 v239, v13, v13
	v_lshlrev_b32_e32 v254, 16, v139
	v_and_b32_e32 v255, 0xffff0000, v139
	v_add_f32_e32 v14, v14, v254
	v_add_f32_e32 v15, v15, v255
	v_fmac_f32_e32 v239, v14, v14
	v_fmac_f32_e32 v239, v15, v15
	v_lshlrev_b32_e32 v254, 16, v140
	v_and_b32_e32 v255, 0xffff0000, v140
	v_add_f32_e32 v40, v40, v254
	v_add_f32_e32 v41, v41, v255
	v_fmac_f32_e32 v239, v40, v40
	v_fmac_f32_e32 v239, v41, v41
	v_lshlrev_b32_e32 v254, 16, v141
	v_and_b32_e32 v255, 0xffff0000, v141
	v_add_f32_e32 v42, v42, v254
	v_add_f32_e32 v43, v43, v255
	v_fmac_f32_e32 v239, v42, v42
	v_fmac_f32_e32 v239, v43, v43
	v_lshlrev_b32_e32 v254, 16, v142
	v_and_b32_e32 v255, 0xffff0000, v142
	v_add_f32_e32 v44, v44, v254
	v_add_f32_e32 v45, v45, v255
	v_fmac_f32_e32 v239, v44, v44
	v_fmac_f32_e32 v239, v45, v45
	v_lshlrev_b32_e32 v254, 16, v143
	v_and_b32_e32 v255, 0xffff0000, v143
	v_add_f32_e32 v46, v46, v254
	v_add_f32_e32 v47, v47, v255
	v_fmac_f32_e32 v239, v46, v46
	v_fmac_f32_e32 v239, v47, v47
	v_lshlrev_b32_e32 v254, 16, v144
	v_and_b32_e32 v255, 0xffff0000, v144
	v_add_f32_e32 v16, v16, v254
	v_add_f32_e32 v17, v17, v255
	v_mul_f32_e32 v240, v16, v16
;     __device__ __forceinline__ void tail(const f32x4& b0, const f32x4& b1, const f32x4& a0, const f32x4& a1, bf16_t* dst, float& s) const {
;         const f32x4 o0 = b0 + a0, o1 = b1 + a1;
;         s += ((o0[0] * o0[0] + o0[1] * o0[1]) + (o0[2] * o0[2] + o0[3] * o0[3])) + ((o1[0] * o1[0] + o1[1] * o1[1]) + (o1[2] * o1[2] + o1[3] * o1[3]));
;     __device__ __forceinline__ void operator()(const f32x4 (&acc)[2][2][4][2], const Unit& u, int wr, int wc, int fr, int fq) const {
;     ...
;                 for (int m = 0; m < 4; ++m) { const int row = u.pm * BM + ai * HALF + wr * 64 + m * 16 + fr; const size_t off = (size_t)row * ldc + col0; float s = 0.f;
; #pragma unroll
;                     for (int bj = 0; bj < 2; ++bj) { const u32x4 r = raw[ai][m][bj];
;                         const f32x4 b0 = {__uint_as_float(r.x << 16), __uint_as_float(r.x & 0xffff0000u), __uint_as_float(r.y << 16), __uint_as_float(r.y & 0xffff0000u)};
;                         const f32x4 b1 = {__uint_as_float(r.z << 16), __uint_as_float(r.z & 0xffff0000u), __uint_as_float(r.w << 16), __uint_as_float(r.w & 0xffff0000u)};
;                         tail(b0, b1, acc[ai][bj][m][0], acc[ai][bj][m][1], out + off + bj * HALF, s); }
	v_fmac_f32_e32 v240, v17, v17
	v_lshlrev_b32_e32 v254, 16, v145
	v_and_b32_e32 v255, 0xffff0000, v145
	v_add_f32_e32 v18, v18, v254
	v_add_f32_e32 v19, v19, v255
	v_fmac_f32_e32 v240, v18, v18
	v_fmac_f32_e32 v240, v19, v19
	v_lshlrev_b32_e32 v254, 16, v146
	v_and_b32_e32 v255, 0xffff0000, v146
	v_add_f32_e32 v20, v20, v254
	v_add_f32_e32 v21, v21, v255
	v_fmac_f32_e32 v240, v20, v20
	v_fmac_f32_e32 v240, v21, v21
	v_lshlrev_b32_e32 v254, 16, v147
	v_and_b32_e32 v255, 0xffff0000, v147
	v_add_f32_e32 v22, v22, v254
	v_add_f32_e32 v23, v23, v255
	v_fmac_f32_e32 v240, v22, v22
	v_fmac_f32_e32 v240, v23, v23
	v_lshlrev_b32_e32 v254, 16, v148
	v_and_b32_e32 v255, 0xffff0000, v148
	v_add_f32_e32 v48, v48, v254
	v_add_f32_e32 v49, v49, v255
	v_fmac_f32_e32 v240, v48, v48
	v_fmac_f32_e32 v240, v49, v49
	v_lshlrev_b32_e32 v254, 16, v149
	v_and_b32_e32 v255, 0xffff0000, v149
	v_add_f32_e32 v50, v50, v254
	v_add_f32_e32 v51, v51, v255
	v_fmac_f32_e32 v240, v50, v50
	v_fmac_f32_e32 v240, v51, v51
	v_lshlrev_b32_e32 v254, 16, v150
	v_and_b32_e32 v255, 0xffff0000, v150
	v_add_f32_e32 v52, v52, v254
	v_add_f32_e32 v53, v53, v255
	v_fmac_f32_e32 v240, v52, v52
	v_fmac_f32_e32 v240, v53, v53
	v_lshlrev_b32_e32 v254, 16, v151
	v_and_b32_e32 v255, 0xffff0000, v151
	v_add_f32_e32 v54, v54, v254
	v_add_f32_e32 v55, v55, v255
	v_fmac_f32_e32 v240, v54, v54
	v_fmac_f32_e32 v240, v55, v55
	v_lshlrev_b32_e32 v254, 16, v152
	v_and_b32_e32 v255, 0xffff0000, v152
	v_add_f32_e32 v24, v24, v254
	v_add_f32_e32 v25, v25, v255
	v_mul_f32_e32 v241, v24, v24
	v_fmac_f32_e32 v241, v25, v25
	v_lshlrev_b32_e32 v254, 16, v153
	v_and_b32_e32 v255, 0xffff0000, v153
	v_add_f32_e32 v26, v26, v254
	v_add_f32_e32 v27, v27, v255
	v_fmac_f32_e32 v241, v26, v26
	v_fmac_f32_e32 v241, v27, v27
	v_lshlrev_b32_e32 v254, 16, v154
	v_and_b32_e32 v255, 0xffff0000, v154
	v_add_f32_e32 v28, v28, v254
	v_add_f32_e32 v29, v29, v255
	v_fmac_f32_e32 v241, v28, v28
	v_fmac_f32_e32 v241, v29, v29
	v_lshlrev_b32_e32 v254, 16, v155
	v_and_b32_e32 v255, 0xffff0000, v155
	v_add_f32_e32 v30, v30, v254
	v_add_f32_e32 v31, v31, v255
	v_fmac_f32_e32 v241, v30, v30
	v_fmac_f32_e32 v241, v31, v31
	v_lshlrev_b32_e32 v254, 16, v156
	v_and_b32_e32 v255, 0xffff0000, v156
	v_add_f32_e32 v56, v56, v254
	v_add_f32_e32 v57, v57, v255
	v_fmac_f32_e32 v241, v56, v56
	v_fmac_f32_e32 v241, v57, v57
	v_lshlrev_b32_e32 v254, 16, v157
	v_and_b32_e32 v255, 0xffff0000, v157
	v_add_f32_e32 v58, v58, v254
	v_add_f32_e32 v59, v59, v255
	v_fmac_f32_e32 v241, v58, v58
	v_fmac_f32_e32 v241, v59, v59
	v_lshlrev_b32_e32 v254, 16, v158
	v_and_b32_e32 v255, 0xffff0000, v158
	v_add_f32_e32 v60, v60, v254
	v_add_f32_e32 v61, v61, v255
	v_fmac_f32_e32 v241, v60, v60
	v_fmac_f32_e32 v241, v61, v61
	v_lshlrev_b32_e32 v254, 16, v159
	v_and_b32_e32 v255, 0xffff0000, v159
	v_add_f32_e32 v62, v62, v254
	v_add_f32_e32 v63, v63, v255
	v_fmac_f32_e32 v241, v62, v62
	v_fmac_f32_e32 v241, v63, v63
	v_lshlrev_b32_e32 v254, 16, v160
	v_and_b32_e32 v255, 0xffff0000, v160
	v_add_f32_e32 v64, v64, v254
	v_add_f32_e32 v65, v65, v255
	v_mul_f32_e32 v242, v64, v64
	v_fmac_f32_e32 v242, v65, v65
	v_lshlrev_b32_e32 v254, 16, v161
	v_and_b32_e32 v255, 0xffff0000, v161
	v_add_f32_e32 v66, v66, v254
	v_add_f32_e32 v67, v67, v255
	v_fmac_f32_e32 v242, v66, v66
	v_fmac_f32_e32 v242, v67, v67
	v_lshlrev_b32_e32 v254, 16, v162
	v_and_b32_e32 v255, 0xffff0000, v162
	v_add_f32_e32 v68, v68, v254
	v_add_f32_e32 v69, v69, v255
	v_fmac_f32_e32 v242, v68, v68
	v_fmac_f32_e32 v242, v69, v69
	v_lshlrev_b32_e32 v254, 16, v163
	v_and_b32_e32 v255, 0xffff0000, v163
	v_add_f32_e32 v70, v70, v254
	v_add_f32_e32 v71, v71, v255
	v_fmac_f32_e32 v242, v70, v70
	v_fmac_f32_e32 v242, v71, v71
	v_lshlrev_b32_e32 v254, 16, v164
	v_and_b32_e32 v255, 0xffff0000, v164
	v_add_f32_e32 v96, v96, v254
	v_add_f32_e32 v97, v97, v255
	v_fmac_f32_e32 v242, v96, v96
	v_fmac_f32_e32 v242, v97, v97
	v_lshlrev_b32_e32 v254, 16, v165
	v_and_b32_e32 v255, 0xffff0000, v165
	v_add_f32_e32 v98, v98, v254
	v_add_f32_e32 v99, v99, v255
	v_fmac_f32_e32 v242, v98, v98
	v_fmac_f32_e32 v242, v99, v99
	v_lshlrev_b32_e32 v254, 16, v166
	v_and_b32_e32 v255, 0xffff0000, v166
	v_add_f32_e32 v100, v100, v254
	v_add_f32_e32 v101, v101, v255
	v_fmac_f32_e32 v242, v100, v100
	v_fmac_f32_e32 v242, v101, v101
	v_lshlrev_b32_e32 v254, 16, v167
	v_and_b32_e32 v255, 0xffff0000, v167
	v_add_f32_e32 v102, v102, v254
	v_add_f32_e32 v103, v103, v255
	v_fmac_f32_e32 v242, v102, v102
	v_fmac_f32_e32 v242, v103, v103
	v_lshlrev_b32_e32 v254, 16, v168
	v_and_b32_e32 v255, 0xffff0000, v168
	v_add_f32_e32 v72, v72, v254
	v_add_f32_e32 v73, v73, v255
	v_mul_f32_e32 v243, v72, v72
	v_fmac_f32_e32 v243, v73, v73
	v_lshlrev_b32_e32 v254, 16, v169
	v_and_b32_e32 v255, 0xffff0000, v169
	v_add_f32_e32 v74, v74, v254
	v_add_f32_e32 v75, v75, v255
	v_fmac_f32_e32 v243, v74, v74
	v_fmac_f32_e32 v243, v75, v75
	v_lshlrev_b32_e32 v254, 16, v170
	v_and_b32_e32 v255, 0xffff0000, v170
	v_add_f32_e32 v76, v76, v254
	v_add_f32_e32 v77, v77, v255
	v_fmac_f32_e32 v243, v76, v76
	v_fmac_f32_e32 v243, v77, v77
	v_lshlrev_b32_e32 v254, 16, v171
	v_and_b32_e32 v255, 0xffff0000, v171
	v_add_f32_e32 v78, v78, v254
	v_add_f32_e32 v79, v79, v255
	v_fmac_f32_e32 v243, v78, v78
	v_fmac_f32_e32 v243, v79, v79
	v_lshlrev_b32_e32 v254, 16, v172
	v_and_b32_e32 v255, 0xffff0000, v172
	v_add_f32_e32 v104, v104, v254
	v_add_f32_e32 v105, v105, v255
	v_fmac_f32_e32 v243, v104, v104
	v_fmac_f32_e32 v243, v105, v105
	v_lshlrev_b32_e32 v254, 16, v173
	v_and_b32_e32 v255, 0xffff0000, v173
	v_add_f32_e32 v106, v106, v254
	v_add_f32_e32 v107, v107, v255
	v_fmac_f32_e32 v243, v106, v106
;     __device__ __forceinline__ void tail(const f32x4& b0, const f32x4& b1, const f32x4& a0, const f32x4& a1, bf16_t* dst, float& s) const {
;         const f32x4 o0 = b0 + a0, o1 = b1 + a1;
;         s += ((o0[0] * o0[0] + o0[1] * o0[1]) + (o0[2] * o0[2] + o0[3] * o0[3])) + ((o1[0] * o1[0] + o1[1] * o1[1]) + (o1[2] * o1[2] + o1[3] * o1[3]));
;     __device__ __forceinline__ void operator()(const f32x4 (&acc)[2][2][4][2], const Unit& u, int wr, int wc, int fr, int fq) const {
;     ...
;                     s += __shfl_xor(s, 16); s += __shfl_xor(s, 32);
;                     if (fq == 0) atomicAdd(ss + row, s); }
	v_fmac_f32_e32 v243, v107, v107
	v_lshlrev_b32_e32 v254, 16, v174
	v_and_b32_e32 v255, 0xffff0000, v174
	v_add_f32_e32 v108, v108, v254
	v_add_f32_e32 v109, v109, v255
	v_fmac_f32_e32 v243, v108, v108
	v_fmac_f32_e32 v243, v109, v109
	v_lshlrev_b32_e32 v254, 16, v175
	v_and_b32_e32 v255, 0xffff0000, v175
	v_add_f32_e32 v110, v110, v254
	v_add_f32_e32 v111, v111, v255
	v_fmac_f32_e32 v243, v110, v110
	v_fmac_f32_e32 v243, v111, v111
	v_lshlrev_b32_e32 v254, 16, v176
	v_and_b32_e32 v255, 0xffff0000, v176
	v_add_f32_e32 v80, v80, v254
	v_add_f32_e32 v81, v81, v255
	v_mul_f32_e32 v226, v80, v80
	v_fmac_f32_e32 v226, v81, v81
	v_lshlrev_b32_e32 v254, 16, v177
	v_and_b32_e32 v255, 0xffff0000, v177
	v_add_f32_e32 v82, v82, v254
	v_add_f32_e32 v83, v83, v255
	v_fmac_f32_e32 v226, v82, v82
	v_fmac_f32_e32 v226, v83, v83
	v_lshlrev_b32_e32 v254, 16, v178
	v_and_b32_e32 v255, 0xffff0000, v178
	v_add_f32_e32 v84, v84, v254
	v_add_f32_e32 v85, v85, v255
	v_fmac_f32_e32 v226, v84, v84
	v_fmac_f32_e32 v226, v85, v85
	v_lshlrev_b32_e32 v254, 16, v179
	v_and_b32_e32 v255, 0xffff0000, v179
	v_add_f32_e32 v86, v86, v254
	v_add_f32_e32 v87, v87, v255
	v_fmac_f32_e32 v226, v86, v86
	v_fmac_f32_e32 v226, v87, v87
	v_lshlrev_b32_e32 v254, 16, v180
	v_and_b32_e32 v255, 0xffff0000, v180
	v_add_f32_e32 v112, v112, v254
	v_add_f32_e32 v113, v113, v255
	v_fmac_f32_e32 v226, v112, v112
	v_fmac_f32_e32 v226, v113, v113
	v_lshlrev_b32_e32 v254, 16, v181
	v_and_b32_e32 v255, 0xffff0000, v181
	v_add_f32_e32 v114, v114, v254
	v_add_f32_e32 v115, v115, v255
	v_fmac_f32_e32 v226, v114, v114
	v_fmac_f32_e32 v226, v115, v115
	v_lshlrev_b32_e32 v254, 16, v182
	v_and_b32_e32 v255, 0xffff0000, v182
	v_add_f32_e32 v116, v116, v254
	v_add_f32_e32 v117, v117, v255
	v_fmac_f32_e32 v226, v116, v116
	v_fmac_f32_e32 v226, v117, v117
	v_lshlrev_b32_e32 v254, 16, v183
	v_and_b32_e32 v255, 0xffff0000, v183
	v_add_f32_e32 v118, v118, v254
	v_add_f32_e32 v119, v119, v255
	v_fmac_f32_e32 v226, v118, v118
	v_fmac_f32_e32 v226, v119, v119
	v_lshlrev_b32_e32 v254, 16, v186
	v_and_b32_e32 v255, 0xffff0000, v186
	v_add_f32_e32 v88, v88, v254
	v_add_f32_e32 v89, v89, v255
	v_mul_f32_e32 v227, v88, v88
	v_fmac_f32_e32 v227, v89, v89
	v_lshlrev_b32_e32 v254, 16, v187
	v_and_b32_e32 v255, 0xffff0000, v187
	v_add_f32_e32 v90, v90, v254
	v_add_f32_e32 v91, v91, v255
	v_fmac_f32_e32 v227, v90, v90
	v_fmac_f32_e32 v227, v91, v91
	v_lshlrev_b32_e32 v254, 16, v188
	v_and_b32_e32 v255, 0xffff0000, v188
	v_add_f32_e32 v92, v92, v254
	v_add_f32_e32 v93, v93, v255
	v_fmac_f32_e32 v227, v92, v92
	v_fmac_f32_e32 v227, v93, v93
	v_lshlrev_b32_e32 v254, 16, v189
	v_and_b32_e32 v255, 0xffff0000, v189
	v_add_f32_e32 v94, v94, v254
	v_add_f32_e32 v95, v95, v255
	v_fmac_f32_e32 v227, v94, v94
	v_fmac_f32_e32 v227, v95, v95
	v_lshlrev_b32_e32 v254, 16, v190
	v_and_b32_e32 v255, 0xffff0000, v190
	v_add_f32_e32 v120, v120, v254
	v_add_f32_e32 v121, v121, v255
	v_fmac_f32_e32 v227, v120, v120
	v_fmac_f32_e32 v227, v121, v121
	v_lshlrev_b32_e32 v254, 16, v191
	v_and_b32_e32 v255, 0xffff0000, v191
	v_add_f32_e32 v122, v122, v254
	v_add_f32_e32 v123, v123, v255
	v_fmac_f32_e32 v227, v122, v122
	v_fmac_f32_e32 v227, v123, v123
	v_lshlrev_b32_e32 v254, 16, v192
	v_and_b32_e32 v255, 0xffff0000, v192
	v_add_f32_e32 v124, v124, v254
	v_add_f32_e32 v125, v125, v255
	v_fmac_f32_e32 v227, v124, v124
	v_fmac_f32_e32 v227, v125, v125
	v_lshlrev_b32_e32 v254, 16, v193
	v_and_b32_e32 v255, 0xffff0000, v193
	v_add_f32_e32 v126, v126, v254
	v_add_f32_e32 v127, v127, v255
	v_fmac_f32_e32 v227, v126, v126
	v_fmac_f32_e32 v227, v127, v127
	ds_bpermute_b32 v128, v232, v238
	ds_bpermute_b32 v132, v232, v239
	ds_bpermute_b32 v136, v232, v240
	ds_bpermute_b32 v140, v232, v241
	ds_bpermute_b32 v144, v232, v242
	ds_bpermute_b32 v148, v232, v243
	ds_bpermute_b32 v152, v232, v226
	ds_bpermute_b32 v156, v232, v227
	s_waitcnt lgkmcnt(0)
	v_add_f32_e32 v238, v238, v128
	v_add_f32_e32 v239, v239, v132
	v_add_f32_e32 v240, v240, v136
	v_add_f32_e32 v241, v241, v140
	v_add_f32_e32 v242, v242, v144
	v_add_f32_e32 v243, v243, v148
	v_add_f32_e32 v226, v226, v152
	v_add_f32_e32 v227, v227, v156
	ds_bpermute_b32 v128, v233, v238
	ds_bpermute_b32 v132, v233, v239
	ds_bpermute_b32 v136, v233, v240
	ds_bpermute_b32 v140, v233, v241
	ds_bpermute_b32 v144, v233, v242
	ds_bpermute_b32 v148, v233, v243
	ds_bpermute_b32 v152, v233, v226
	ds_bpermute_b32 v156, v233, v227
	s_waitcnt lgkmcnt(0)
	v_add_f32_e32 v238, v238, v128
	v_add_f32_e32 v239, v239, v132
	v_add_f32_e32 v240, v240, v136
	v_add_f32_e32 v241, v241, v140
	v_add_f32_e32 v242, v242, v144
	v_add_f32_e32 v243, v243, v148
	v_add_f32_e32 v226, v226, v152
	v_add_f32_e32 v227, v227, v156
	s_mov_b64 exec, 0xffff
	global_atomic_add_f32 v230, v238, s[50:51] offset:0
	global_atomic_add_f32 v230, v239, s[50:51] offset:64
	global_atomic_add_f32 v230, v240, s[50:51] offset:128
	global_atomic_add_f32 v230, v241, s[50:51] offset:192
	global_atomic_add_f32 v230, v242, s[50:51] offset:512
	global_atomic_add_f32 v230, v243, s[50:51] offset:576
	global_atomic_add_f32 v230, v226, s[50:51] offset:640
	global_atomic_add_f32 v230, v227, s[50:51] offset:704
	s_mov_b64 exec, -1
	s_waitcnt vmcnt(0)
	s_barrier
	s_cmp_lg_u32 s36, 0
	s_cbranch_scc1 .Lp6_fin_wait
	s_mov_b64 exec, 1
	v_mov_b32_e32 v237, 0
	v_mov_b32_e32 v236, 1
	global_atomic_add v237, v236, s[54:55]
	s_mov_b32 s42, 0
.Lp6_fin_poll:
	global_load_dword v236, v237, s[54:55] sc1
	s_waitcnt vmcnt(0)
	v_readfirstlane_b32 s43, v236
	s_add_u32 s42, s42, 1
	s_cmp_ge_u32 s43, 8
	s_cbranch_scc1 .Lp6_fin_got
	s_cmp_gt_u32 s42, 0x40000
	s_cbranch_scc1 .Lp6_fin_got
	s_sleep 1
	s_branch .Lp6_fin_poll
; __global__ void __launch_bounds__(NWAVES * 64, 2) hybrid_fwd(Args args) {
;     ...
;         for (int m0 = gw * 4; m0 < M; m0 += NGW * 4) {
;             v2u r[4][8]; float rs[4];
; #pragma unroll
;             for (int q = 0; q < 4; ++q) { const v2u* xr = (const v2u*)(MIXED + (size_t)(m0 + q) * DM) + lane; rs[q] = __builtin_amdgcn_rsqf(SS2[m0 + q] * (1.f / DM) + NORM_EPS);
; #pragma unroll
;                 for (int j = 0; j < 8; ++j) r[q][j] = xr[64 * j]; }
; #pragma unroll
;             for (int q = 0; q < 4; ++q) { f32x4* orow = (f32x4*)(out + (size_t)(m0 + q) * DM) + lane;
; #pragma unroll
;                 for (int j = 0; j < 8; ++j) { const f32x4 w = wfin[j]; const float s = rs[q];
;                     orow[64 * j] = (f32x4){__uint_as_float(r[q][j].x << 16) * s * w.x, __uint_as_float(r[q][j].x & 0xffff0000u) * s * w.y, __uint_as_float(r[q][j].y << 16) * s * w.z, __uint_as_float(r[q][j].y & 0xffff0000u) * s * w.w}; } }
.Lp6_fin_got:
	s_mov_b64 exec, -1
.Lp6_fin_wait:
	s_barrier
	global_load_dword v238, v230, s[50:51] offset:0 sc0 sc1
	global_load_dword v239, v230, s[50:51] offset:64 sc0 sc1
	global_load_dword v240, v230, s[50:51] offset:128 sc0 sc1
	global_load_dword v241, v230, s[50:51] offset:192 sc0 sc1
	global_load_dword v242, v230, s[50:51] offset:512 sc0 sc1
	global_load_dword v243, v230, s[50:51] offset:576 sc0 sc1
	global_load_dword v226, v230, s[50:51] offset:640 sc0 sc1
	global_load_dword v227, v230, s[50:51] offset:704 sc0 sc1
	v_readlane_b32 s44, v244, 0
	v_readlane_b32 s45, v244, 1
	v_and_b32_e32 v254, 63, v185
	v_lshrrev_b32_e32 v254, 4, v254
	v_lshlrev_b32_e32 v254, 5, v254
	s_lshl_b32 s40, s38, 7
	s_lshl_b32 s41, s18, 10
	s_add_u32 s40, s40, s41
	v_add_u32_e32 v254, s40, v254
	global_load_dwordx4 v[128:131], v254, s[44:45] offset:0
	global_load_dwordx4 v[132:135], v254, s[44:45] offset:16
	global_load_dwordx4 v[136:139], v254, s[44:45] offset:512
	global_load_dwordx4 v[140:143], v254, s[44:45] offset:528
	s_waitcnt vmcnt(0)
	v_fmamk_f32 v235, v238, 0x3a000000, v231
	v_add_u32_e32 v234, 0x0, v229
	v_rsq_f32_e32 v235, v235
	s_nop 0
	v_mul_f32_e32 v0, v0, v235
	v_mul_f32_e32 v1, v1, v235
	v_mul_f32_e32 v2, v2, v235
	v_mul_f32_e32 v3, v3, v235
	v_mul_f32_e32 v4, v4, v235
	v_mul_f32_e32 v5, v5, v235
	v_mul_f32_e32 v6, v6, v235
	v_mul_f32_e32 v7, v7, v235
	v_mul_f32_e32 v32, v32, v235
	v_mul_f32_e32 v33, v33, v235
	v_mul_f32_e32 v34, v34, v235
	v_mul_f32_e32 v35, v35, v235
	v_mul_f32_e32 v36, v36, v235
	v_mul_f32_e32 v37, v37, v235
	v_mul_f32_e32 v38, v38, v235
	v_mul_f32_e32 v39, v39, v235
	v_mul_f32_e32 v0, v0, v128
	v_mul_f32_e32 v1, v1, v129
	v_mul_f32_e32 v2, v2, v130
	v_mul_f32_e32 v3, v3, v131
	v_mul_f32_e32 v4, v4, v132
	v_mul_f32_e32 v5, v5, v133
	v_mul_f32_e32 v6, v6, v134
	v_mul_f32_e32 v7, v7, v135
	v_mul_f32_e32 v32, v32, v136
	v_mul_f32_e32 v33, v33, v137
	v_mul_f32_e32 v34, v34, v138
	v_mul_f32_e32 v35, v35, v139
	v_mul_f32_e32 v36, v36, v140
	v_mul_f32_e32 v37, v37, v141
	v_mul_f32_e32 v38, v38, v142
	v_mul_f32_e32 v39, v39, v143
	global_store_dwordx4 v234, v[0:3], s[52:53] offset:0
	global_store_dwordx4 v234, v[4:7], s[52:53] offset:16
	global_store_dwordx4 v234, v[32:35], s[52:53] offset:512
	global_store_dwordx4 v234, v[36:39], s[52:53] offset:528
	s_nop 1
	v_fmamk_f32 v235, v239, 0x3a000000, v231
	v_add_u32_e32 v234, 0x20000, v229
	v_rsq_f32_e32 v235, v235
	s_nop 0
	v_mul_f32_e32 v8, v8, v235
	v_mul_f32_e32 v9, v9, v235
	v_mul_f32_e32 v10, v10, v235
	v_mul_f32_e32 v11, v11, v235
	v_mul_f32_e32 v12, v12, v235
	v_mul_f32_e32 v13, v13, v235
	v_mul_f32_e32 v14, v14, v235
	v_mul_f32_e32 v15, v15, v235
	v_mul_f32_e32 v40, v40, v235
	v_mul_f32_e32 v41, v41, v235
	v_mul_f32_e32 v42, v42, v235
	v_mul_f32_e32 v43, v43, v235
	v_mul_f32_e32 v44, v44, v235
	v_mul_f32_e32 v45, v45, v235
	v_mul_f32_e32 v46, v46, v235
	v_mul_f32_e32 v47, v47, v235
	v_mul_f32_e32 v8, v8, v128
	v_mul_f32_e32 v9, v9, v129
	v_mul_f32_e32 v10, v10, v130
	v_mul_f32_e32 v11, v11, v131
	v_mul_f32_e32 v12, v12, v132
	v_mul_f32_e32 v13, v13, v133
	v_mul_f32_e32 v14, v14, v134
	v_mul_f32_e32 v15, v15, v135
	v_mul_f32_e32 v40, v40, v136
	v_mul_f32_e32 v41, v41, v137
	v_mul_f32_e32 v42, v42, v138
	v_mul_f32_e32 v43, v43, v139
	v_mul_f32_e32 v44, v44, v140
	v_mul_f32_e32 v45, v45, v141
	v_mul_f32_e32 v46, v46, v142
	v_mul_f32_e32 v47, v47, v143
	global_store_dwordx4 v234, v[8:11], s[52:53] offset:0
	global_store_dwordx4 v234, v[12:15], s[52:53] offset:16
	global_store_dwordx4 v234, v[40:43], s[52:53] offset:512
	global_store_dwordx4 v234, v[44:47], s[52:53] offset:528
	s_nop 1
	v_fmamk_f32 v235, v240, 0x3a000000, v231
	v_add_u32_e32 v234, 0x40000, v229
	v_rsq_f32_e32 v235, v235
	s_nop 0
	v_mul_f32_e32 v16, v16, v235
	v_mul_f32_e32 v17, v17, v235
	v_mul_f32_e32 v18, v18, v235
	v_mul_f32_e32 v19, v19, v235
	v_mul_f32_e32 v20, v20, v235
	v_mul_f32_e32 v21, v21, v235
	v_mul_f32_e32 v22, v22, v235
	v_mul_f32_e32 v23, v23, v235
	v_mul_f32_e32 v48, v48, v235
	v_mul_f32_e32 v49, v49, v235
	v_mul_f32_e32 v50, v50, v235
	v_mul_f32_e32 v51, v51, v235
	v_mul_f32_e32 v52, v52, v235
	v_mul_f32_e32 v53, v53, v235
	v_mul_f32_e32 v54, v54, v235
	v_mul_f32_e32 v55, v55, v235
	v_mul_f32_e32 v16, v16, v128
	v_mul_f32_e32 v17, v17, v129
	v_mul_f32_e32 v18, v18, v130
	v_mul_f32_e32 v19, v19, v131
	v_mul_f32_e32 v20, v20, v132
	v_mul_f32_e32 v21, v21, v133
	v_mul_f32_e32 v22, v22, v134
	v_mul_f32_e32 v23, v23, v135
	v_mul_f32_e32 v48, v48, v136
	v_mul_f32_e32 v49, v49, v137
	v_mul_f32_e32 v50, v50, v138
	v_mul_f32_e32 v51, v51, v139
	v_mul_f32_e32 v52, v52, v140
	v_mul_f32_e32 v53, v53, v141
	v_mul_f32_e32 v54, v54, v142
	v_mul_f32_e32 v55, v55, v143
	global_store_dwordx4 v234, v[16:19], s[52:53] offset:0
	global_store_dwordx4 v234, v[20:23], s[52:53] offset:16
	global_store_dwordx4 v234, v[48:51], s[52:53] offset:512
	global_store_dwordx4 v234, v[52:55], s[52:53] offset:528
	s_nop 1
	v_fmamk_f32 v235, v241, 0x3a000000, v231
	v_add_u32_e32 v234, 0x60000, v229
	v_rsq_f32_e32 v235, v235
	s_nop 0
	v_mul_f32_e32 v24, v24, v235
	v_mul_f32_e32 v25, v25, v235
	v_mul_f32_e32 v26, v26, v235
	v_mul_f32_e32 v27, v27, v235
	v_mul_f32_e32 v28, v28, v235
	v_mul_f32_e32 v29, v29, v235
	v_mul_f32_e32 v30, v30, v235
	v_mul_f32_e32 v31, v31, v235
	v_mul_f32_e32 v56, v56, v235
	v_mul_f32_e32 v57, v57, v235
	v_mul_f32_e32 v58, v58, v235
	v_mul_f32_e32 v59, v59, v235
	v_mul_f32_e32 v60, v60, v235
	v_mul_f32_e32 v61, v61, v235
	v_mul_f32_e32 v62, v62, v235
	v_mul_f32_e32 v63, v63, v235
	v_mul_f32_e32 v24, v24, v128
	v_mul_f32_e32 v25, v25, v129
	v_mul_f32_e32 v26, v26, v130
	v_mul_f32_e32 v27, v27, v131
; template <class Epi, class Sched, bool ALIGN_EPI = false, bool SP2 = false>
; __device__ __forceinline__ void gemm_phase(PG8_LAS unsigned char* lds, const Gemm g, const Sched& S, const Epi& E) {
;     ...
;         if (!has_next) break;
; #pragma unroll
;         for (int a = 0; a < 2; ++a)
; #pragma unroll
;             for (int b = 0; b < 2; ++b)
; #pragma unroll
;                 for (int m = 0; m < 4; ++m)
; #pragma unroll
;                     for (int n = 0; n < 2; ++n) acc[a][b][m][n] = (f32x4){0.f, 0.f, 0.f, 0.f};
;         cur = nxt; cA = nA; cB = nB; ++ui;
; __global__ void __launch_bounds__(NWAVES * 64, 2) hybrid_fwd(Args args) {
;     ...
;         for (int m0 = gw * 4; m0 < M; m0 += NGW * 4) {
;             v2u r[4][8]; float rs[4];
; #pragma unroll
;             for (int q = 0; q < 4; ++q) { const v2u* xr = (const v2u*)(MIXED + (size_t)(m0 + q) * DM) + lane; rs[q] = __builtin_amdgcn_rsqf(SS2[m0 + q] * (1.f / DM) + NORM_EPS);
; #pragma unroll
;                 for (int j = 0; j < 8; ++j) r[q][j] = xr[64 * j]; }
; #pragma unroll
;             for (int q = 0; q < 4; ++q) { f32x4* orow = (f32x4*)(out + (size_t)(m0 + q) * DM) + lane;
; #pragma unroll
;                 for (int j = 0; j < 8; ++j) { const f32x4 w = wfin[j]; const float s = rs[q];
;                     orow[64 * j] = (f32x4){__uint_as_float(r[q][j].x << 16) * s * w.x, __uint_as_float(r[q][j].x & 0xffff0000u) * s * w.y, __uint_as_float(r[q][j].y << 16) * s * w.z, __uint_as_float(r[q][j].y & 0xffff0000u) * s * w.w}; } }
	v_mul_f32_e32 v28, v28, v132
	v_mul_f32_e32 v29, v29, v133
	v_mul_f32_e32 v30, v30, v134
	v_mul_f32_e32 v31, v31, v135
	v_mul_f32_e32 v56, v56, v136
	v_mul_f32_e32 v57, v57, v137
	v_mul_f32_e32 v58, v58, v138
	v_mul_f32_e32 v59, v59, v139
	v_mul_f32_e32 v60, v60, v140
	v_mul_f32_e32 v61, v61, v141
	v_mul_f32_e32 v62, v62, v142
	v_mul_f32_e32 v63, v63, v143
	global_store_dwordx4 v234, v[24:27], s[52:53] offset:0
	global_store_dwordx4 v234, v[28:31], s[52:53] offset:16
	global_store_dwordx4 v234, v[56:59], s[52:53] offset:512
	global_store_dwordx4 v234, v[60:63], s[52:53] offset:528
	s_nop 1
	v_fmamk_f32 v235, v242, 0x3a000000, v231
	v_add_u32_e32 v234, 0x100000, v229
	v_rsq_f32_e32 v235, v235
	s_nop 0
	v_mul_f32_e32 v64, v64, v235
	v_mul_f32_e32 v65, v65, v235
	v_mul_f32_e32 v66, v66, v235
	v_mul_f32_e32 v67, v67, v235
	v_mul_f32_e32 v68, v68, v235
	v_mul_f32_e32 v69, v69, v235
	v_mul_f32_e32 v70, v70, v235
	v_mul_f32_e32 v71, v71, v235
	v_mul_f32_e32 v96, v96, v235
	v_mul_f32_e32 v97, v97, v235
	v_mul_f32_e32 v98, v98, v235
	v_mul_f32_e32 v99, v99, v235
	v_mul_f32_e32 v100, v100, v235
	v_mul_f32_e32 v101, v101, v235
	v_mul_f32_e32 v102, v102, v235
	v_mul_f32_e32 v103, v103, v235
	v_mul_f32_e32 v64, v64, v128
	v_mul_f32_e32 v65, v65, v129
	v_mul_f32_e32 v66, v66, v130
	v_mul_f32_e32 v67, v67, v131
	v_mul_f32_e32 v68, v68, v132
	v_mul_f32_e32 v69, v69, v133
	v_mul_f32_e32 v70, v70, v134
	v_mul_f32_e32 v71, v71, v135
	v_mul_f32_e32 v96, v96, v136
	v_mul_f32_e32 v97, v97, v137
	v_mul_f32_e32 v98, v98, v138
	v_mul_f32_e32 v99, v99, v139
	v_mul_f32_e32 v100, v100, v140
	v_mul_f32_e32 v101, v101, v141
	v_mul_f32_e32 v102, v102, v142
	v_mul_f32_e32 v103, v103, v143
	global_store_dwordx4 v234, v[64:67], s[52:53] offset:0
	global_store_dwordx4 v234, v[68:71], s[52:53] offset:16
	global_store_dwordx4 v234, v[96:99], s[52:53] offset:512
	global_store_dwordx4 v234, v[100:103], s[52:53] offset:528
	s_nop 1
	v_fmamk_f32 v235, v243, 0x3a000000, v231
	v_add_u32_e32 v234, 0x120000, v229
	v_rsq_f32_e32 v235, v235
	s_nop 0
	v_mul_f32_e32 v72, v72, v235
	v_mul_f32_e32 v73, v73, v235
	v_mul_f32_e32 v74, v74, v235
	v_mul_f32_e32 v75, v75, v235
	v_mul_f32_e32 v76, v76, v235
	v_mul_f32_e32 v77, v77, v235
	v_mul_f32_e32 v78, v78, v235
	v_mul_f32_e32 v79, v79, v235
	v_mul_f32_e32 v104, v104, v235
	v_mul_f32_e32 v105, v105, v235
	v_mul_f32_e32 v106, v106, v235
	v_mul_f32_e32 v107, v107, v235
	v_mul_f32_e32 v108, v108, v235
	v_mul_f32_e32 v109, v109, v235
	v_mul_f32_e32 v110, v110, v235
	v_mul_f32_e32 v111, v111, v235
	v_mul_f32_e32 v72, v72, v128
	v_mul_f32_e32 v73, v73, v129
	v_mul_f32_e32 v74, v74, v130
	v_mul_f32_e32 v75, v75, v131
	v_mul_f32_e32 v76, v76, v132
	v_mul_f32_e32 v77, v77, v133
	v_mul_f32_e32 v78, v78, v134
	v_mul_f32_e32 v79, v79, v135
	v_mul_f32_e32 v104, v104, v136
	v_mul_f32_e32 v105, v105, v137
	v_mul_f32_e32 v106, v106, v138
	v_mul_f32_e32 v107, v107, v139
	v_mul_f32_e32 v108, v108, v140
	v_mul_f32_e32 v109, v109, v141
	v_mul_f32_e32 v110, v110, v142
	v_mul_f32_e32 v111, v111, v143
	global_store_dwordx4 v234, v[72:75], s[52:53] offset:0
	global_store_dwordx4 v234, v[76:79], s[52:53] offset:16
	global_store_dwordx4 v234, v[104:107], s[52:53] offset:512
	global_store_dwordx4 v234, v[108:111], s[52:53] offset:528
	s_nop 1
	v_fmamk_f32 v235, v226, 0x3a000000, v231
	v_add_u32_e32 v234, 0x140000, v229
	v_rsq_f32_e32 v235, v235
	s_nop 0
	v_mul_f32_e32 v80, v80, v235
	v_mul_f32_e32 v81, v81, v235
	v_mul_f32_e32 v82, v82, v235
	v_mul_f32_e32 v83, v83, v235
	v_mul_f32_e32 v84, v84, v235
	v_mul_f32_e32 v85, v85, v235
	v_mul_f32_e32 v86, v86, v235
	v_mul_f32_e32 v87, v87, v235
	v_mul_f32_e32 v112, v112, v235
	v_mul_f32_e32 v113, v113, v235
	v_mul_f32_e32 v114, v114, v235
	v_mul_f32_e32 v115, v115, v235
	v_mul_f32_e32 v116, v116, v235
	v_mul_f32_e32 v117, v117, v235
	v_mul_f32_e32 v118, v118, v235
	v_mul_f32_e32 v119, v119, v235
	v_mul_f32_e32 v80, v80, v128
	v_mul_f32_e32 v81, v81, v129
	v_mul_f32_e32 v82, v82, v130
	v_mul_f32_e32 v83, v83, v131
	v_mul_f32_e32 v84, v84, v132
	v_mul_f32_e32 v85, v85, v133
	v_mul_f32_e32 v86, v86, v134
	v_mul_f32_e32 v87, v87, v135
	v_mul_f32_e32 v112, v112, v136
	v_mul_f32_e32 v113, v113, v137
	v_mul_f32_e32 v114, v114, v138
	v_mul_f32_e32 v115, v115, v139
	v_mul_f32_e32 v116, v116, v140
	v_mul_f32_e32 v117, v117, v141
	v_mul_f32_e32 v118, v118, v142
	v_mul_f32_e32 v119, v119, v143
	global_store_dwordx4 v234, v[80:83], s[52:53] offset:0
	global_store_dwordx4 v234, v[84:87], s[52:53] offset:16
	global_store_dwordx4 v234, v[112:115], s[52:53] offset:512
	global_store_dwordx4 v234, v[116:119], s[52:53] offset:528
	s_nop 1
	v_fmamk_f32 v235, v227, 0x3a000000, v231
	v_add_u32_e32 v234, 0x160000, v229
	v_rsq_f32_e32 v235, v235
	s_nop 0
	v_mul_f32_e32 v88, v88, v235
	v_mul_f32_e32 v89, v89, v235
	v_mul_f32_e32 v90, v90, v235
	v_mul_f32_e32 v91, v91, v235
	v_mul_f32_e32 v92, v92, v235
	v_mul_f32_e32 v93, v93, v235
	v_mul_f32_e32 v94, v94, v235
	v_mul_f32_e32 v95, v95, v235
	v_mul_f32_e32 v120, v120, v235
	v_mul_f32_e32 v121, v121, v235
	v_mul_f32_e32 v122, v122, v235
	v_mul_f32_e32 v123, v123, v235
	v_mul_f32_e32 v124, v124, v235
	v_mul_f32_e32 v125, v125, v235
	v_mul_f32_e32 v126, v126, v235
	v_mul_f32_e32 v127, v127, v235
	v_mul_f32_e32 v88, v88, v128
	v_mul_f32_e32 v89, v89, v129
	v_mul_f32_e32 v90, v90, v130
	v_mul_f32_e32 v91, v91, v131
	v_mul_f32_e32 v92, v92, v132
	v_mul_f32_e32 v93, v93, v133
	v_mul_f32_e32 v94, v94, v134
	v_mul_f32_e32 v95, v95, v135
	v_mul_f32_e32 v120, v120, v136
	v_mul_f32_e32 v121, v121, v137
	v_mul_f32_e32 v122, v122, v138
	v_mul_f32_e32 v123, v123, v139
	v_mul_f32_e32 v124, v124, v140
	v_mul_f32_e32 v125, v125, v141
	v_mul_f32_e32 v126, v126, v142
	v_mul_f32_e32 v127, v127, v143
	global_store_dwordx4 v234, v[88:91], s[52:53] offset:0
	global_store_dwordx4 v234, v[92:95], s[52:53] offset:16
	global_store_dwordx4 v234, v[120:123], s[52:53] offset:512
	global_store_dwordx4 v234, v[124:127], s[52:53] offset:528
	s_nop 1
	s_cmp_eq_u32 s19, 0
	s_cbranch_scc1 .Lp6_done
	s_mov_b32 s17, s20
	s_mov_b32 s18, s21
	s_mov_b64 s[22:23], s[26:27]
	s_mov_b64 s[24:25], s[28:29]
	s_add_u32 s16, s16, 1
	s_branch .Lp6_unit

; #define LAS __attribute__((address_space(3)))
; #define GRID_BAR(k) do { if (IN(k) && IN((k) + 1)) xcd_barrier(bar); } while (0)
;     __host__ __device__ bool next(int i, Unit& u) const {
;         const long L = (long)i * G + c; if (L >= nwg) return false;
;         int wgid = (int)L; { const int q = nwg / NXCD, r = nwg % NXCD, xcd = wgid % NXCD, off = wgid / NXCD; wgid = (xcd < r ? xcd * (q + 1) : r * (q + 1) + (xcd - r) * q) + off; }
;         const int nig = wgm * nN, gid = wgid / nig, fm = gid * wgm, gsz = (nM - fm) < wgm ? (nM - fm) : wgm;
;         u.pm = fm + ((wgid % nig) % gsz); u.pn = (wgid % nig) / gsz; return true;
; __global__ void __launch_bounds__(NWAVES * 64, 2) hybrid_fwd(Args args) {
;     ...
;     if (IN(6)) {
;         pg8::Gemm g{ACT, Wdn_t, M, DM, FF}; pg8::StaticOrder S; S.init(M, DM, G, bx);
;         pg8::EpiRes<true> E{HB, MIXED, SS2, DM};
;         pg8::gemm_phase<pg8::EpiRes<true>, pg8::StaticOrder, true, true>((LAS unsigned char*)lds, g, S, E);
;     }
;     GRID_BAR(6);
.Lp6_exit:
	v_readlane_b32 s40, v253, 60
	v_readlane_b32 s41, v253, 61
	s_nop 3
	s_mov_b32 vcc_lo, s40
	s_mov_b32 vcc_hi, s41
	v_readlane_b32 s4, v253, 0
	v_readlane_b32 s5, v253, 1
	v_readlane_b32 s6, v253, 2
	v_readlane_b32 s7, v253, 3
	v_readlane_b32 s8, v253, 4
	v_readlane_b32 s9, v253, 5
	v_readlane_b32 s10, v253, 6
	v_readlane_b32 s11, v253, 7
	v_readlane_b32 s12, v253, 8
	v_readlane_b32 s13, v253, 9
	v_readlane_b32 s14, v253, 10
	v_readlane_b32 s15, v253, 11
	v_readlane_b32 s16, v253, 12
	v_readlane_b32 s17, v253, 13
	v_readlane_b32 s18, v253, 14
	v_readlane_b32 s19, v253, 15
	v_readlane_b32 s20, v253, 16
	v_readlane_b32 s21, v253, 17
	v_readlane_b32 s22, v253, 18
	v_readlane_b32 s23, v253, 19
	v_readlane_b32 s24, v253, 20
	v_readlane_b32 s25, v253, 21
	v_readlane_b32 s26, v253, 22
	v_readlane_b32 s27, v253, 23
	v_readlane_b32 s28, v253, 24
	v_readlane_b32 s29, v253, 25
	v_readlane_b32 s30, v253, 26
	v_readlane_b32 s31, v253, 27
	v_readlane_b32 s32, v253, 28
	v_readlane_b32 s33, v253, 29
	v_readlane_b32 s34, v253, 30
	v_readlane_b32 s35, v253, 31
	v_readlane_b32 s36, v253, 32
	v_readlane_b32 s37, v253, 33
	v_readlane_b32 s38, v253, 34
	v_readlane_b32 s39, v253, 35
	v_readlane_b32 s40, v253, 36
	v_readlane_b32 s41, v253, 37
	v_readlane_b32 s42, v253, 38
	v_readlane_b32 s43, v253, 39
	v_readlane_b32 s44, v253, 40
	v_readlane_b32 s45, v253, 41
	v_readlane_b32 s46, v253, 42
	v_readlane_b32 s47, v253, 43
	v_readlane_b32 s48, v253, 44
	v_readlane_b32 s49, v253, 45
	v_readlane_b32 s50, v253, 46
	v_readlane_b32 s51, v253, 47
	v_readlane_b32 s52, v253, 48
	v_readlane_b32 s53, v253, 49
	v_readlane_b32 s54, v253, 50
	v_readlane_b32 s55, v253, 51
	v_readlane_b32 s56, v253, 52
	v_readlane_b32 s57, v253, 53
	v_readlane_b32 s58, v253, 54
	v_readlane_b32 s59, v253, 55
	s_nop 7
	s_mov_b32 s101, 1
	s_branch .LBB0_887
.Lp6_base:
	s_cmpk_lt_i32 s2, 0x200
	s_cselect_b64 s[0:1], -1, 0
	s_cmpk_gt_i32 s2, 0x1ff
	v_readfirstlane_b32 s6, v185
	s_cbranch_scc1 .LBB0_847
	s_ashr_i32 s3, s2, 31
	s_lshr_b32 s3, s3, 29
	s_add_i32 s10, s2, s3
	s_and_b32 s3, s10, -8
	s_sub_i32 s3, s2, s3
	s_cmp_gt_i32 s3, -1
	s_cbranch_scc0 .LBB0_844
	s_lshl_b32 s7, s3, 6
	s_ashr_i32 s4, s10, 3
	s_cbranch_execz .LBB0_845
	s_branch .LBB0_846

; __device__ __forceinline__ unsigned xb_ld(unsigned* p)              { return __hip_atomic_load(p, __ATOMIC_RELAXED, __HIP_MEMORY_SCOPE_AGENT); }
; __device__ __forceinline__ void xcd_barrier_complete(unsigned* bar, unsigned x, unsigned& nloc, unsigned& nx) {
;     const unsigned G = gridDim.x * gridDim.y * gridDim.z;
;     unsigned sum, cnt, mine, sp = 0u;
;     for (;;) {
;         sum = 0u; cnt = 0u; mine = 0u;
; #pragma unroll
;         for (unsigned j = 0; j < 16; ++j) { const unsigned c = xb_ld(&bar[XB_XCNT(j)]); sum += c; cnt += (c > 0u) ? 1u : 0u; mine = (j == x) ? c : mine; }
; __device__ __forceinline__ void xcd_barrier(const XcdBarrier& b) {
;     asm volatile("s_waitcnt vmcnt(0)" ::: "memory");
;     __syncthreads();
;     if (threadIdx.x == 0) {
;         unsigned* bar = b.bar;
;         __builtin_amdgcn_s_waitcnt(0);
;         unsigned nloc = b.st[0], nx = b.st[1];
;         if (nloc == 0u) { xcd_barrier_complete(bar, b.x, nloc, nx); b.st[0] = nloc; b.st[1] = nx; }
.LBB0_887:
	s_cmp_eq_u32 s101, 1
	s_cbranch_scc1 .LBB0_944
	s_cmp_gt_i32 s71, 7
	s_cselect_b64 s[0:1], -1, 0
	s_and_b64 s[2:3], s[8:9], s[0:1]
	s_andn2_b64 vcc, exec, s[2:3]
	s_cbranch_vccnz .LBB0_941
	s_waitcnt vmcnt(0)
	s_waitcnt vmcnt(0) lgkmcnt(0)
	s_barrier
	s_and_saveexec_b64 s[2:3], s[96:97]
	s_cbranch_execz .LBB0_940
	s_add_i32 s4, 0, 0x20fc0
	v_mov_b32_e32 v0, s4
	s_waitcnt vmcnt(0) expcnt(0) lgkmcnt(0)
	ds_read_b32 v2, v0
	s_add_i32 s4, 0, 0x20fc4
	v_mov_b32_e32 v0, s4
	ds_read_b32 v0, v0
	s_waitcnt lgkmcnt(1)
	v_cmp_ne_u32_e32 vcc, 0, v2
	s_cbranch_vccnz .LBB0_904
	v_readlane_b32 s4, v244, 4
	v_readlane_b32 s5, v244, 5
	v_readlane_b32 s6, v244, 6
	s_mul_i32 s33, s5, s6
	s_mul_i32 s33, s33, s4
	s_add_u32 s4, s76, 0x20200
	s_addc_u32 s5, s77, 0
	s_add_u32 s6, s76, 0x20400
	s_addc_u32 s7, s77, 0
	s_add_u32 s8, s76, 0x20500
	s_addc_u32 s9, s77, 0
	s_add_u32 s10, s76, 0x20600
	s_addc_u32 s11, s77, 0
	s_add_u32 s12, s76, 0x20700
	s_addc_u32 s13, s77, 0
	s_add_u32 s14, s76, 0x20800
	s_addc_u32 s15, s77, 0
	s_add_u32 s16, s76, 0x20900
	s_addc_u32 s17, s77, 0
	s_add_u32 s18, s76, 0x20a00
	s_addc_u32 s19, s77, 0
	s_add_u32 s20, s76, 0x20b00
	s_addc_u32 s21, s77, 0
	s_add_u32 s22, s76, 0x20c00
	s_addc_u32 s23, s77, 0
	s_add_u32 s24, s76, 0x20d00
	s_addc_u32 s25, s77, 0
	s_add_u32 s26, s76, 0x20e00
	s_addc_u32 s27, s77, 0
	s_add_u32 s28, s76, 0x20f00
	s_addc_u32 s29, s77, 0
	s_add_u32 s30, s76, 0x21000
	s_addc_u32 s31, s77, 0
	s_add_u32 s34, s76, 0x21100
	s_addc_u32 s35, s77, 0
	s_add_u32 s36, s76, 0x21200
	s_addc_u32 s37, s77, 0
	s_add_u32 s38, s76, 0x21300
	s_addc_u32 s39, s77, 0
	s_mov_b32 s46, 1
	v_mov_b32_e32 v16, 0
	s_branch .LBB0_892

; __global__ void __launch_bounds__(NWAVES * 64, 2) hybrid_fwd(Args args) {
;     extern __shared__ __attribute__((aligned(16))) unsigned char lds[];
;     cg::grid_group grid = cg::this_grid();
	.amdhsa_kernel _Z10hybrid_fwd4Args
		.amdhsa_group_segment_fixed_size 0
		.amdhsa_private_segment_fixed_size 0
		.amdhsa_kernarg_size 352
		.amdhsa_user_sgpr_count 2
		.amdhsa_user_sgpr_dispatch_ptr 0
		.amdhsa_user_sgpr_queue_ptr 0
		.amdhsa_user_sgpr_kernarg_segment_ptr 1
		.amdhsa_user_sgpr_dispatch_id 0
		.amdhsa_user_sgpr_kernarg_preload_length 0
		.amdhsa_user_sgpr_kernarg_preload_offset 0
		.amdhsa_user_sgpr_private_segment_size 0
		.amdhsa_uses_dynamic_stack 0
		.amdhsa_enable_private_segment 0
		.amdhsa_system_sgpr_workgroup_id_x 1
		.amdhsa_system_sgpr_workgroup_id_y 0
		.amdhsa_system_sgpr_workgroup_id_z 0
		.amdhsa_system_sgpr_workgroup_info 0
		.amdhsa_system_vgpr_workitem_id 2
		.amdhsa_next_free_vgpr 256
		.amdhsa_next_free_sgpr 102
		.amdhsa_accum_offset 256
		.amdhsa_reserve_vcc 1
		.amdhsa_float_round_mode_32 0
		.amdhsa_float_round_mode_16_64 0
		.amdhsa_float_denorm_mode_32 3
		.amdhsa_float_denorm_mode_16_64 3
		.amdhsa_dx10_clamp 1
		.amdhsa_ieee_mode 1
		.amdhsa_fp16_overflow 0
		.amdhsa_tg_split 0
		.amdhsa_exception_fp_ieee_invalid_op 0
		.amdhsa_exception_fp_denorm_src 0
		.amdhsa_exception_fp_ieee_div_zero 0
		.amdhsa_exception_fp_ieee_overflow 0
		.amdhsa_exception_fp_ieee_underflow 0
		.amdhsa_exception_fp_ieee_inexact 0
		.amdhsa_exception_int_div_zero 0
	.end_amdhsa_kernel

; __global__ void __launch_bounds__(NWAVES * 64, 2) hybrid_fwd(Args args) {
amdhsa.kernels:
  - .agpr_count:     0
    .args:
      - .offset:         0
        .size:           96
        .value_kind:     by_value
      - .offset:         96
        .size:           4
        .value_kind:     hidden_block_count_x
      - .offset:         100
        .size:           4
        .value_kind:     hidden_block_count_y
      - .offset:         104
        .size:           4
        .value_kind:     hidden_block_count_z
      - .offset:         108
        .size:           2
        .value_kind:     hidden_group_size_x
      - .offset:         110
        .size:           2
        .value_kind:     hidden_group_size_y
      - .offset:         112
        .size:           2
        .value_kind:     hidden_group_size_z
      - .offset:         114
        .size:           2
        .value_kind:     hidden_remainder_x
      - .offset:         116
        .size:           2
        .value_kind:     hidden_remainder_y
      - .offset:         118
        .size:           2
        .value_kind:     hidden_remainder_z
      - .offset:         136
        .size:           8
        .value_kind:     hidden_global_offset_x
      - .offset:         144
        .size:           8
        .value_kind:     hidden_global_offset_y
      - .offset:         152
        .size:           8
        .value_kind:     hidden_global_offset_z
      - .offset:         160
        .size:           2
        .value_kind:     hidden_grid_dims
      - .offset:         184
        .size:           8
        .value_kind:     hidden_multigrid_sync_arg
      - .offset:         216
        .size:           4
        .value_kind:     hidden_dynamic_lds_size
    .group_segment_fixed_size: 0
    .kernarg_segment_align: 8
    .kernarg_segment_size: 352
    .language:       OpenCL C
    .language_version:
      - 2
      - 0
    .max_flat_workgroup_size: 512
    .name:           _Z10hybrid_fwd4Args
    .private_segment_fixed_size: 0
    .sgpr_count:     108
    .sgpr_spill_count: 45
    .symbol:         _Z10hybrid_fwd4Args.kd
    .uniform_work_group_size: 1
    .uses_dynamic_stack: false
    .vgpr_count:     256
    .vgpr_spill_count: 0
    .wavefront_size: 64
